# adds: P0 lane-0 blocks vectorised over lanes 0..3 (one log-sigmoid instance per row), both EpiT1 epilogue ladders in P3a software-pipelined (loads 8 half-steps ahead), 2-wait-state pad after 128-bit s
# speedup vs baseline: 1.0352x; 1.0158x over previous
.LBB0_23:
	s_or_b64 exec, exec, s[0:1]
	s_movk_i32 s24, 0x4200
	v_cmp_gt_i32_e32 vcc, s24, v42
	v_mbcnt_lo_u32_b32 v185, -1, 0
	s_waitcnt lgkmcnt(0)
	s_barrier
	s_and_saveexec_b64 s[0:1], vcc
	s_cbranch_execz .LBB0_31
	v_readlane_b32 s76, v254, 5
	v_readlane_b32 s77, v254, 6
	v_readlane_b32 s78, v254, 7
	v_readlane_b32 s79, v254, 8
	v_and_b32_e32 v112, 3, v148
	v_lshlrev_b32_e32 v112, 2, v112
	s_nop 4
	global_load_dword v110, v112, s[76:77]
	global_load_dword v111, v112, s[78:79]
	s_mov_b64 s[18:19], 2
	s_mov_b64 s[20:21], 4
	s_mov_b64 s[22:23], 8
	s_mov_b64 s[68:69], 15
	v_lshlrev_b32_e32 v1, 4, v148
	global_load_dwordx4 v[2:5], v1, s[64:65]
	global_load_dwordx4 v[6:9], v1, s[64:65] offset:1024
	global_load_dwordx4 v[10:13], v1, s[64:65] offset:2048
	global_load_dwordx4 v[14:17], v1, s[64:65] offset:3072
	v_mbcnt_hi_u32_b32 v18, -1, v185
	v_and_b32_e32 v19, 64, v18
	v_add_u32_e32 v19, 64, v19
	v_xor_b32_e32 v20, 1, v18
	v_cmp_lt_i32_e32 vcc, v20, v19
	s_lshl_b32 s6, s90, 4
	v_ashrrev_i32_e32 v43, 31, v42
	v_cndmask_b32_e32 v20, v18, v20, vcc
	v_lshlrev_b32_e32 v66, 2, v20
	v_xor_b32_e32 v20, 2, v18
	v_cmp_lt_i32_e32 vcc, v20, v19
	s_ashr_i32 s7, s6, 31
	v_lshlrev_b64 v[50:51], 11, v[42:43]
	v_cndmask_b32_e32 v20, v18, v20, vcc
	v_lshlrev_b32_e32 v67, 2, v20
	v_xor_b32_e32 v20, 4, v18
	v_cmp_lt_i32_e32 vcc, v20, v19
	v_mov_b32_e32 v45, 0
	v_add_u32_e32 v1, s73, v1
	v_cndmask_b32_e32 v20, v18, v20, vcc
	v_lshlrev_b32_e32 v68, 2, v20
	v_xor_b32_e32 v20, 8, v18
	v_cmp_lt_i32_e32 vcc, v20, v19
	v_cmp_eq_u32_e64 s[2:3], 0, v148
	s_lshl_b64 s[8:9], s[6:7], 5
	v_cndmask_b32_e32 v20, v18, v20, vcc
	v_lshlrev_b32_e32 v69, 2, v20
	v_xor_b32_e32 v20, 16, v18
	v_cmp_lt_i32_e32 vcc, v20, v19
	s_lshl_b64 s[10:11], s[6:7], 11
	v_lshlrev_b64 v[52:53], 5, v[42:43]
	v_cndmask_b32_e32 v20, v18, v20, vcc
	v_lshlrev_b32_e32 v70, 2, v20
	v_xor_b32_e32 v20, 32, v18
	v_cmp_lt_i32_e32 vcc, v20, v19
	s_mov_b64 s[12:13], 0
	s_movk_i32 s25, 0x4000
	v_cndmask_b32_e32 v18, v18, v20, vcc
	v_lshlrev_b32_e32 v71, 2, v18
	v_add_u32_e32 v18, s33, v42
	v_ashrrev_i32_e32 v19, 31, v18
	v_lshlrev_b64 v[46:47], 5, v[18:19]
	v_lshlrev_b64 v[48:49], 11, v[18:19]
	v_lshlrev_b32_e32 v18, 3, v148
	v_or_b32_e32 v48, v48, v18
	v_or_b32_e32 v50, v50, v18
	v_mov_b32_e32 v72, s55
	v_mov_b32_e32 v73, s53
	v_lshlrev_b32_e32 v44, 4, v148
	v_mov_b32_e32 v74, 0x358637bd
	s_mov_b32 s28, 0x800000
	s_mov_b32 s29, 0x276e000
	s_mov_b32 s30, 0xbfb8aa3b
	s_mov_b32 s31, 0xb2a5705f
	s_mov_b32 s34, 0x42ce8ed0
	s_mov_b32 s35, 0xc2b17218
	s_mov_b32 s64, 0x7f800000
	s_mov_b32 s65, 0x3f2aaaab
	v_mov_b32_e32 v75, 0x3ecc95a3
	s_mov_b32 s66, 0x3f317218
	s_mov_b32 s67, 0x33800000
	s_movk_i32 s84, 0x41ff
	v_mov_b32_e32 v76, 0x7f800000
	s_branch .LBB0_26

.LBB0_26:
	v_add_u32_e32 v18, 0xffffc000, v42
	v_cmp_gt_i32_e32 vcc, s25, v42
	v_mov_b32_e32 v29, s54
	v_mov_b32_e32 v32, s52
	v_cndmask_b32_e32 v19, 0, v43, vcc
	v_cndmask_b32_e32 v18, v18, v42, vcc
	s_waitcnt lgkmcnt(0)
	v_cndmask_b32_e32 v21, v72, v73, vcc
	v_cndmask_b32_e32 v20, v29, v32, vcc
	v_lshlrev_b64 v[18:19], 12, v[18:19]
	v_lshl_add_u64 v[18:19], v[20:21], 0, v[18:19]
	v_lshl_add_u64 v[18:19], v[18:19], 0, v[44:45]
	global_load_dwordx4 v[56:59], v[18:19], off
	global_load_dwordx4 v[60:63], v[18:19], off offset:1024
	global_load_dwordx4 v[34:37], v[18:19], off offset:3072
	global_load_dwordx4 v[38:41], v[18:19], off offset:2048
	s_waitcnt vmcnt(3)
	v_pk_mul_f32 v[18:19], v[58:59], v[58:59]
	v_pk_mul_f32 v[20:21], v[56:57], v[56:57]
	s_waitcnt vmcnt(2)
	v_pk_mul_f32 v[22:23], v[62:63], v[62:63]
	v_pk_mul_f32 v[24:25], v[60:61], v[60:61]
	v_pk_mov_b32 v[30:31], v[20:21], v[18:19] op_sel:[1,0]
	v_mov_b32_e32 v21, v19
	v_pk_mov_b32 v[18:19], v[24:25], v[22:23] op_sel:[1,0]
	v_mov_b32_e32 v25, v23
	s_waitcnt vmcnt(0)
	v_mul_f32_e32 v26, v39, v39
	v_mul_f32_e32 v28, v41, v41
	v_pk_add_f32 v[20:21], v[30:31], v[20:21]
	v_pk_add_f32 v[18:19], v[18:19], v[24:25]
	v_mul_f32_e32 v33, v34, v34
	v_mul_f32_e32 v54, v35, v35
	v_mul_f32_e32 v55, v36, v36
	v_mul_f32_e32 v64, v37, v37
	v_pk_fma_f32 v[22:23], v[38:39], v[38:39], v[26:27] op_sel_hi:[1,1,0]
	v_pk_fma_f32 v[26:27], v[40:41], v[40:41], v[28:29] op_sel_hi:[1,1,0]
	v_pk_add_f32 v[20:21], v[20:21], v[20:21] op_sel:[0,1] op_sel_hi:[1,0]
	v_pk_add_f32 v[18:19], v[18:19], v[18:19] op_sel:[0,1] op_sel_hi:[1,0]
	v_mov_b32_e32 v23, v55
	v_mov_b32_e32 v27, v64
	v_mov_b32_e32 v21, v33
	v_mov_b32_e32 v19, v54
	v_pk_add_f32 v[22:23], v[22:23], v[26:27]
	v_pk_add_f32 v[18:19], v[20:21], v[18:19]
	v_add_u32_e32 v20, s33, v42
	v_pk_add_f32 v[18:19], v[18:19], v[22:23]
	v_cmp_gt_i32_e64 s[4:5], s24, v20
	v_add_f32_e32 v18, v18, v19
	ds_bpermute_b32 v19, v66, v18
	v_cndmask_b32_e64 v20, v42, v20, s[4:5]
	v_add_u32_e32 v25, 0xffffc000, v20
	v_mov_b32_e32 v21, s55
	v_mov_b32_e32 v24, s53
	s_waitcnt lgkmcnt(0)
	v_add_f32_e32 v18, v18, v19
	ds_bpermute_b32 v19, v67, v18
	s_waitcnt lgkmcnt(0)
	v_add_f32_e32 v22, v18, v19
	ds_bpermute_b32 v23, v68, v22
	v_lshl_add_u64 v[18:19], s[74:75], 0, v[50:51]
	v_add_co_u32_e32 v54, vcc, s29, v18
	v_ashrrev_i32_e32 v18, 31, v20
	s_waitcnt lgkmcnt(0)
	v_add_f32_e32 v22, v22, v23
	ds_bpermute_b32 v23, v69, v22
	v_addc_co_u32_e32 v55, vcc, 0, v19, vcc
	v_cmp_gt_i32_e32 vcc, s25, v20
	s_waitcnt lgkmcnt(0)
	v_add_f32_e32 v22, v22, v23
	ds_bpermute_b32 v23, v70, v22
	v_cndmask_b32_e32 v19, 0, v18, vcc
	v_cndmask_b32_e32 v18, v25, v20, vcc
	v_cndmask_b32_e32 v21, v21, v24, vcc
	v_cndmask_b32_e32 v20, v29, v32, vcc
	s_waitcnt lgkmcnt(0)
	v_add_f32_e32 v22, v22, v23
	ds_bpermute_b32 v23, v71, v22
	v_lshlrev_b64 v[18:19], 12, v[18:19]
	v_lshl_add_u64 v[18:19], v[20:21], 0, v[18:19]
	v_lshl_add_u64 v[18:19], v[18:19], 0, v[44:45]
	s_waitcnt lgkmcnt(0)
	v_add_f32_e32 v20, v22, v23
	v_fmamk_f32 v20, v20, 0x3a800000, v74
	v_mul_f32_e32 v21, 0x4b800000, v20
	v_cmp_gt_f32_e32 vcc, s28, v20
	s_nop 1
	v_cndmask_b32_e32 v20, v20, v21, vcc
	v_rsq_f32_e32 v64, v20
	global_load_dwordx4 v[30:33], v[18:19], off
	global_load_dwordx4 v[26:29], v[18:19], off offset:1024
	global_load_dwordx4 v[22:25], v[18:19], off offset:2048
	s_nop 0
	global_load_dwordx4 v[18:21], v[18:19], off offset:3072
	v_mul_f32_e32 v65, 0x45800000, v64
	v_cndmask_b32_e32 v64, v64, v65, vcc
	v_pk_mul_f32 v[56:57], v[56:57], v[64:65] op_sel_hi:[1,0]
	v_pk_mul_f32 v[58:59], v[58:59], v[64:65] op_sel_hi:[1,0]
	v_pk_mul_f32 v[38:39], v[38:39], v[64:65] op_sel_hi:[1,0]
	v_pk_mul_f32 v[34:35], v[34:35], v[64:65] op_sel_hi:[1,0]
	v_pk_mul_f32 v[60:61], v[60:61], v[64:65] op_sel_hi:[1,0]
	v_pk_mul_f32 v[78:79], v[62:63], v[64:65] op_sel_hi:[1,0]
	v_pk_mul_f32 v[40:41], v[40:41], v[64:65] op_sel_hi:[1,0]
	v_pk_mul_f32 v[36:37], v[36:37], v[64:65] op_sel_hi:[1,0]
	v_pk_mul_f32 v[62:63], v[4:5], v[58:59]
	v_pk_mul_f32 v[64:65], v[2:3], v[56:57]
	v_pk_mul_f32 v[56:57], v[10:11], v[38:39]
	v_pk_mul_f32 v[38:39], v[14:15], v[34:35]
	v_cvt_pk_bf16_f32 v34, v64, v65
	v_cvt_pk_bf16_f32 v35, v62, v63
	v_pk_mul_f32 v[58:59], v[8:9], v[78:79]
	v_pk_mul_f32 v[60:61], v[6:7], v[60:61]
	global_store_dwordx2 v[54:55], v[34:35], off
	v_cvt_pk_bf16_f32 v34, v60, v61
	v_cvt_pk_bf16_f32 v35, v58, v59
	v_pk_mul_f32 v[40:41], v[12:13], v[40:41]
	global_store_dwordx2 v[54:55], v[34:35], off offset:512
	v_cvt_pk_bf16_f32 v34, v56, v57
	v_cvt_pk_bf16_f32 v35, v40, v41
	v_pk_mul_f32 v[36:37], v[16:17], v[36:37]
	global_store_dwordx2 v[54:55], v[34:35], off offset:1024
	v_cvt_pk_bf16_f32 v34, v38, v39
	v_cvt_pk_bf16_f32 v35, v36, v37
	ds_read_b128 v[78:81], v1
	ds_read_b128 v[82:85], v1 offset:1024
	ds_read_b128 v[86:89], v1 offset:2048
	ds_read_b128 v[90:93], v1 offset:3072
	ds_read_b128 v[94:97], v1 offset:4096
	ds_read_b128 v[98:101], v1 offset:5120
	ds_read_b128 v[102:105], v1 offset:6144
	ds_read_b128 v[106:109], v1 offset:7168
	s_waitcnt lgkmcnt(7)
	v_mul_f32_e32 v77, v65, v79
	v_mul_f32_e32 v79, v63, v81
	s_waitcnt lgkmcnt(6)
	v_mul_f32_e32 v81, v61, v83
	v_mul_f32_e32 v83, v59, v85
	v_fmac_f32_e32 v77, v64, v78
	v_fmac_f32_e32 v79, v62, v80
	s_waitcnt lgkmcnt(5)
	v_mul_f32_e32 v85, v57, v87
	v_mul_f32_e32 v87, v41, v89
	v_fmac_f32_e32 v81, v60, v82
	v_fmac_f32_e32 v83, v58, v84
	v_add_f32_e32 v77, v77, v79
	s_waitcnt lgkmcnt(4)
	v_mul_f32_e32 v89, v39, v91
	v_mul_f32_e32 v91, v37, v93
	v_fmac_f32_e32 v85, v56, v86
	v_fmac_f32_e32 v87, v40, v88
	v_add_f32_e32 v78, v81, v83
	v_add_f32_e32 v77, 0, v77
	v_fmac_f32_e32 v89, v38, v90
	v_fmac_f32_e32 v91, v36, v92
	v_add_f32_e32 v79, v85, v87
	v_add_f32_e32 v77, v77, v78
	s_waitcnt lgkmcnt(3)
	v_mul_f32_e32 v93, v65, v95
	v_mul_f32_e32 v95, v63, v97
	v_add_f32_e32 v80, v89, v91
	v_add_f32_e32 v77, v77, v79
	s_waitcnt lgkmcnt(2)
	v_mul_f32_e32 v97, v61, v99
	v_mul_f32_e32 v99, v59, v101
	v_fmac_f32_e32 v93, v64, v94
	v_fmac_f32_e32 v95, v62, v96
	v_add_f32_e32 v77, v77, v80
	v_fmac_f32_e32 v97, v60, v98
	v_fmac_f32_e32 v99, v58, v100
	ds_bpermute_b32 v78, v66, v77
	v_add_f32_e32 v79, v93, v95
	v_add_f32_e32 v80, v97, v99
	v_add_f32_e32 v79, 0, v79
	s_waitcnt lgkmcnt(2)
	v_mul_f32_e32 v101, v57, v103
	v_add_f32_e32 v79, v79, v80
	v_mul_f32_e32 v80, v41, v105
	v_fmac_f32_e32 v101, v56, v102
	v_fmac_f32_e32 v80, v40, v104
	v_add_f32_e32 v80, v101, v80
	s_waitcnt lgkmcnt(0)
	v_add_f32_e32 v77, v77, v78
	v_add_f32_e32 v79, v79, v80
	v_mul_f32_e32 v80, v39, v107
	v_mul_f32_e32 v81, v37, v109
	ds_bpermute_b32 v78, v67, v77
	v_fmac_f32_e32 v80, v38, v106
	v_fmac_f32_e32 v81, v36, v108
	v_add_f32_e32 v80, v80, v81
	v_add_f32_e32 v79, v79, v80
	ds_bpermute_b32 v80, v66, v79
	s_waitcnt lgkmcnt(1)
	v_add_f32_e32 v77, v77, v78
	ds_bpermute_b32 v78, v68, v77
	global_store_dwordx2 v[54:55], v[34:35], off offset:1536
	s_waitcnt lgkmcnt(1)
	v_add_f32_e32 v82, v79, v80
	ds_bpermute_b32 v83, v67, v82
	s_waitcnt lgkmcnt(1)
	v_add_f32_e32 v77, v77, v78
	ds_read_b128 v[78:81], v1 offset:8192
	ds_bpermute_b32 v86, v69, v77
	s_waitcnt lgkmcnt(2)
	v_add_f32_e32 v87, v82, v83
	ds_read_b128 v[82:85], v1 offset:9216
	s_waitcnt lgkmcnt(2)
	v_mul_f32_e32 v79, v65, v79
	v_fmac_f32_e32 v79, v64, v78
	v_mul_f32_e32 v78, v63, v81
	v_fmac_f32_e32 v78, v62, v80
	v_add_f32_e32 v78, v79, v78
	s_waitcnt lgkmcnt(0)
	v_mul_f32_e32 v83, v61, v83
	v_add_f32_e32 v89, 0, v78
	v_fmac_f32_e32 v83, v60, v82
	v_mul_f32_e32 v82, v59, v85
	ds_read_b128 v[78:81], v1 offset:10240
	v_fmac_f32_e32 v82, v58, v84
	v_add_f32_e32 v82, v83, v82
	v_add_f32_e32 v89, v89, v82
	ds_read_b128 v[82:85], v1 offset:11264
	s_waitcnt lgkmcnt(1)
	v_mul_f32_e32 v79, v57, v79
	v_fmac_f32_e32 v79, v56, v78
	v_mul_f32_e32 v78, v41, v81
	v_fmac_f32_e32 v78, v40, v80
	v_add_f32_e32 v78, v79, v78
	s_waitcnt lgkmcnt(0)
	v_mul_f32_e32 v79, v39, v83
	v_mul_f32_e32 v80, v37, v85
	v_fmac_f32_e32 v79, v38, v82
	v_fmac_f32_e32 v80, v36, v84
	v_add_f32_e32 v78, v89, v78
	v_add_f32_e32 v79, v79, v80
	v_add_f32_e32 v78, v78, v79
	ds_bpermute_b32 v88, v68, v87
	ds_bpermute_b32 v79, v66, v78
	v_add_f32_e32 v77, v77, v86
	ds_bpermute_b32 v80, v70, v77
	s_waitcnt lgkmcnt(2)
	v_add_f32_e32 v84, v87, v88
	s_waitcnt lgkmcnt(1)
	v_add_f32_e32 v79, v78, v79
	ds_bpermute_b32 v85, v69, v84
	ds_bpermute_b32 v86, v67, v79
	s_waitcnt lgkmcnt(2)
	v_add_f32_e32 v77, v77, v80
	ds_read_b128 v[80:83], v1 offset:12288
	ds_bpermute_b32 v78, v71, v77
	s_waitcnt lgkmcnt(3)
	v_add_f32_e32 v88, v84, v85
	s_waitcnt lgkmcnt(2)
	v_add_f32_e32 v79, v79, v86
	ds_read_b128 v[84:87], v1 offset:13312
	s_waitcnt lgkmcnt(2)
	v_mul_f32_e32 v81, v65, v81
	v_fmac_f32_e32 v81, v64, v80
	v_mul_f32_e32 v80, v63, v83
	v_fmac_f32_e32 v80, v62, v82
	v_add_f32_e32 v80, v81, v80
	s_waitcnt lgkmcnt(0)
	v_mul_f32_e32 v85, v61, v85
	v_add_f32_e32 v90, 0, v80
	v_fmac_f32_e32 v85, v60, v84
	v_mul_f32_e32 v84, v59, v87
	ds_read_b128 v[80:83], v1 offset:14336
	v_fmac_f32_e32 v84, v58, v86
	v_add_f32_e32 v84, v85, v84
	v_add_f32_e32 v90, v90, v84
	ds_read_b128 v[84:87], v1 offset:15360
	s_waitcnt lgkmcnt(1)
	v_mul_f32_e32 v81, v57, v81
	v_fmac_f32_e32 v81, v56, v80
	v_mul_f32_e32 v80, v41, v83
	v_fmac_f32_e32 v80, v40, v82
	v_add_f32_e32 v80, v81, v80
	s_waitcnt lgkmcnt(0)
	v_mul_f32_e32 v85, v39, v85
	v_add_f32_e32 v90, v90, v80
	v_fmac_f32_e32 v85, v38, v84
	v_mul_f32_e32 v84, v37, v87
	ds_read_b128 v[80:83], v1 offset:16384
	v_fmac_f32_e32 v84, v36, v86
	v_add_f32_e32 v84, v85, v84
	v_add_f32_e32 v90, v90, v84
	ds_read_b128 v[84:87], v1 offset:17408
	s_waitcnt lgkmcnt(1)
	v_mul_f32_e32 v81, v65, v81
	v_fmac_f32_e32 v81, v64, v80
	v_mul_f32_e32 v80, v63, v83
	v_fmac_f32_e32 v80, v62, v82
	v_add_f32_e32 v80, v81, v80
	s_waitcnt lgkmcnt(0)
	v_mul_f32_e32 v85, v61, v85
	v_add_f32_e32 v92, 0, v80
	v_fmac_f32_e32 v85, v60, v84
	v_mul_f32_e32 v84, v59, v87
	ds_read_b128 v[80:83], v1 offset:18432
	v_fmac_f32_e32 v84, v58, v86
	v_add_f32_e32 v84, v85, v84
	v_add_f32_e32 v92, v92, v84
	ds_read_b128 v[84:87], v1 offset:19456
	s_waitcnt lgkmcnt(1)
	v_mul_f32_e32 v81, v57, v81
	v_fmac_f32_e32 v81, v56, v80
	v_mul_f32_e32 v80, v41, v83
	ds_bpermute_b32 v91, v66, v90
	v_fmac_f32_e32 v80, v40, v82
	v_add_f32_e32 v80, v81, v80
	s_waitcnt lgkmcnt(1)
	v_mul_f32_e32 v81, v39, v85
	v_mul_f32_e32 v82, v37, v87
	v_fmac_f32_e32 v81, v38, v84
	v_fmac_f32_e32 v82, v36, v86
	v_add_f32_e32 v80, v92, v80
	v_add_f32_e32 v81, v81, v82
	v_add_f32_e32 v80, v80, v81
	ds_bpermute_b32 v81, v66, v80
	s_waitcnt lgkmcnt(1)
	v_add_f32_e32 v83, v90, v91
	ds_bpermute_b32 v84, v67, v83
	ds_bpermute_b32 v89, v68, v79
	ds_bpermute_b32 v82, v70, v88
	s_waitcnt lgkmcnt(3)
	v_add_f32_e32 v80, v80, v81
	ds_bpermute_b32 v81, v67, v80
	s_waitcnt lgkmcnt(3)
	v_add_f32_e32 v83, v83, v84
	ds_bpermute_b32 v84, v68, v83
	s_waitcnt lgkmcnt(3)
	v_add_f32_e32 v85, v79, v89
	ds_bpermute_b32 v86, v69, v85
	s_waitcnt lgkmcnt(2)
	v_add_f32_e32 v80, v80, v81
	ds_bpermute_b32 v81, v68, v80
	s_waitcnt lgkmcnt(2)
	v_add_f32_e32 v83, v83, v84
	ds_bpermute_b32 v84, v69, v83
	s_waitcnt lgkmcnt(2)
	v_add_f32_e32 v85, v85, v86
	ds_bpermute_b32 v86, v70, v85
	s_waitcnt lgkmcnt(2)
	v_add_f32_e32 v81, v80, v81
	ds_bpermute_b32 v87, v69, v81
	s_waitcnt lgkmcnt(2)
	v_add_f32_e32 v84, v83, v84
	v_add_f32_e32 v79, v88, v82
	ds_bpermute_b32 v88, v70, v84
	s_waitcnt lgkmcnt(2)
	v_add_f32_e32 v80, v85, v86
	s_waitcnt lgkmcnt(1)
	v_add_f32_e32 v85, v81, v87
	ds_bpermute_b32 v87, v70, v85
	ds_read_b128 v[92:95], v1 offset:21504
	s_waitcnt lgkmcnt(2)
	v_add_f32_e32 v81, v84, v88
	ds_read_b128 v[88:91], v1 offset:20480
	ds_bpermute_b32 v82, v71, v79
	s_waitcnt lgkmcnt(3)
	v_add_f32_e32 v84, v85, v87
	s_waitcnt lgkmcnt(2)
	v_mul_f32_e32 v93, v61, v93
	v_fmac_f32_e32 v93, v60, v92
	s_waitcnt lgkmcnt(1)
	v_mul_f32_e32 v87, v65, v89
	v_fmac_f32_e32 v87, v64, v88
	v_mul_f32_e32 v88, v63, v91
	v_fmac_f32_e32 v88, v62, v90
	v_mul_f32_e32 v92, v59, v95
	v_add_f32_e32 v87, v87, v88
	ds_read_b128 v[88:91], v1 offset:22528
	v_fmac_f32_e32 v92, v58, v94
	v_add_f32_e32 v87, 0, v87
	v_add_f32_e32 v92, v93, v92
	v_add_f32_e32 v87, v87, v92
	ds_read_b128 v[92:95], v1 offset:23552
	s_waitcnt lgkmcnt(1)
	v_mul_f32_e32 v89, v57, v89
	v_fmac_f32_e32 v89, v56, v88
	v_mul_f32_e32 v88, v41, v91
	v_fmac_f32_e32 v88, v40, v90
	s_waitcnt lgkmcnt(0)
	v_mul_f32_e32 v93, v39, v93
	v_add_f32_e32 v88, v89, v88
	v_fmac_f32_e32 v93, v38, v92
	v_mul_f32_e32 v92, v37, v95
	v_add_f32_e32 v87, v87, v88
	v_fmac_f32_e32 v92, v36, v94
	ds_read_b128 v[88:91], v1 offset:24576
	v_add_f32_e32 v92, v93, v92
	v_add_f32_e32 v87, v87, v92
	ds_read_b128 v[92:95], v1 offset:25600
	ds_bpermute_b32 v96, v66, v87
	s_waitcnt lgkmcnt(2)
	v_mul_f32_e32 v89, v65, v89
	v_fmac_f32_e32 v89, v64, v88
	v_mul_f32_e32 v88, v63, v91
	v_fmac_f32_e32 v88, v62, v90
	s_waitcnt lgkmcnt(1)
	v_mul_f32_e32 v93, v61, v93
	v_add_f32_e32 v88, v89, v88
	v_fmac_f32_e32 v93, v60, v92
	v_mul_f32_e32 v92, v59, v95
	v_add_f32_e32 v97, 0, v88
	ds_read_b128 v[88:91], v1 offset:26624
	v_fmac_f32_e32 v92, v58, v94
	v_add_f32_e32 v92, v93, v92
	v_add_f32_e32 v97, v97, v92
	ds_read_b128 v[92:95], v1 offset:27648
	s_waitcnt lgkmcnt(1)
	v_mul_f32_e32 v89, v57, v89
	v_fmac_f32_e32 v89, v56, v88
	v_mul_f32_e32 v88, v41, v91
	v_fmac_f32_e32 v88, v40, v90
	s_waitcnt lgkmcnt(0)
	v_mul_f32_e32 v93, v39, v93
	v_add_f32_e32 v88, v89, v88
	v_fmac_f32_e32 v93, v38, v92
	v_mul_f32_e32 v92, v37, v95
	v_add_f32_e32 v97, v97, v88
	v_fmac_f32_e32 v92, v36, v94
	ds_read_b128 v[88:91], v1 offset:28672
	v_add_f32_e32 v92, v93, v92
	v_add_f32_e32 v97, v97, v92
	ds_read_b128 v[92:95], v1 offset:29696
	ds_bpermute_b32 v98, v66, v97
	s_waitcnt lgkmcnt(2)
	v_mul_f32_e32 v65, v65, v89
	v_mul_f32_e32 v63, v63, v91
	v_fmac_f32_e32 v65, v64, v88
	v_fmac_f32_e32 v63, v62, v90
	v_add_f32_e32 v62, v65, v63
	s_waitcnt lgkmcnt(1)
	v_mul_f32_e32 v65, v61, v93
	v_add_f32_e32 v64, 0, v62
	v_fmac_f32_e32 v65, v60, v92
	ds_read_b128 v[60:63], v1 offset:30720
	ds_read_b128 v[88:91], v1 offset:31744
	v_mul_f32_e32 v59, v59, v95
	v_fmac_f32_e32 v59, v58, v94
	v_add_f32_e32 v58, v65, v59
	s_waitcnt lgkmcnt(1)
	v_mul_f32_e32 v57, v57, v61
	v_mul_f32_e32 v41, v41, v63
	v_fmac_f32_e32 v57, v56, v60
	v_fmac_f32_e32 v41, v40, v62
	s_waitcnt lgkmcnt(0)
	v_mul_f32_e32 v39, v39, v89
	v_mul_f32_e32 v37, v37, v91
	v_add_f32_e32 v58, v64, v58
	v_add_f32_e32 v40, v57, v41
	v_fmac_f32_e32 v39, v38, v88
	v_fmac_f32_e32 v37, v36, v90
	v_add_f32_e32 v40, v58, v40
	v_add_f32_e32 v36, v39, v37
	v_add_f32_e32 v36, v40, v36
	ds_bpermute_b32 v37, v66, v36
	v_add_f32_e32 v38, v87, v96
	v_add_f32_e32 v40, v97, v98
	ds_bpermute_b32 v39, v67, v38
	ds_bpermute_b32 v41, v67, v40
	s_waitcnt lgkmcnt(2)
	v_add_f32_e32 v36, v36, v37
	ds_bpermute_b32 v37, v67, v36
	ds_bpermute_b32 v83, v71, v80
	s_waitcnt lgkmcnt(3)
	v_add_f32_e32 v38, v38, v39
	s_waitcnt lgkmcnt(2)
	v_add_f32_e32 v40, v40, v41
	ds_bpermute_b32 v39, v68, v38
	s_waitcnt lgkmcnt(2)
	v_add_f32_e32 v36, v36, v37
	ds_bpermute_b32 v41, v68, v40
	ds_bpermute_b32 v37, v68, v36
	ds_bpermute_b32 v86, v71, v81
	s_waitcnt lgkmcnt(3)
	v_add_f32_e32 v38, v38, v39
	ds_bpermute_b32 v39, v69, v38
	s_waitcnt lgkmcnt(3)
	v_add_f32_e32 v40, v40, v41
	s_waitcnt lgkmcnt(2)
	v_add_f32_e32 v36, v36, v37
	ds_bpermute_b32 v41, v69, v40
	ds_bpermute_b32 v37, v69, v36
	s_waitcnt lgkmcnt(2)
	v_add_f32_e32 v38, v38, v39
	ds_bpermute_b32 v39, v70, v38
	ds_bpermute_b32 v85, v71, v84
	s_waitcnt lgkmcnt(3)
	v_add_f32_e32 v56, v40, v41
	s_waitcnt lgkmcnt(2)
	v_add_f32_e32 v36, v36, v37
	ds_bpermute_b32 v57, v70, v56
	ds_bpermute_b32 v37, v70, v36
	s_waitcnt lgkmcnt(3)
	v_add_f32_e32 v40, v38, v39
	ds_bpermute_b32 v41, v71, v40
	s_waitcnt lgkmcnt(2)
	v_add_f32_e32 v38, v56, v57
	s_waitcnt lgkmcnt(1)
	v_add_f32_e32 v36, v36, v37
	ds_bpermute_b32 v39, v71, v38
	ds_bpermute_b32 v37, v71, v36
	s_and_saveexec_b64 s[26:27], s[68:69]
	s_waitcnt vmcnt(4)
	s_cbranch_execz .LBB0_28
	v_readlane_b32 s36, v254, 5
	v_readlane_b32 s37, v254, 6
	v_lshl_add_u64 v[34:35], s[74:75], 0, v[52:53]
	v_add_f32_e32 v55, v77, v78
	v_add_co_u32_e32 v34, vcc, 0x26a8000, v34
	v_readlane_b32 s38, v254, 7
	s_nop 0
	v_addc_co_u32_e32 v35, vcc, 0, v35, vcc
	v_readlane_b32 s39, v254, 8
	s_waitcnt lgkmcnt(2)
	v_add_f32_e32 v40, v40, v41
	s_waitcnt lgkmcnt(1)
	v_add_f32_e32 v38, v38, v39
	s_waitcnt lgkmcnt(0)
	v_add_f32_e32 v36, v36, v37
	v_readlane_b32 s40, v254, 9
	v_readlane_b32 s41, v254, 10
	v_readlane_b32 s42, v254, 11
	v_readlane_b32 s43, v254, 12
	v_readlane_b32 s44, v254, 13
	v_readlane_b32 s45, v254, 14
	v_readlane_b32 s46, v254, 15
	v_readlane_b32 s47, v254, 16
	v_readlane_b32 s48, v254, 17
	v_readlane_b32 s49, v254, 18
	v_readlane_b32 s50, v254, 19
	v_readlane_b32 s51, v254, 20
	v_add_f32_e32 v56, v79, v82
	v_add_f32_e32 v57, v80, v83
	v_add_f32_e32 v58, v81, v86
	v_cndmask_b32_e64 v55, v55, v56, s[18:19]
	v_cndmask_b32_e64 v55, v55, v57, s[20:21]
	v_cndmask_b32_e64 v55, v55, v58, s[22:23]
	v_add_f32_e32 v54, v110, v55
	v_add_co_u32_e32 v34, vcc, v112, v34
	s_nop 1
	v_addc_co_u32_e32 v35, vcc, 0, v35, vcc
	global_store_dword v[34:35], v54, off
	v_add_f32_e32 v55, v84, v85
	v_cndmask_b32_e64 v55, v55, v40, s[18:19]
	v_cndmask_b32_e64 v55, v55, v38, s[20:21]
	v_cndmask_b32_e64 v55, v55, v36, s[22:23]
	v_add_f32_e32 v54, v111, v55
	v_mul_f32_e64 v55, |v54|, s30
	v_fma_f32 v56, |v54|, s30, -v55
	v_rndne_f32_e32 v57, v55
	v_fma_f32 v56, |v54|, s31, v56
	v_sub_f32_e32 v55, v55, v57
	v_add_f32_e32 v55, v55, v56
	v_cvt_i32_f32_e32 v57, v57
	v_exp_f32_e32 v55, v55
	v_cmp_ngt_f32_e64 vcc, |v54|, s34
	v_min_f32_e32 v56, 0, v54
	v_ldexp_f32 v55, v55, v57
	v_cndmask_b32_e32 v55, 0, v55, vcc
	v_cmp_nlt_f32_e64 vcc, |v54|, s35
	s_nop 1
	v_cndmask_b32_e32 v57, v76, v55, vcc
	v_add_f32_e32 v58, 1.0, v57
	v_add_f32_e32 v59, -1.0, v58
	v_frexp_mant_f32_e32 v60, v58
	v_cvt_f64_f32_e32 v[54:55], v58
	v_sub_f32_e32 v61, v59, v58
	v_frexp_exp_i32_f64_e32 v54, v[54:55]
	v_cmp_gt_f32_e32 vcc, s65, v60
	v_sub_f32_e32 v59, v57, v59
	v_add_f32_e32 v55, 1.0, v61
	v_subbrev_co_u32_e32 v54, vcc, 0, v54, vcc
	v_add_f32_e32 v55, v59, v55
	v_sub_u32_e32 v59, 0, v54
	v_cvt_f32_i32_e32 v54, v54
	v_ldexp_f32 v58, v58, v59
	v_ldexp_f32 v55, v55, v59
	v_add_f32_e32 v59, -1.0, v58
	v_add_f32_e32 v60, 1.0, v58
	v_add_f32_e32 v61, 1.0, v59
	v_add_f32_e32 v62, -1.0, v60
	v_sub_f32_e32 v61, v58, v61
	v_sub_f32_e32 v58, v58, v62
	v_mul_f32_e32 v62, 0x3f317218, v54
	v_add_f32_e32 v61, v55, v61
	v_add_f32_e32 v55, v55, v58
	v_fma_f32 v58, v54, s66, -v62
	v_add_f32_e32 v63, v59, v61
	v_add_f32_e32 v64, v60, v55
	v_fmac_f32_e32 v58, 0xb102e308, v54
	v_sub_f32_e32 v54, v59, v63
	v_sub_f32_e32 v59, v60, v64
	v_rcp_f32_e32 v60, v64
	v_add_f32_e32 v65, v62, v58
	v_add_f32_e32 v55, v55, v59
	v_sub_f32_e32 v59, v65, v62
	v_sub_f32_e32 v58, v58, v59
	v_mul_f32_e32 v59, v63, v60
	v_add_f32_e32 v54, v61, v54
	v_mul_f32_e32 v61, v64, v59
	v_fma_f32 v62, v59, v64, -v61
	v_fmac_f32_e32 v62, v59, v55
	v_add_f32_e32 v77, v61, v62
	v_sub_f32_e32 v78, v63, v77
	v_sub_f32_e32 v61, v77, v61
	v_sub_f32_e32 v63, v63, v78
	v_sub_f32_e32 v61, v61, v62
	v_sub_f32_e32 v62, v63, v77
	v_add_f32_e32 v54, v54, v62
	v_add_f32_e32 v54, v61, v54
	v_add_f32_e32 v61, v78, v54
	v_mul_f32_e32 v62, v60, v61
	v_sub_f32_e32 v63, v78, v61
	v_mul_f32_e32 v77, v64, v62
	v_add_f32_e32 v54, v54, v63
	v_add_f32_e32 v63, v59, v62
	v_fma_f32 v64, v62, v64, -v77
	v_sub_f32_e32 v59, v63, v59
	v_fmac_f32_e32 v64, v62, v55
	v_sub_f32_e32 v55, v62, v59
	v_add_f32_e32 v59, v77, v64
	v_sub_f32_e32 v62, v59, v77
	v_sub_f32_e32 v77, v61, v59
	v_sub_f32_e32 v61, v61, v77
	v_sub_f32_e32 v59, v61, v59
	v_sub_f32_e32 v62, v62, v64
	v_add_f32_e32 v54, v54, v59
	v_add_f32_e32 v54, v62, v54
	v_add_f32_e32 v54, v77, v54
	v_mul_f32_e32 v54, v60, v54
	v_add_f32_e32 v54, v55, v54
	v_add_f32_e32 v55, v63, v54
	v_mul_f32_e32 v59, v55, v55
	v_fmamk_f32 v62, v59, 0x3e9b6dac, v75
	v_sub_f32_e32 v60, v55, v63
	v_ldexp_f32 v61, v55, 1
	v_mul_f32_e32 v55, v55, v59
	v_fmaak_f32 v59, v59, v62, 0x3f2aaada
	v_mul_f32_e32 v55, v55, v59
	v_add_f32_e32 v59, v61, v55
	v_sub_f32_e32 v54, v54, v60
	v_sub_f32_e32 v60, v59, v61
	v_ldexp_f32 v54, v54, 1
	v_sub_f32_e32 v55, v55, v60
	v_add_f32_e32 v54, v54, v55
	v_add_f32_e32 v55, v59, v54
	v_sub_f32_e32 v59, v55, v59
	v_add_f32_e32 v60, v65, v55
	v_sub_f32_e32 v54, v54, v59
	v_sub_f32_e32 v59, v60, v65
	v_sub_f32_e32 v61, v60, v59
	v_sub_f32_e32 v55, v55, v59
	v_add_f32_e32 v59, v58, v54
	v_sub_f32_e32 v61, v65, v61
	v_sub_f32_e32 v62, v59, v58
	v_add_f32_e32 v55, v55, v61
	v_sub_f32_e32 v61, v59, v62
	v_sub_f32_e32 v54, v54, v62
	v_sub_f32_e32 v58, v58, v61
	v_add_f32_e32 v55, v59, v55
	v_add_f32_e32 v54, v54, v58
	v_add_f32_e32 v58, v60, v55
	v_sub_f32_e32 v59, v58, v60
	v_sub_f32_e32 v55, v55, v59
	v_add_f32_e32 v54, v54, v55
	v_add_f32_e32 v54, v58, v54
	v_cmp_neq_f32_e32 vcc, s64, v57
	s_nop 1
	v_cndmask_b32_e32 v54, v76, v54, vcc
	v_cmp_lt_f32_e64 vcc, |v57|, s67
	s_nop 1
	v_cndmask_b32_e32 v54, v54, v57, vcc
	v_sub_f32_e32 v54, v56, v54
	global_store_dword v[34:35], v54, off offset:16
.LBB0_28:
	s_or_b64 exec, exec, s[26:27]
	s_and_saveexec_b64 s[26:27], s[4:5]
	s_cbranch_execz .LBB0_25
	v_pk_mul_f32 v[34:35], v[32:33], v[32:33]
	s_waitcnt lgkmcnt(0)
	v_pk_mul_f32 v[36:37], v[30:31], v[30:31]
	s_nop 0
	v_pk_mov_b32 v[38:39], v[36:37], v[34:35] op_sel:[1,0]
	v_mov_b32_e32 v37, v35
	v_pk_add_f32 v[34:35], v[38:39], v[36:37]
	v_pk_mul_f32 v[36:37], v[28:29], v[28:29]
	v_pk_mul_f32 v[38:39], v[26:27], v[26:27]
	v_pk_add_f32 v[34:35], v[34:35], v[34:35] op_sel:[0,1] op_sel_hi:[1,0]
	v_pk_mov_b32 v[40:41], v[38:39], v[36:37] op_sel:[1,0]
	v_mov_b32_e32 v39, v37
	v_pk_add_f32 v[36:37], v[40:41], v[38:39]
	v_mul_f32_e32 v38, v18, v18
	v_mul_f32_e32 v39, v19, v19
	v_pk_add_f32 v[36:37], v[36:37], v[36:37] op_sel:[0,1] op_sel_hi:[1,0]
	v_mov_b32_e32 v35, v38
	v_mov_b32_e32 v37, v39
	v_pk_add_f32 v[34:35], v[34:35], v[36:37]
	v_mul_f32_e32 v36, v23, v23
	v_mul_f32_e32 v38, v25, v25
	v_mul_f32_e32 v40, v20, v20
	v_mul_f32_e32 v41, v21, v21
	v_pk_fma_f32 v[36:37], v[22:23], v[22:23], v[36:37] op_sel_hi:[1,1,0]
	v_pk_fma_f32 v[38:39], v[24:25], v[24:25], v[38:39] op_sel_hi:[1,1,0]
	v_mov_b32_e32 v37, v40
	v_mov_b32_e32 v39, v41
	v_pk_add_f32 v[36:37], v[36:37], v[38:39]
	s_nop 0
	v_pk_add_f32 v[34:35], v[34:35], v[36:37]
	v_lshl_add_u64 v[36:37], s[74:75], 0, v[48:49]
	v_add_f32_e32 v34, v34, v35
	ds_bpermute_b32 v35, v66, v34
	s_waitcnt lgkmcnt(0)
	v_add_f32_e32 v34, v34, v35
	ds_bpermute_b32 v35, v67, v34
	s_waitcnt lgkmcnt(0)
	v_add_f32_e32 v34, v34, v35
	ds_bpermute_b32 v35, v68, v34
	s_waitcnt lgkmcnt(0)
	v_add_f32_e32 v34, v34, v35
	ds_bpermute_b32 v35, v69, v34
	s_waitcnt lgkmcnt(0)
	v_add_f32_e32 v34, v34, v35
	ds_bpermute_b32 v35, v70, v34
	s_waitcnt lgkmcnt(0)
	v_add_f32_e32 v34, v34, v35
	ds_bpermute_b32 v35, v71, v34
	s_waitcnt lgkmcnt(0)
	v_add_f32_e32 v34, v34, v35
	v_fmamk_f32 v34, v34, 0x3a800000, v74
	v_mul_f32_e32 v35, 0x4b800000, v34
	v_cmp_gt_f32_e32 vcc, s28, v34
	s_nop 1
	v_cndmask_b32_e32 v34, v34, v35, vcc
	v_rsq_f32_e32 v34, v34
	s_nop 0
	v_mul_f32_e32 v35, 0x45800000, v34
	v_cndmask_b32_e32 v38, v34, v35, vcc
	v_pk_mul_f32 v[30:31], v[30:31], v[38:39] op_sel_hi:[1,0]
	v_pk_mul_f32 v[32:33], v[32:33], v[38:39] op_sel_hi:[1,0]
	v_pk_mul_f32 v[34:35], v[2:3], v[30:31]
	v_add_co_u32_e32 v30, vcc, s29, v36
	v_pk_mul_f32 v[32:33], v[4:5], v[32:33]
	s_nop 0
	v_addc_co_u32_e32 v31, vcc, 0, v37, vcc
	v_pk_mul_f32 v[36:37], v[26:27], v[38:39] op_sel_hi:[1,0]
	v_pk_mul_f32 v[26:27], v[28:29], v[38:39] op_sel_hi:[1,0]
	v_cvt_pk_bf16_f32 v40, v34, v35
	v_cvt_pk_bf16_f32 v41, v32, v33
	global_store_dwordx2 v[30:31], v[40:41], off
	v_pk_mul_f32 v[26:27], v[8:9], v[26:27]
	v_pk_mul_f32 v[28:29], v[6:7], v[36:37]
	v_pk_mul_f32 v[18:19], v[18:19], v[38:39] op_sel_hi:[1,0]
	v_cvt_pk_bf16_f32 v36, v28, v29
	v_cvt_pk_bf16_f32 v37, v26, v27
	global_store_dwordx2 v[30:31], v[36:37], off offset:512
	v_pk_mul_f32 v[36:37], v[22:23], v[38:39] op_sel_hi:[1,0]
	v_pk_mul_f32 v[22:23], v[24:25], v[38:39] op_sel_hi:[1,0]
	v_pk_mul_f32 v[24:25], v[10:11], v[36:37]
	v_pk_mul_f32 v[22:23], v[12:13], v[22:23]
	v_cvt_pk_bf16_f32 v36, v24, v25
	v_pk_mul_f32 v[20:21], v[20:21], v[38:39] op_sel_hi:[1,0]
	v_cvt_pk_bf16_f32 v37, v22, v23
	global_store_dwordx2 v[30:31], v[36:37], off offset:1024
	v_pk_mul_f32 v[20:21], v[16:17], v[20:21]
	v_pk_mul_f32 v[36:37], v[14:15], v[18:19]
	s_nop 0
	v_cvt_pk_bf16_f32 v18, v36, v37
	v_cvt_pk_bf16_f32 v19, v20, v21
	ds_read_b128 v[38:41], v1
	ds_read_b128 v[54:57], v1 offset:1024
	global_store_dwordx2 v[30:31], v[18:19], off offset:1536
	ds_read_b128 v[78:81], v1 offset:21504
	s_waitcnt lgkmcnt(2)
	v_mul_f32_e32 v39, v35, v39
	v_fmac_f32_e32 v39, v34, v38
	v_mul_f32_e32 v38, v33, v41
	v_fmac_f32_e32 v38, v32, v40
	v_add_f32_e32 v38, v39, v38
	s_waitcnt lgkmcnt(1)
	v_mul_f32_e32 v55, v29, v55
	v_add_f32_e32 v58, 0, v38
	v_fmac_f32_e32 v55, v28, v54
	v_mul_f32_e32 v54, v27, v57
	ds_read_b128 v[38:41], v1 offset:2048
	v_fmac_f32_e32 v54, v26, v56
	v_add_f32_e32 v54, v55, v54
	v_add_f32_e32 v58, v58, v54
	ds_read_b128 v[54:57], v1 offset:3072
	s_waitcnt lgkmcnt(1)
	v_mul_f32_e32 v39, v25, v39
	v_fmac_f32_e32 v39, v24, v38
	v_mul_f32_e32 v38, v23, v41
	v_fmac_f32_e32 v38, v22, v40
	v_add_f32_e32 v38, v39, v38
	s_waitcnt lgkmcnt(0)
	v_mul_f32_e32 v39, v37, v55
	v_mul_f32_e32 v40, v21, v57
	v_fmac_f32_e32 v39, v36, v54
	v_fmac_f32_e32 v40, v20, v56
	v_add_f32_e32 v38, v58, v38
	v_add_f32_e32 v39, v39, v40
	v_add_f32_e32 v54, v38, v39
	ds_bpermute_b32 v55, v66, v54
	ds_read_b128 v[38:41], v1 offset:4096
	v_mul_f32_e32 v77, v27, v81
	v_fmac_f32_e32 v77, v26, v80
	s_waitcnt lgkmcnt(1)
	v_add_f32_e32 v58, v54, v55
	ds_read_b128 v[54:57], v1 offset:5120
	s_waitcnt lgkmcnt(1)
	v_mul_f32_e32 v39, v35, v39
	v_fmac_f32_e32 v39, v34, v38
	v_mul_f32_e32 v38, v33, v41
	v_fmac_f32_e32 v38, v32, v40
	v_add_f32_e32 v38, v39, v38
	s_waitcnt lgkmcnt(0)
	v_mul_f32_e32 v55, v29, v55
	v_add_f32_e32 v60, 0, v38
	v_fmac_f32_e32 v55, v28, v54
	v_mul_f32_e32 v54, v27, v57
	ds_read_b128 v[38:41], v1 offset:6144
	v_fmac_f32_e32 v54, v26, v56
	v_add_f32_e32 v54, v55, v54
	v_add_f32_e32 v60, v60, v54
	ds_read_b128 v[54:57], v1 offset:7168
	s_waitcnt lgkmcnt(1)
	v_mul_f32_e32 v39, v25, v39
	v_fmac_f32_e32 v39, v24, v38
	v_mul_f32_e32 v38, v23, v41
	v_fmac_f32_e32 v38, v22, v40
	v_add_f32_e32 v38, v39, v38
	s_waitcnt lgkmcnt(0)
	v_mul_f32_e32 v39, v37, v55
	v_mul_f32_e32 v40, v21, v57
	ds_bpermute_b32 v59, v67, v58
	v_fmac_f32_e32 v39, v36, v54
	v_fmac_f32_e32 v40, v20, v56
	v_add_f32_e32 v38, v60, v38
	v_add_f32_e32 v39, v39, v40
	v_add_f32_e32 v38, v38, v39
	ds_bpermute_b32 v39, v66, v38
	s_waitcnt lgkmcnt(1)
	v_add_f32_e32 v40, v58, v59
	ds_bpermute_b32 v41, v68, v40
	s_waitcnt lgkmcnt(1)
	v_add_f32_e32 v54, v38, v39
	ds_bpermute_b32 v55, v67, v54
	s_waitcnt lgkmcnt(1)
	v_add_f32_e32 v58, v40, v41
	ds_read_b128 v[38:41], v1 offset:8192
	ds_bpermute_b32 v59, v69, v58
	s_waitcnt lgkmcnt(2)
	v_add_f32_e32 v60, v54, v55
	ds_read_b128 v[54:57], v1 offset:9216
	s_waitcnt lgkmcnt(2)
	v_mul_f32_e32 v39, v35, v39
	v_fmac_f32_e32 v39, v34, v38
	v_mul_f32_e32 v38, v33, v41
	v_fmac_f32_e32 v38, v32, v40
	v_add_f32_e32 v38, v39, v38
	s_waitcnt lgkmcnt(0)
	v_mul_f32_e32 v55, v29, v55
	v_add_f32_e32 v62, 0, v38
	v_fmac_f32_e32 v55, v28, v54
	v_mul_f32_e32 v54, v27, v57
	ds_read_b128 v[38:41], v1 offset:10240
	v_fmac_f32_e32 v54, v26, v56
	v_add_f32_e32 v54, v55, v54
	v_add_f32_e32 v62, v62, v54
	ds_read_b128 v[54:57], v1 offset:11264
	s_waitcnt lgkmcnt(1)
	v_mul_f32_e32 v39, v25, v39
	v_fmac_f32_e32 v39, v24, v38
	v_mul_f32_e32 v38, v23, v41
	v_fmac_f32_e32 v38, v22, v40
	v_add_f32_e32 v38, v39, v38
	s_waitcnt lgkmcnt(0)
	v_mul_f32_e32 v39, v37, v55
	v_mul_f32_e32 v40, v21, v57
	v_fmac_f32_e32 v39, v36, v54
	v_fmac_f32_e32 v40, v20, v56
	v_add_f32_e32 v38, v62, v38
	v_add_f32_e32 v39, v39, v40
	v_add_f32_e32 v38, v38, v39
	ds_bpermute_b32 v61, v68, v60
	ds_bpermute_b32 v39, v66, v38
	v_add_f32_e32 v40, v58, v59
	ds_bpermute_b32 v41, v70, v40
	ds_read_b128 v[54:57], v1 offset:12288
	s_waitcnt lgkmcnt(3)
	v_add_f32_e32 v58, v60, v61
	s_waitcnt lgkmcnt(2)
	v_add_f32_e32 v60, v38, v39
	ds_bpermute_b32 v59, v69, v58
	ds_bpermute_b32 v61, v67, v60
	s_waitcnt lgkmcnt(3)
	v_add_f32_e32 v38, v40, v41
	ds_bpermute_b32 v39, v71, v38
	s_waitcnt lgkmcnt(2)
	v_add_f32_e32 v40, v58, v59
	s_waitcnt lgkmcnt(1)
	v_add_f32_e32 v41, v60, v61
	ds_read_b128 v[58:61], v1 offset:13312
	v_mul_f32_e32 v55, v35, v55
	v_fmac_f32_e32 v55, v34, v54
	v_mul_f32_e32 v54, v33, v57
	v_fmac_f32_e32 v54, v32, v56
	v_add_f32_e32 v54, v55, v54
	s_waitcnt lgkmcnt(0)
	v_mul_f32_e32 v59, v29, v59
	v_add_f32_e32 v63, 0, v54
	v_fmac_f32_e32 v59, v28, v58
	v_mul_f32_e32 v58, v27, v61
	ds_read_b128 v[54:57], v1 offset:14336
	v_fmac_f32_e32 v58, v26, v60
	v_add_f32_e32 v58, v59, v58
	v_add_f32_e32 v63, v63, v58
	ds_read_b128 v[58:61], v1 offset:15360
	s_waitcnt lgkmcnt(1)
	v_mul_f32_e32 v55, v25, v55
	v_fmac_f32_e32 v55, v24, v54
	v_mul_f32_e32 v54, v23, v57
	v_fmac_f32_e32 v54, v22, v56
	v_add_f32_e32 v54, v55, v54
	s_waitcnt lgkmcnt(0)
	v_mul_f32_e32 v59, v37, v59
	v_add_f32_e32 v63, v63, v54
	v_fmac_f32_e32 v59, v36, v58
	v_mul_f32_e32 v58, v21, v61
	ds_read_b128 v[54:57], v1 offset:16384
	v_fmac_f32_e32 v58, v20, v60
	v_add_f32_e32 v58, v59, v58
	v_add_f32_e32 v63, v63, v58
	ds_read_b128 v[58:61], v1 offset:17408
	s_waitcnt lgkmcnt(1)
	v_mul_f32_e32 v55, v35, v55
	v_fmac_f32_e32 v55, v34, v54
	v_mul_f32_e32 v54, v33, v57
	v_fmac_f32_e32 v54, v32, v56
	v_add_f32_e32 v54, v55, v54
	s_waitcnt lgkmcnt(0)
	v_mul_f32_e32 v59, v29, v59
	v_add_f32_e32 v65, 0, v54
	v_fmac_f32_e32 v59, v28, v58
	v_mul_f32_e32 v58, v27, v61
	ds_read_b128 v[54:57], v1 offset:18432
	v_fmac_f32_e32 v58, v26, v60
	v_add_f32_e32 v58, v59, v58
	v_add_f32_e32 v65, v65, v58
	ds_read_b128 v[58:61], v1 offset:19456
	s_waitcnt lgkmcnt(1)
	v_mul_f32_e32 v55, v25, v55
	v_fmac_f32_e32 v55, v24, v54
	v_mul_f32_e32 v54, v23, v57
	v_fmac_f32_e32 v54, v22, v56
	v_add_f32_e32 v54, v55, v54
	s_waitcnt lgkmcnt(0)
	v_mul_f32_e32 v55, v37, v59
	v_mul_f32_e32 v56, v21, v61
	v_fmac_f32_e32 v55, v36, v58
	v_fmac_f32_e32 v56, v20, v60
	v_add_f32_e32 v54, v65, v54
	v_add_f32_e32 v55, v55, v56
	v_add_f32_e32 v54, v54, v55
	ds_bpermute_b32 v64, v66, v63
	ds_bpermute_b32 v55, v66, v54
	ds_bpermute_b32 v62, v68, v41
	ds_bpermute_b32 v56, v70, v40
	s_waitcnt lgkmcnt(3)
	v_add_f32_e32 v57, v63, v64
	s_waitcnt lgkmcnt(2)
	v_add_f32_e32 v54, v54, v55
	ds_bpermute_b32 v58, v67, v57
	ds_bpermute_b32 v55, v67, v54
	s_waitcnt lgkmcnt(3)
	v_add_f32_e32 v41, v41, v62
	ds_bpermute_b32 v59, v69, v41
	s_waitcnt lgkmcnt(3)
	v_add_f32_e32 v40, v40, v56
	s_waitcnt lgkmcnt(2)
	v_add_f32_e32 v57, v57, v58
	s_waitcnt lgkmcnt(1)
	v_add_f32_e32 v54, v54, v55
	ds_bpermute_b32 v58, v68, v57
	ds_bpermute_b32 v55, v68, v54
	s_waitcnt lgkmcnt(2)
	v_add_f32_e32 v41, v41, v59
	ds_read_b128 v[60:63], v1 offset:20480
	s_waitcnt lgkmcnt(2)
	v_add_f32_e32 v56, v57, v58
	s_waitcnt lgkmcnt(1)
	v_add_f32_e32 v54, v54, v55
	ds_bpermute_b32 v57, v69, v56
	ds_bpermute_b32 v59, v69, v54
	s_waitcnt lgkmcnt(2)
	v_mul_f32_e32 v61, v35, v61
	v_fmac_f32_e32 v61, v34, v60
	v_mul_f32_e32 v60, v33, v63
	s_waitcnt lgkmcnt(1)
	v_add_f32_e32 v56, v56, v57
	s_waitcnt lgkmcnt(0)
	v_add_f32_e32 v64, v54, v59
	ds_bpermute_b32 v57, v70, v56
	ds_bpermute_b32 v65, v70, v64
	v_fmac_f32_e32 v60, v32, v62
	v_add_f32_e32 v60, v61, v60
	ds_bpermute_b32 v58, v70, v41
	s_waitcnt lgkmcnt(2)
	v_add_f32_e32 v54, v56, v57
	s_waitcnt lgkmcnt(1)
	v_add_f32_e32 v56, v64, v65
	v_add_f32_e32 v64, 0, v60
	ds_read_b128 v[60:63], v1 offset:22528
	v_mul_f32_e32 v65, v29, v79
	v_fmac_f32_e32 v65, v28, v78
	ds_read_b128 v[78:81], v1 offset:23552
	v_add_f32_e32 v65, v65, v77
	s_waitcnt lgkmcnt(1)
	v_mul_f32_e32 v61, v25, v61
	v_fmac_f32_e32 v61, v24, v60
	v_mul_f32_e32 v60, v23, v63
	v_fmac_f32_e32 v60, v22, v62
	v_add_f32_e32 v64, v64, v65
	v_add_f32_e32 v60, v61, v60
	v_add_f32_e32 v64, v64, v60
	ds_read_b128 v[60:63], v1 offset:24576
	s_waitcnt lgkmcnt(1)
	v_mul_f32_e32 v65, v37, v79
	v_mul_f32_e32 v77, v21, v81
	v_fmac_f32_e32 v65, v36, v78
	v_fmac_f32_e32 v77, v20, v80
	ds_read_b128 v[78:81], v1 offset:25600
	s_waitcnt lgkmcnt(1)
	v_mul_f32_e32 v61, v35, v61
	v_fmac_f32_e32 v61, v34, v60
	v_mul_f32_e32 v60, v33, v63
	v_fmac_f32_e32 v60, v32, v62
	s_waitcnt lgkmcnt(0)
	v_mul_f32_e32 v79, v29, v79
	v_add_f32_e32 v60, v61, v60
	v_fmac_f32_e32 v79, v28, v78
	v_mul_f32_e32 v78, v27, v81
	v_add_f32_e32 v65, v65, v77
	v_add_f32_e32 v77, 0, v60
	ds_read_b128 v[60:63], v1 offset:26624
	v_fmac_f32_e32 v78, v26, v80
	v_add_f32_e32 v78, v79, v78
	v_add_f32_e32 v77, v77, v78
	ds_read_b128 v[78:81], v1 offset:27648
	s_waitcnt lgkmcnt(1)
	v_mul_f32_e32 v61, v25, v61
	v_fmac_f32_e32 v61, v24, v60
	v_mul_f32_e32 v60, v23, v63
	v_fmac_f32_e32 v60, v22, v62
	s_waitcnt lgkmcnt(0)
	v_mul_f32_e32 v79, v37, v79
	v_add_f32_e32 v60, v61, v60
	v_fmac_f32_e32 v79, v36, v78
	v_mul_f32_e32 v78, v21, v81
	v_add_f32_e32 v77, v77, v60
	v_fmac_f32_e32 v78, v20, v80
	ds_read_b128 v[60:63], v1 offset:28672
	v_add_f32_e32 v78, v79, v78
	v_add_f32_e32 v77, v77, v78
	ds_read_b128 v[78:81], v1 offset:29696
	v_add_f32_e32 v64, v64, v65
	s_waitcnt lgkmcnt(1)
	v_mul_f32_e32 v35, v35, v61
	v_mul_f32_e32 v33, v33, v63
	v_fmac_f32_e32 v35, v34, v60
	v_fmac_f32_e32 v33, v32, v62
	v_add_f32_e32 v32, v35, v33
	s_waitcnt lgkmcnt(0)
	v_mul_f32_e32 v29, v29, v79
	v_mul_f32_e32 v27, v27, v81
	v_add_f32_e32 v60, 0, v32
	v_fmac_f32_e32 v29, v28, v78
	ds_read_b128 v[32:35], v1 offset:30720
	v_fmac_f32_e32 v27, v26, v80
	v_add_f32_e32 v26, v29, v27
	v_add_f32_e32 v60, v60, v26
	ds_read_b128 v[26:29], v1 offset:31744
	s_waitcnt lgkmcnt(1)
	v_mul_f32_e32 v25, v25, v33
	v_mul_f32_e32 v23, v23, v35
	v_fmac_f32_e32 v25, v24, v32
	v_fmac_f32_e32 v23, v22, v34
	v_add_f32_e32 v22, v25, v23
	s_waitcnt lgkmcnt(0)
	v_mul_f32_e32 v23, v37, v27
	v_mul_f32_e32 v21, v21, v29
	v_fmac_f32_e32 v23, v36, v26
	v_fmac_f32_e32 v21, v20, v28
	v_add_f32_e32 v22, v60, v22
	v_add_f32_e32 v20, v23, v21
	v_add_f32_e32 v20, v22, v20
	ds_bpermute_b32 v65, v66, v64
	ds_bpermute_b32 v82, v66, v77
	ds_bpermute_b32 v21, v66, v20
	v_add_f32_e32 v41, v41, v58
	ds_bpermute_b32 v55, v71, v40
	s_waitcnt lgkmcnt(3)
	v_add_f32_e32 v22, v64, v65
	s_waitcnt lgkmcnt(2)
	v_add_f32_e32 v24, v77, v82
	s_waitcnt lgkmcnt(1)
	v_add_f32_e32 v20, v20, v21
	ds_bpermute_b32 v23, v67, v22
	ds_bpermute_b32 v25, v67, v24
	ds_bpermute_b32 v21, v67, v20
	ds_bpermute_b32 v58, v71, v41
	ds_bpermute_b32 v59, v71, v54
	s_waitcnt lgkmcnt(4)
	v_add_f32_e32 v22, v22, v23
	s_waitcnt lgkmcnt(3)
	v_add_f32_e32 v24, v24, v25
	s_waitcnt lgkmcnt(2)
	v_add_f32_e32 v20, v20, v21
	ds_bpermute_b32 v23, v68, v22
	ds_bpermute_b32 v25, v68, v24
	ds_bpermute_b32 v21, v68, v20
	ds_bpermute_b32 v57, v71, v56
	s_waitcnt lgkmcnt(3)
	v_add_f32_e32 v22, v22, v23
	s_waitcnt lgkmcnt(2)
	v_add_f32_e32 v24, v24, v25
	s_waitcnt lgkmcnt(1)
	v_add_f32_e32 v20, v20, v21
	ds_bpermute_b32 v23, v69, v22
	ds_bpermute_b32 v25, v69, v24
	ds_bpermute_b32 v21, v69, v20
	s_waitcnt lgkmcnt(2)
	v_add_f32_e32 v22, v22, v23
	s_waitcnt lgkmcnt(1)
	v_add_f32_e32 v26, v24, v25
	s_waitcnt lgkmcnt(0)
	v_add_f32_e32 v20, v20, v21
	ds_bpermute_b32 v23, v70, v22
	ds_bpermute_b32 v27, v70, v26
	ds_bpermute_b32 v21, v70, v20
	s_waitcnt lgkmcnt(2)
	v_add_f32_e32 v24, v22, v23
	s_waitcnt lgkmcnt(1)
	v_add_f32_e32 v22, v26, v27
	s_waitcnt lgkmcnt(0)
	v_add_f32_e32 v20, v20, v21
	ds_bpermute_b32 v25, v71, v24
	ds_bpermute_b32 v23, v71, v22
	ds_bpermute_b32 v21, v71, v20
	s_and_b64 exec, exec, s[68:69]
	s_cbranch_execz .LBB0_25
	v_readlane_b32 s36, v254, 5
	v_readlane_b32 s37, v254, 6
	v_lshl_add_u64 v[18:19], s[74:75], 0, v[46:47]
	v_add_f32_e32 v27, v38, v39
	v_add_co_u32_e32 v18, vcc, 0x26a8000, v18
	v_readlane_b32 s38, v254, 7
	s_nop 0
	v_addc_co_u32_e32 v19, vcc, 0, v19, vcc
	v_readlane_b32 s39, v254, 8
	s_waitcnt lgkmcnt(2)
	v_add_f32_e32 v24, v24, v25
	s_waitcnt lgkmcnt(1)
	v_add_f32_e32 v22, v22, v23
	s_waitcnt lgkmcnt(0)
	v_add_f32_e32 v20, v20, v21
	v_readlane_b32 s40, v254, 9
	v_readlane_b32 s41, v254, 10
	v_readlane_b32 s42, v254, 11
	v_readlane_b32 s43, v254, 12
	v_readlane_b32 s44, v254, 13
	v_readlane_b32 s45, v254, 14
	v_readlane_b32 s46, v254, 15
	v_readlane_b32 s47, v254, 16
	v_readlane_b32 s48, v254, 17
	v_readlane_b32 s49, v254, 18
	v_readlane_b32 s50, v254, 19
	v_readlane_b32 s51, v254, 20
	v_add_f32_e32 v28, v40, v55
	v_add_f32_e32 v29, v41, v58
	v_add_f32_e32 v30, v54, v59
	v_cndmask_b32_e64 v27, v27, v28, s[18:19]
	v_cndmask_b32_e64 v27, v27, v29, s[20:21]
	v_cndmask_b32_e64 v27, v27, v30, s[22:23]
	v_add_f32_e32 v26, v110, v27
	v_add_co_u32_e32 v18, vcc, v112, v18
	s_nop 1
	v_addc_co_u32_e32 v19, vcc, 0, v19, vcc
	global_store_dword v[18:19], v26, off
	v_add_f32_e32 v27, v56, v57
	v_cndmask_b32_e64 v27, v27, v24, s[18:19]
	v_cndmask_b32_e64 v27, v27, v22, s[20:21]
	v_cndmask_b32_e64 v27, v27, v20, s[22:23]
	v_add_f32_e32 v26, v111, v27
	v_mul_f32_e64 v27, |v26|, s30
	v_fma_f32 v28, |v26|, s30, -v27
	v_rndne_f32_e32 v29, v27
	v_fma_f32 v28, |v26|, s31, v28
	v_sub_f32_e32 v27, v27, v29
	v_add_f32_e32 v27, v27, v28
	v_cvt_i32_f32_e32 v29, v29
	v_exp_f32_e32 v27, v27
	v_cmp_ngt_f32_e64 vcc, |v26|, s34
	v_min_f32_e32 v28, 0, v26
	v_ldexp_f32 v27, v27, v29
	v_cndmask_b32_e32 v27, 0, v27, vcc
	v_cmp_nlt_f32_e64 vcc, |v26|, s35
	s_nop 1
	v_cndmask_b32_e32 v29, v76, v27, vcc
	v_add_f32_e32 v30, 1.0, v29
	v_add_f32_e32 v31, -1.0, v30
	v_frexp_mant_f32_e32 v32, v30
	v_cvt_f64_f32_e32 v[26:27], v30
	v_sub_f32_e32 v33, v31, v30
	v_frexp_exp_i32_f64_e32 v26, v[26:27]
	v_cmp_gt_f32_e32 vcc, s65, v32
	v_sub_f32_e32 v31, v29, v31
	v_add_f32_e32 v27, 1.0, v33
	v_subbrev_co_u32_e32 v26, vcc, 0, v26, vcc
	v_add_f32_e32 v27, v31, v27
	v_sub_u32_e32 v31, 0, v26
	v_cvt_f32_i32_e32 v26, v26
	v_ldexp_f32 v30, v30, v31
	v_ldexp_f32 v27, v27, v31
	v_add_f32_e32 v31, -1.0, v30
	v_add_f32_e32 v32, 1.0, v30
	v_add_f32_e32 v33, 1.0, v31
	v_add_f32_e32 v34, -1.0, v32
	v_sub_f32_e32 v33, v30, v33
	v_sub_f32_e32 v30, v30, v34
	v_mul_f32_e32 v34, 0x3f317218, v26
	v_add_f32_e32 v33, v27, v33
	v_add_f32_e32 v27, v27, v30
	v_fma_f32 v30, v26, s66, -v34
	v_add_f32_e32 v35, v31, v33
	v_add_f32_e32 v36, v32, v27
	v_fmac_f32_e32 v30, 0xb102e308, v26
	v_sub_f32_e32 v26, v31, v35
	v_sub_f32_e32 v31, v32, v36
	v_rcp_f32_e32 v32, v36
	v_add_f32_e32 v37, v34, v30
	v_add_f32_e32 v27, v27, v31
	v_sub_f32_e32 v31, v37, v34
	v_sub_f32_e32 v30, v30, v31
	v_mul_f32_e32 v31, v35, v32
	v_add_f32_e32 v26, v33, v26
	v_mul_f32_e32 v33, v36, v31
	v_fma_f32 v34, v31, v36, -v33
	v_fmac_f32_e32 v34, v31, v27
	v_add_f32_e32 v38, v33, v34
	v_sub_f32_e32 v39, v35, v38
	v_sub_f32_e32 v33, v38, v33
	v_sub_f32_e32 v35, v35, v39
	v_sub_f32_e32 v33, v33, v34
	v_sub_f32_e32 v34, v35, v38
	v_add_f32_e32 v26, v26, v34
	v_add_f32_e32 v26, v33, v26
	v_add_f32_e32 v33, v39, v26
	v_mul_f32_e32 v34, v32, v33
	v_sub_f32_e32 v35, v39, v33
	v_mul_f32_e32 v38, v36, v34
	v_add_f32_e32 v26, v26, v35
	v_add_f32_e32 v35, v31, v34
	v_fma_f32 v36, v34, v36, -v38
	v_sub_f32_e32 v31, v35, v31
	v_fmac_f32_e32 v36, v34, v27
	v_sub_f32_e32 v27, v34, v31
	v_add_f32_e32 v31, v38, v36
	v_sub_f32_e32 v34, v31, v38
	v_sub_f32_e32 v38, v33, v31
	v_sub_f32_e32 v33, v33, v38
	v_sub_f32_e32 v31, v33, v31
	v_sub_f32_e32 v34, v34, v36
	v_add_f32_e32 v26, v26, v31
	v_add_f32_e32 v26, v34, v26
	v_add_f32_e32 v26, v38, v26
	v_mul_f32_e32 v26, v32, v26
	v_add_f32_e32 v26, v27, v26
	v_add_f32_e32 v27, v35, v26
	v_mul_f32_e32 v31, v27, v27
	v_fmamk_f32 v34, v31, 0x3e9b6dac, v75
	v_sub_f32_e32 v32, v27, v35
	v_ldexp_f32 v33, v27, 1
	v_mul_f32_e32 v27, v27, v31
	v_fmaak_f32 v31, v31, v34, 0x3f2aaada
	v_mul_f32_e32 v27, v27, v31
	v_add_f32_e32 v31, v33, v27
	v_sub_f32_e32 v26, v26, v32
	v_sub_f32_e32 v32, v31, v33
	v_ldexp_f32 v26, v26, 1
	v_sub_f32_e32 v27, v27, v32
	v_add_f32_e32 v26, v26, v27
	v_add_f32_e32 v27, v31, v26
	v_sub_f32_e32 v31, v27, v31
	v_add_f32_e32 v32, v37, v27
	v_sub_f32_e32 v26, v26, v31
	v_sub_f32_e32 v31, v32, v37
	v_sub_f32_e32 v33, v32, v31
	v_sub_f32_e32 v27, v27, v31
	v_add_f32_e32 v31, v30, v26
	v_sub_f32_e32 v33, v37, v33
	v_sub_f32_e32 v34, v31, v30
	v_add_f32_e32 v27, v27, v33
	v_sub_f32_e32 v33, v31, v34
	v_sub_f32_e32 v26, v26, v34
	v_sub_f32_e32 v30, v30, v33
	v_add_f32_e32 v27, v31, v27
	v_add_f32_e32 v26, v26, v30
	v_add_f32_e32 v30, v32, v27
	v_sub_f32_e32 v31, v30, v32
	v_sub_f32_e32 v27, v27, v31
	v_add_f32_e32 v26, v26, v27
	v_add_f32_e32 v26, v30, v26
	v_cmp_neq_f32_e32 vcc, s64, v29
	s_nop 1
	v_cndmask_b32_e32 v26, v76, v26, vcc
	v_cmp_lt_f32_e64 vcc, |v29|, s67
	s_nop 1
	v_cndmask_b32_e32 v26, v26, v29, vcc
	v_sub_f32_e32 v26, v28, v26
	global_store_dword v[18:19], v26, off offset:16
	s_branch .LBB0_25

.LBB0_658:
	ds_read_b128 v[138:141], v147
	ds_read_b128 v[186:189], v147 offset:1024
	ds_read_b128 v[190:193], v147 offset:2048
	ds_read_b128 v[194:197], v147 offset:3072
	s_add_u32 s46, s48, 0xfffc0080
	s_addc_u32 s47, s49, -1
	s_cmp_eq_u32 s39, 12
	s_cselect_b32 s57, s21, s47
	s_cselect_b32 s56, s22, s46
	s_cselect_b32 s51, s23, s37
	s_cselect_b32 s50, s35, s36
	v_lshl_add_u64 v[142:143], s[48:49], 0, v[130:131]
	s_add_i32 m0, s45, 0xc000
	ds_read_b128 v[198:201], v158
	ds_read_b128 v[202:205], v158 offset:1024
	ds_read_b128 v[206:209], v158 offset:2048
	ds_read_b128 v[210:213], v158 offset:3072
	ds_read_b128 v[214:217], v158 offset:4096
	ds_read_b128 v[218:221], v158 offset:5120
	ds_read_b128 v[222:225], v158 offset:6144
	ds_read_b128 v[226:229], v158 offset:7168
	global_load_lds_dwordx4 v[142:143], off
	v_lshl_add_u64 v[142:143], s[48:49], 0, v[132:133]
	s_add_i32 m0, s45, 0xe000
	s_nop 0
	global_load_lds_dwordx4 v[142:143], off
	s_waitcnt lgkmcnt(8)
	s_barrier
	s_waitcnt lgkmcnt(0)
	s_setprio 1
	s_waitcnt lgkmcnt(0)
	v_mfma_f32_16x16x32_bf16 v[126:129], v[138:141], v[198:201], v[126:129]
	v_mfma_f32_16x16x32_bf16 v[122:125], v[190:193], v[198:201], v[122:125]
	v_mfma_f32_16x16x32_bf16 v[110:113], v[138:141], v[206:209], v[110:113]
	v_mfma_f32_16x16x32_bf16 v[106:109], v[190:193], v[206:209], v[106:109]
	v_mfma_f32_16x16x32_bf16 v[94:97], v[138:141], v[214:217], v[94:97]
	v_mfma_f32_16x16x32_bf16 v[90:93], v[190:193], v[214:217], v[90:93]
	v_mfma_f32_16x16x32_bf16 v[78:81], v[138:141], v[222:225], v[78:81]
	v_mfma_f32_16x16x32_bf16 v[74:77], v[190:193], v[222:225], v[74:77]
	v_mfma_f32_16x16x32_bf16 v[126:129], v[186:189], v[202:205], v[126:129]
	v_mfma_f32_16x16x32_bf16 v[122:125], v[194:197], v[202:205], v[122:125]
	v_mfma_f32_16x16x32_bf16 v[110:113], v[186:189], v[210:213], v[110:113]
	v_mfma_f32_16x16x32_bf16 v[106:109], v[194:197], v[210:213], v[106:109]
	v_mfma_f32_16x16x32_bf16 v[94:97], v[186:189], v[218:221], v[94:97]
	v_mfma_f32_16x16x32_bf16 v[90:93], v[194:197], v[218:221], v[90:93]
	v_mfma_f32_16x16x32_bf16 v[78:81], v[186:189], v[226:229], v[78:81]
	v_mfma_f32_16x16x32_bf16 v[74:77], v[194:197], v[226:229], v[74:77]
	s_setprio 0
	s_barrier
	s_add_i32 s46, s67, s59
	v_lshl_add_u64 v[142:143], s[50:51], 0, v[152:153]
	s_mov_b32 m0, s46
	ds_read_b128 v[230:233], v159
	ds_read_b128 v[234:237], v159 offset:1024
	ds_read_b128 v[238:241], v159 offset:2048
	ds_read_b128 v[242:245], v159 offset:3072
	global_load_lds_dwordx4 v[142:143], off
	v_lshl_add_u64 v[168:169], s[50:51], 0, v[156:157]
	s_add_i32 m0, s46, 0x2000
	s_nop 0
	global_load_lds_dwordx4 v[168:169], off
	s_barrier
	s_waitcnt lgkmcnt(0)
	s_setprio 1
	s_waitcnt lgkmcnt(0)
	v_mfma_f32_16x16x32_bf16 v[118:121], v[230:233], v[198:201], v[118:121]
	v_mfma_f32_16x16x32_bf16 v[114:117], v[238:241], v[198:201], v[114:117]
	v_mfma_f32_16x16x32_bf16 v[102:105], v[230:233], v[206:209], v[102:105]
	v_mfma_f32_16x16x32_bf16 v[98:101], v[238:241], v[206:209], v[98:101]
	v_mfma_f32_16x16x32_bf16 v[86:89], v[230:233], v[214:217], v[86:89]
	v_mfma_f32_16x16x32_bf16 v[82:85], v[238:241], v[214:217], v[82:85]
	v_mfma_f32_16x16x32_bf16 v[70:73], v[230:233], v[222:225], v[70:73]
	v_mfma_f32_16x16x32_bf16 v[66:69], v[238:241], v[222:225], v[66:69]
	v_mfma_f32_16x16x32_bf16 v[118:121], v[234:237], v[202:205], v[118:121]
	v_mfma_f32_16x16x32_bf16 v[114:117], v[242:245], v[202:205], v[114:117]
	v_mfma_f32_16x16x32_bf16 v[102:105], v[234:237], v[210:213], v[102:105]
	v_mfma_f32_16x16x32_bf16 v[98:101], v[242:245], v[210:213], v[98:101]
	v_mfma_f32_16x16x32_bf16 v[86:89], v[234:237], v[218:221], v[86:89]
	v_mfma_f32_16x16x32_bf16 v[82:85], v[242:245], v[218:221], v[82:85]
	v_mfma_f32_16x16x32_bf16 v[70:73], v[234:237], v[226:229], v[70:73]
	v_mfma_f32_16x16x32_bf16 v[66:69], v[242:245], v[226:229], v[66:69]
	s_setprio 0
	s_mov_b32 m0, s45
	v_lshl_add_u64 v[246:247], s[56:57], 0, v[150:151]
	s_barrier
	ds_read_b128 v[198:201], v158 offset:16384
	ds_read_b128 v[202:205], v158 offset:17408
	ds_read_b128 v[206:209], v158 offset:18432
	ds_read_b128 v[210:213], v158 offset:19456
	ds_read_b128 v[214:217], v158 offset:20480
	ds_read_b128 v[218:221], v158 offset:21504
	ds_read_b128 v[222:225], v158 offset:22528
	ds_read_b128 v[226:229], v158 offset:23552
	global_load_lds_dwordx4 v[246:247], off
	v_lshl_add_u64 v[248:249], s[56:57], 0, v[154:155]
	s_mov_b32 m0, s60
	s_nop 0
	global_load_lds_dwordx4 v[248:249], off
	s_barrier
	s_waitcnt lgkmcnt(0)
	s_setprio 1
	s_waitcnt lgkmcnt(0)
	v_mfma_f32_16x16x32_bf16 v[62:65], v[138:141], v[198:201], v[62:65]
	v_mfma_f32_16x16x32_bf16 v[58:61], v[190:193], v[198:201], v[58:61]
	v_mfma_f32_16x16x32_bf16 v[50:53], v[138:141], v[206:209], v[50:53]
	v_mfma_f32_16x16x32_bf16 v[42:45], v[190:193], v[206:209], v[42:45]
	v_mfma_f32_16x16x32_bf16 v[34:37], v[138:141], v[214:217], v[34:37]
	v_mfma_f32_16x16x32_bf16 v[26:29], v[190:193], v[214:217], v[26:29]
	v_mfma_f32_16x16x32_bf16 v[18:21], v[138:141], v[222:225], v[18:21]
	v_mfma_f32_16x16x32_bf16 v[10:13], v[190:193], v[222:225], v[10:13]
	v_mfma_f32_16x16x32_bf16 v[62:65], v[186:189], v[202:205], v[62:65]
	v_mfma_f32_16x16x32_bf16 v[58:61], v[194:197], v[202:205], v[58:61]
	v_mfma_f32_16x16x32_bf16 v[50:53], v[186:189], v[210:213], v[50:53]
	v_mfma_f32_16x16x32_bf16 v[42:45], v[194:197], v[210:213], v[42:45]
	v_mfma_f32_16x16x32_bf16 v[34:37], v[186:189], v[218:221], v[34:37]
	v_mfma_f32_16x16x32_bf16 v[26:29], v[194:197], v[218:221], v[26:29]
	v_mfma_f32_16x16x32_bf16 v[18:21], v[186:189], v[226:229], v[18:21]
	v_mfma_f32_16x16x32_bf16 v[10:13], v[194:197], v[226:229], v[10:13]
	s_setprio 0
	s_barrier
	s_add_u32 s46, s50, 0x40000
	s_addc_u32 s47, s51, 0
	s_add_i32 s69, s68, s59
	v_lshl_add_u64 v[138:139], s[46:47], 0, v[152:153]
	s_mov_b32 m0, s69
	s_nop 0
	global_load_lds_dwordx4 v[138:139], off
	v_lshl_add_u64 v[138:139], s[46:47], 0, v[156:157]
	s_add_i32 m0, s69, 0x2000
	s_nop 0
	global_load_lds_dwordx4 v[138:139], off
	s_waitcnt vmcnt(6)
	s_barrier
	s_setprio 1
	v_mfma_f32_16x16x32_bf16 v[54:57], v[230:233], v[198:201], v[54:57]
	v_mfma_f32_16x16x32_bf16 v[46:49], v[238:241], v[198:201], v[46:49]
	v_mfma_f32_16x16x32_bf16 v[38:41], v[230:233], v[206:209], v[38:41]
	v_mfma_f32_16x16x32_bf16 v[30:33], v[238:241], v[206:209], v[30:33]
	v_mfma_f32_16x16x32_bf16 v[22:25], v[230:233], v[214:217], v[22:25]
	v_mfma_f32_16x16x32_bf16 v[14:17], v[238:241], v[214:217], v[14:17]
	v_mfma_f32_16x16x32_bf16 v[6:9], v[230:233], v[222:225], v[6:9]
	v_mfma_f32_16x16x32_bf16 v[2:5], v[238:241], v[222:225], v[2:5]
	v_mfma_f32_16x16x32_bf16 v[54:57], v[234:237], v[202:205], v[54:57]
	v_mfma_f32_16x16x32_bf16 v[46:49], v[242:245], v[202:205], v[46:49]
	v_mfma_f32_16x16x32_bf16 v[38:41], v[234:237], v[210:213], v[38:41]
	v_mfma_f32_16x16x32_bf16 v[30:33], v[242:245], v[210:213], v[30:33]
	v_mfma_f32_16x16x32_bf16 v[22:25], v[234:237], v[218:221], v[22:25]
	v_mfma_f32_16x16x32_bf16 v[14:17], v[242:245], v[218:221], v[14:17]
	v_mfma_f32_16x16x32_bf16 v[6:9], v[234:237], v[226:229], v[6:9]
	v_mfma_f32_16x16x32_bf16 v[2:5], v[242:245], v[226:229], v[2:5]
	s_setprio 0
	s_add_i32 s69, 0, 0x18000
	v_add_u32_e32 v185, s69, v145
	s_barrier
	ds_read_b128 v[138:141], v185
	ds_read_b128 v[186:189], v185 offset:1024
	ds_read_b128 v[190:193], v185 offset:2048
	ds_read_b128 v[194:197], v185 offset:3072
	s_add_u32 s46, s56, 0x40000
	s_addc_u32 s47, s57, 0
	s_mov_b32 m0, s61
	v_lshl_add_u64 v[230:231], s[46:47], 0, v[150:151]
	ds_read_b128 v[198:201], v158 offset:32768
	ds_read_b128 v[202:205], v158 offset:33792
	ds_read_b128 v[206:209], v158 offset:34816
	ds_read_b128 v[210:213], v158 offset:35840
	ds_read_b128 v[214:217], v158 offset:36864
	ds_read_b128 v[218:221], v158 offset:37888
	ds_read_b128 v[222:225], v158 offset:38912
	ds_read_b128 v[226:229], v158 offset:39936
	global_load_lds_dwordx4 v[230:231], off
	v_lshl_add_u64 v[230:231], s[46:47], 0, v[154:155]
	s_mov_b32 m0, s62
	s_nop 0
	global_load_lds_dwordx4 v[230:231], off
	s_waitcnt lgkmcnt(8)
	s_barrier
	s_waitcnt lgkmcnt(0)
	s_setprio 1
	s_waitcnt lgkmcnt(0)
	v_mfma_f32_16x16x32_bf16 v[126:129], v[138:141], v[198:201], v[126:129]
	v_mfma_f32_16x16x32_bf16 v[122:125], v[190:193], v[198:201], v[122:125]
	v_mfma_f32_16x16x32_bf16 v[110:113], v[138:141], v[206:209], v[110:113]
	v_mfma_f32_16x16x32_bf16 v[106:109], v[190:193], v[206:209], v[106:109]
	v_mfma_f32_16x16x32_bf16 v[94:97], v[138:141], v[214:217], v[94:97]
	v_mfma_f32_16x16x32_bf16 v[90:93], v[190:193], v[214:217], v[90:93]
	v_mfma_f32_16x16x32_bf16 v[78:81], v[138:141], v[222:225], v[78:81]
	v_mfma_f32_16x16x32_bf16 v[74:77], v[190:193], v[222:225], v[74:77]
	v_mfma_f32_16x16x32_bf16 v[126:129], v[186:189], v[202:205], v[126:129]
	v_mfma_f32_16x16x32_bf16 v[122:125], v[194:197], v[202:205], v[122:125]
	v_mfma_f32_16x16x32_bf16 v[110:113], v[186:189], v[210:213], v[110:113]
	v_mfma_f32_16x16x32_bf16 v[106:109], v[194:197], v[210:213], v[106:109]
	v_mfma_f32_16x16x32_bf16 v[94:97], v[186:189], v[218:221], v[94:97]
	v_mfma_f32_16x16x32_bf16 v[90:93], v[194:197], v[218:221], v[90:93]
	v_mfma_f32_16x16x32_bf16 v[78:81], v[186:189], v[226:229], v[78:81]
	v_mfma_f32_16x16x32_bf16 v[74:77], v[194:197], v[226:229], v[74:77]
	s_setprio 0
	s_barrier
	s_add_i32 s56, 0, 0x1c000
	s_add_i32 s46, s69, s59
	v_add_u32_e32 v185, s56, v145
	v_lshl_add_u64 v[142:143], v[142:143], 0, s[6:7]
	s_mov_b32 m0, s46
	ds_read_b128 v[230:233], v185
	ds_read_b128 v[234:237], v185 offset:1024
	ds_read_b128 v[238:241], v185 offset:2048
	ds_read_b128 v[242:245], v185 offset:3072
	global_load_lds_dwordx4 v[142:143], off
	v_lshl_add_u64 v[142:143], v[168:169], 0, s[6:7]
	s_add_i32 m0, s46, 0x2000
	s_nop 0
	global_load_lds_dwordx4 v[142:143], off
	s_barrier
	s_waitcnt lgkmcnt(0)
	s_setprio 1
	s_waitcnt lgkmcnt(0)
	v_mfma_f32_16x16x32_bf16 v[118:121], v[230:233], v[198:201], v[118:121]
	v_mfma_f32_16x16x32_bf16 v[114:117], v[238:241], v[198:201], v[114:117]
	v_mfma_f32_16x16x32_bf16 v[102:105], v[230:233], v[206:209], v[102:105]
	v_mfma_f32_16x16x32_bf16 v[98:101], v[238:241], v[206:209], v[98:101]
	v_mfma_f32_16x16x32_bf16 v[86:89], v[230:233], v[214:217], v[86:89]
	v_mfma_f32_16x16x32_bf16 v[82:85], v[238:241], v[214:217], v[82:85]
	v_mfma_f32_16x16x32_bf16 v[70:73], v[230:233], v[222:225], v[70:73]
	v_mfma_f32_16x16x32_bf16 v[66:69], v[238:241], v[222:225], v[66:69]
	v_mfma_f32_16x16x32_bf16 v[118:121], v[234:237], v[202:205], v[118:121]
	v_mfma_f32_16x16x32_bf16 v[114:117], v[242:245], v[202:205], v[114:117]
	v_mfma_f32_16x16x32_bf16 v[102:105], v[234:237], v[210:213], v[102:105]
	v_mfma_f32_16x16x32_bf16 v[98:101], v[242:245], v[210:213], v[98:101]
	v_mfma_f32_16x16x32_bf16 v[86:89], v[234:237], v[218:221], v[86:89]
	v_mfma_f32_16x16x32_bf16 v[82:85], v[242:245], v[218:221], v[82:85]
	v_mfma_f32_16x16x32_bf16 v[70:73], v[234:237], v[226:229], v[70:73]
	v_mfma_f32_16x16x32_bf16 v[66:69], v[242:245], v[226:229], v[66:69]
	s_setprio 0
	s_mov_b32 m0, s64
	v_lshl_add_u64 v[142:143], v[246:247], 0, s[6:7]
	s_barrier
	ds_read_b128 v[198:201], v158 offset:49152
	ds_read_b128 v[202:205], v158 offset:50176
	ds_read_b128 v[206:209], v158 offset:51200
	ds_read_b128 v[210:213], v158 offset:52224
	ds_read_b128 v[214:217], v158 offset:53248
	ds_read_b128 v[218:221], v158 offset:54272
	ds_read_b128 v[222:225], v158 offset:55296
	ds_read_b128 v[226:229], v158 offset:56320
	global_load_lds_dwordx4 v[142:143], off
	v_lshl_add_u64 v[142:143], v[248:249], 0, s[6:7]
	s_mov_b32 m0, s65
	s_nop 0
	global_load_lds_dwordx4 v[142:143], off
	s_barrier
	s_waitcnt lgkmcnt(0)
	s_setprio 1
	s_waitcnt lgkmcnt(0)
	v_mfma_f32_16x16x32_bf16 v[62:65], v[138:141], v[198:201], v[62:65]
	v_mfma_f32_16x16x32_bf16 v[58:61], v[190:193], v[198:201], v[58:61]
	v_mfma_f32_16x16x32_bf16 v[50:53], v[138:141], v[206:209], v[50:53]
	v_mfma_f32_16x16x32_bf16 v[42:45], v[190:193], v[206:209], v[42:45]
	v_mfma_f32_16x16x32_bf16 v[34:37], v[138:141], v[214:217], v[34:37]
	v_mfma_f32_16x16x32_bf16 v[26:29], v[190:193], v[214:217], v[26:29]
	v_mfma_f32_16x16x32_bf16 v[18:21], v[138:141], v[222:225], v[18:21]
	v_mfma_f32_16x16x32_bf16 v[10:13], v[190:193], v[222:225], v[10:13]
	v_mfma_f32_16x16x32_bf16 v[62:65], v[186:189], v[202:205], v[62:65]
	v_mfma_f32_16x16x32_bf16 v[58:61], v[194:197], v[202:205], v[58:61]
	v_mfma_f32_16x16x32_bf16 v[50:53], v[186:189], v[210:213], v[50:53]
	v_mfma_f32_16x16x32_bf16 v[42:45], v[194:197], v[210:213], v[42:45]
	v_mfma_f32_16x16x32_bf16 v[34:37], v[186:189], v[218:221], v[34:37]
	v_mfma_f32_16x16x32_bf16 v[26:29], v[194:197], v[218:221], v[26:29]
	v_mfma_f32_16x16x32_bf16 v[18:21], v[186:189], v[226:229], v[18:21]
	v_mfma_f32_16x16x32_bf16 v[10:13], v[194:197], v[226:229], v[10:13]
	s_setprio 0
	s_barrier
	s_add_u32 s46, s50, 0x40080
	s_addc_u32 s47, s51, 0
	s_add_i32 s50, s56, s59
	v_lshl_add_u64 v[138:139], s[46:47], 0, v[152:153]
	s_mov_b32 m0, s50
	s_nop 0
	global_load_lds_dwordx4 v[138:139], off
	v_lshl_add_u64 v[138:139], s[46:47], 0, v[156:157]
	s_add_i32 m0, s50, 0x2000
	s_nop 0
	global_load_lds_dwordx4 v[138:139], off
	s_waitcnt vmcnt(6)
	s_barrier
	s_setprio 1
	v_mfma_f32_16x16x32_bf16 v[54:57], v[230:233], v[198:201], v[54:57]
	v_mfma_f32_16x16x32_bf16 v[46:49], v[238:241], v[198:201], v[46:49]
	v_mfma_f32_16x16x32_bf16 v[38:41], v[230:233], v[206:209], v[38:41]
	v_mfma_f32_16x16x32_bf16 v[30:33], v[238:241], v[206:209], v[30:33]
	v_mfma_f32_16x16x32_bf16 v[22:25], v[230:233], v[214:217], v[22:25]
	v_mfma_f32_16x16x32_bf16 v[14:17], v[238:241], v[214:217], v[14:17]
	v_mfma_f32_16x16x32_bf16 v[6:9], v[230:233], v[222:225], v[6:9]
	v_mfma_f32_16x16x32_bf16 v[2:5], v[238:241], v[222:225], v[2:5]
	v_mfma_f32_16x16x32_bf16 v[54:57], v[234:237], v[202:205], v[54:57]
	v_mfma_f32_16x16x32_bf16 v[46:49], v[242:245], v[202:205], v[46:49]
	v_mfma_f32_16x16x32_bf16 v[38:41], v[234:237], v[210:213], v[38:41]
	v_mfma_f32_16x16x32_bf16 v[30:33], v[242:245], v[210:213], v[30:33]
	v_mfma_f32_16x16x32_bf16 v[22:25], v[234:237], v[218:221], v[22:25]
	v_mfma_f32_16x16x32_bf16 v[14:17], v[242:245], v[218:221], v[14:17]
	v_mfma_f32_16x16x32_bf16 v[6:9], v[234:237], v[226:229], v[6:9]
	v_mfma_f32_16x16x32_bf16 v[2:5], v[242:245], v[226:229], v[2:5]
	s_setprio 0
	s_add_i32 s39, s39, 2
	s_add_u32 s48, s48, 0x100
	s_addc_u32 s49, s49, 0
	s_add_u32 s36, s36, 0x100
	s_addc_u32 s37, s37, 0
	s_cmp_gt_u32 s39, 13
	s_barrier
	s_cbranch_scc0 .LBB0_658
	v_lshl_add_u32 v142, s44, 8, v144
	v_lshl_or_b32 v140, s20, 8, v146
	v_ashrrev_i32_e32 v143, 31, v142
	v_ashrrev_i32_e32 v141, 31, v140
	v_lshlrev_b64 v[138:139], 10, v[142:143]
	v_lshl_add_u64 v[138:139], v[138:139], 0, v[140:141]
	v_lshlrev_b64 v[138:139], 1, v[138:139]
	s_and_b64 vcc, exec, s[2:3]
	s_mov_b32 s20, s34
	s_mov_b32 s44, s38
	s_mov_b64 s[50:51], s[42:43]
	s_mov_b64 s[48:49], s[40:41]
	v_mov_b32_e32 v192, v138
	v_add_u32_e32 v193, 0x8000, v138
	v_add_u32_e32 v194, 0x10000, v138
	v_add_u32_e32 v195, 0x18000, v138
	v_add_u32_e32 v196, 0x40000, v138
	v_add_u32_e32 v197, 0x48000, v138
	v_add_u32_e32 v198, 0x50000, v138
	v_add_u32_e32 v199, 0x58000, v138
	global_load_dwordx4 v[200:203], v192, s[4:5]
	global_load_dwordx4 v[204:207], v192, s[4:5] offset:256
	global_load_dwordx4 v[208:211], v193, s[4:5]
	global_load_dwordx4 v[212:215], v193, s[4:5] offset:256
	global_load_dwordx4 v[216:219], v194, s[4:5]
	global_load_dwordx4 v[220:223], v194, s[4:5] offset:256
	global_load_dwordx4 v[224:227], v195, s[4:5]
	global_load_dwordx4 v[228:231], v195, s[4:5] offset:256
	s_waitcnt vmcnt(7)
	v_lshlrev_b32_e32 v143, 16, v200
	v_and_b32_e32 v185, 0xffff0000, v200
	v_lshlrev_b32_e32 v200, 16, v201
	v_and_b32_e32 v201, 0xffff0000, v201
	v_lshlrev_b32_e32 v191, 16, v203
	v_and_b32_e32 v203, 0xffff0000, v203
	v_lshlrev_b32_e32 v190, 16, v202
	v_and_b32_e32 v202, 0xffff0000, v202
	v_mul_f32_e32 v126, v126, v143
	v_mul_f32_e32 v127, v127, v185
	v_mul_f32_e32 v128, v128, v200
	v_mul_f32_e32 v129, v129, v201
	v_mul_f32_e32 v125, v125, v203
	v_mul_f32_e32 v143, v122, v190
	v_mul_f32_e32 v185, v123, v202
	v_mul_f32_e32 v200, v124, v191
	v_cvt_pk_bf16_f32 v122, v126, v127
	v_cvt_pk_bf16_f32 v123, v128, v129
	v_cvt_pk_bf16_f32 v124, v143, v185
	v_cvt_pk_bf16_f32 v125, v200, v125
	global_store_dwordx4 v192, v[122:125], s[18:19]
	s_nop 1
	global_load_dwordx4 v[200:203], v196, s[4:5]
	s_waitcnt vmcnt(8)
	v_lshlrev_b32_e32 v122, 16, v204
	v_and_b32_e32 v123, 0xffff0000, v204
	v_lshlrev_b32_e32 v124, 16, v205
	v_and_b32_e32 v125, 0xffff0000, v205
	v_lshlrev_b32_e32 v204, 16, v206
	v_and_b32_e32 v205, 0xffff0000, v206
	v_lshlrev_b32_e32 v206, 16, v207
	v_and_b32_e32 v207, 0xffff0000, v207
	v_mul_f32_e32 v117, v117, v207
	v_mul_f32_e32 v118, v118, v122
	v_mul_f32_e32 v119, v119, v123
	v_mul_f32_e32 v120, v120, v124
	v_mul_f32_e32 v121, v121, v125
	v_mul_f32_e32 v122, v114, v204
	v_mul_f32_e32 v123, v115, v205
	v_mul_f32_e32 v124, v116, v206
	v_cvt_pk_bf16_f32 v114, v118, v119
	v_cvt_pk_bf16_f32 v115, v120, v121
	v_cvt_pk_bf16_f32 v116, v122, v123
	v_cvt_pk_bf16_f32 v117, v124, v117
	global_store_dwordx4 v192, v[114:117], s[18:19] offset:256
	s_nop 1
	global_load_dwordx4 v[204:207], v196, s[4:5] offset:256
	s_waitcnt vmcnt(9)
	v_lshlrev_b32_e32 v118, 16, v208
	v_and_b32_e32 v208, 0xffff0000, v208
	v_lshlrev_b32_e32 v119, 16, v209
	v_and_b32_e32 v209, 0xffff0000, v209
	v_lshlrev_b32_e32 v121, 16, v211
	v_and_b32_e32 v211, 0xffff0000, v211
	v_lshlrev_b32_e32 v120, 16, v210
	v_and_b32_e32 v210, 0xffff0000, v210
	v_mul_f32_e32 v110, v110, v118
	v_mul_f32_e32 v111, v111, v208
	v_mul_f32_e32 v112, v112, v119
	v_mul_f32_e32 v113, v113, v209
	v_mul_f32_e32 v109, v109, v211
	v_mul_f32_e32 v208, v106, v120
	v_mul_f32_e32 v209, v107, v210
	v_mul_f32_e32 v210, v108, v121
	v_cvt_pk_bf16_f32 v106, v110, v111
	v_cvt_pk_bf16_f32 v107, v112, v113
	v_cvt_pk_bf16_f32 v108, v208, v209
	v_cvt_pk_bf16_f32 v109, v210, v109
	global_store_dwordx4 v193, v[106:109], s[18:19]
	s_nop 1
	global_load_dwordx4 v[208:211], v197, s[4:5]
	s_waitcnt vmcnt(10)
	v_lshlrev_b32_e32 v106, 16, v212
	v_and_b32_e32 v107, 0xffff0000, v212
	v_lshlrev_b32_e32 v108, 16, v213
	v_and_b32_e32 v109, 0xffff0000, v213
	v_lshlrev_b32_e32 v212, 16, v214
	v_and_b32_e32 v213, 0xffff0000, v214
	v_lshlrev_b32_e32 v214, 16, v215
	v_and_b32_e32 v215, 0xffff0000, v215
	v_mul_f32_e32 v101, v101, v215
	v_mul_f32_e32 v102, v102, v106
	v_mul_f32_e32 v103, v103, v107
	v_mul_f32_e32 v104, v104, v108
	v_mul_f32_e32 v105, v105, v109
	v_mul_f32_e32 v106, v98, v212
	v_mul_f32_e32 v107, v99, v213
	v_mul_f32_e32 v108, v100, v214
	v_cvt_pk_bf16_f32 v98, v102, v103
	v_cvt_pk_bf16_f32 v99, v104, v105
	v_cvt_pk_bf16_f32 v100, v106, v107
	v_cvt_pk_bf16_f32 v101, v108, v101
	global_store_dwordx4 v193, v[98:101], s[18:19] offset:256
	s_nop 1
	global_load_dwordx4 v[212:215], v197, s[4:5] offset:256
	s_waitcnt vmcnt(11)
	v_lshlrev_b32_e32 v102, 16, v216
	v_and_b32_e32 v216, 0xffff0000, v216
	v_lshlrev_b32_e32 v103, 16, v217
	v_and_b32_e32 v217, 0xffff0000, v217
	v_lshlrev_b32_e32 v105, 16, v219
	v_and_b32_e32 v219, 0xffff0000, v219
	v_lshlrev_b32_e32 v104, 16, v218
	v_and_b32_e32 v218, 0xffff0000, v218
	v_mul_f32_e32 v94, v94, v102
	v_mul_f32_e32 v95, v95, v216
	v_mul_f32_e32 v96, v96, v103
	v_mul_f32_e32 v97, v97, v217
	v_mul_f32_e32 v93, v93, v219
	v_mul_f32_e32 v216, v90, v104
	v_mul_f32_e32 v217, v91, v218
	v_mul_f32_e32 v218, v92, v105
	v_cvt_pk_bf16_f32 v90, v94, v95
	v_cvt_pk_bf16_f32 v91, v96, v97
	v_cvt_pk_bf16_f32 v92, v216, v217
	v_cvt_pk_bf16_f32 v93, v218, v93
	global_store_dwordx4 v194, v[90:93], s[18:19]
	s_nop 1
	global_load_dwordx4 v[216:219], v198, s[4:5]
	s_waitcnt vmcnt(12)
	v_lshlrev_b32_e32 v90, 16, v220
	v_and_b32_e32 v91, 0xffff0000, v220
	v_lshlrev_b32_e32 v92, 16, v221
	v_and_b32_e32 v93, 0xffff0000, v221
	v_lshlrev_b32_e32 v220, 16, v222
	v_and_b32_e32 v221, 0xffff0000, v222
	v_lshlrev_b32_e32 v222, 16, v223
	v_and_b32_e32 v223, 0xffff0000, v223
	v_mul_f32_e32 v85, v85, v223
	v_mul_f32_e32 v86, v86, v90
	v_mul_f32_e32 v87, v87, v91
	v_mul_f32_e32 v88, v88, v92
	v_mul_f32_e32 v89, v89, v93
	v_mul_f32_e32 v90, v82, v220
	v_mul_f32_e32 v91, v83, v221
	v_mul_f32_e32 v92, v84, v222
	v_cvt_pk_bf16_f32 v82, v86, v87
	v_cvt_pk_bf16_f32 v83, v88, v89
	v_cvt_pk_bf16_f32 v84, v90, v91
	v_cvt_pk_bf16_f32 v85, v92, v85
	global_store_dwordx4 v194, v[82:85], s[18:19] offset:256
	s_nop 1
	global_load_dwordx4 v[220:223], v198, s[4:5] offset:256
	s_waitcnt vmcnt(13)
	v_lshlrev_b32_e32 v86, 16, v224
	v_and_b32_e32 v224, 0xffff0000, v224
	v_lshlrev_b32_e32 v87, 16, v225
	v_and_b32_e32 v225, 0xffff0000, v225
	v_lshlrev_b32_e32 v89, 16, v227
	v_and_b32_e32 v227, 0xffff0000, v227
	v_lshlrev_b32_e32 v88, 16, v226
	v_and_b32_e32 v226, 0xffff0000, v226
	v_mul_f32_e32 v78, v78, v86
	v_mul_f32_e32 v79, v79, v224
	v_mul_f32_e32 v80, v80, v87
	v_mul_f32_e32 v81, v81, v225
	v_mul_f32_e32 v77, v77, v227
	v_mul_f32_e32 v224, v74, v88
	v_mul_f32_e32 v225, v75, v226
	v_mul_f32_e32 v226, v76, v89
	v_cvt_pk_bf16_f32 v74, v78, v79
	v_cvt_pk_bf16_f32 v75, v80, v81
	v_cvt_pk_bf16_f32 v76, v224, v225
	v_cvt_pk_bf16_f32 v77, v226, v77
	global_store_dwordx4 v195, v[74:77], s[18:19]
	s_nop 1
	global_load_dwordx4 v[224:227], v199, s[4:5]
	s_waitcnt vmcnt(14)
	v_lshlrev_b32_e32 v74, 16, v228
	v_and_b32_e32 v75, 0xffff0000, v228
	v_lshlrev_b32_e32 v76, 16, v229
	v_and_b32_e32 v77, 0xffff0000, v229
	v_lshlrev_b32_e32 v228, 16, v230
	v_and_b32_e32 v229, 0xffff0000, v230
	v_lshlrev_b32_e32 v230, 16, v231
	v_and_b32_e32 v231, 0xffff0000, v231
	v_mul_f32_e32 v69, v69, v231
	v_mul_f32_e32 v70, v70, v74
	v_mul_f32_e32 v71, v71, v75
	v_mul_f32_e32 v72, v72, v76
	v_mul_f32_e32 v73, v73, v77
	v_mul_f32_e32 v74, v66, v228
	v_mul_f32_e32 v75, v67, v229
	v_mul_f32_e32 v76, v68, v230
	v_cvt_pk_bf16_f32 v66, v70, v71
	v_cvt_pk_bf16_f32 v67, v72, v73
	v_cvt_pk_bf16_f32 v68, v74, v75
	v_cvt_pk_bf16_f32 v69, v76, v69
	global_store_dwordx4 v195, v[66:69], s[18:19] offset:256
	s_nop 1
	global_load_dwordx4 v[228:231], v199, s[4:5] offset:256
	s_waitcnt vmcnt(14)
	v_lshlrev_b32_e32 v70, 16, v200
	v_and_b32_e32 v200, 0xffff0000, v200
	v_lshlrev_b32_e32 v71, 16, v201
	v_and_b32_e32 v201, 0xffff0000, v201
	v_lshlrev_b32_e32 v73, 16, v203
	v_and_b32_e32 v203, 0xffff0000, v203
	v_lshlrev_b32_e32 v72, 16, v202
	v_and_b32_e32 v202, 0xffff0000, v202
	v_mul_f32_e32 v62, v62, v70
	v_mul_f32_e32 v63, v63, v200
	v_mul_f32_e32 v64, v64, v71
	v_mul_f32_e32 v65, v65, v201
	v_mul_f32_e32 v61, v61, v203
	v_mul_f32_e32 v200, v58, v72
	v_mul_f32_e32 v201, v59, v202
	v_mul_f32_e32 v202, v60, v73
	v_cvt_pk_bf16_f32 v58, v62, v63
	v_cvt_pk_bf16_f32 v59, v64, v65
	v_cvt_pk_bf16_f32 v60, v200, v201
	v_cvt_pk_bf16_f32 v61, v202, v61
	global_store_dwordx4 v196, v[58:61], s[18:19]
	s_nop 1
	s_waitcnt vmcnt(13)
	v_lshlrev_b32_e32 v58, 16, v204
	v_and_b32_e32 v59, 0xffff0000, v204
	v_lshlrev_b32_e32 v60, 16, v205
	v_and_b32_e32 v61, 0xffff0000, v205
	v_lshlrev_b32_e32 v204, 16, v206
	v_and_b32_e32 v205, 0xffff0000, v206
	v_lshlrev_b32_e32 v206, 16, v207
	v_and_b32_e32 v207, 0xffff0000, v207
	v_mul_f32_e32 v49, v49, v207
	v_mul_f32_e32 v54, v54, v58
	v_mul_f32_e32 v55, v55, v59
	v_mul_f32_e32 v56, v56, v60
	v_mul_f32_e32 v57, v57, v61
	v_mul_f32_e32 v58, v46, v204
	v_mul_f32_e32 v59, v47, v205
	v_mul_f32_e32 v60, v48, v206
	v_cvt_pk_bf16_f32 v46, v54, v55
	v_cvt_pk_bf16_f32 v47, v56, v57
	v_cvt_pk_bf16_f32 v48, v58, v59
	v_cvt_pk_bf16_f32 v49, v60, v49
	global_store_dwordx4 v196, v[46:49], s[18:19] offset:256
	s_nop 1
	s_waitcnt vmcnt(12)
	v_lshlrev_b32_e32 v54, 16, v208
	v_and_b32_e32 v208, 0xffff0000, v208
	v_lshlrev_b32_e32 v55, 16, v209
	v_and_b32_e32 v209, 0xffff0000, v209
	v_lshlrev_b32_e32 v56, 16, v210
	v_and_b32_e32 v210, 0xffff0000, v210
	v_lshlrev_b32_e32 v57, 16, v211
	v_and_b32_e32 v211, 0xffff0000, v211
	v_mul_f32_e32 v208, v51, v208
	v_mul_f32_e32 v209, v53, v209
	v_mul_f32_e32 v210, v43, v210
	v_mul_f32_e32 v45, v45, v211
	v_mul_f32_e32 v50, v50, v54
	v_mul_f32_e32 v51, v52, v55
	v_mul_f32_e32 v52, v42, v56
	v_mul_f32_e32 v53, v44, v57
	v_cvt_pk_bf16_f32 v42, v50, v208
	v_cvt_pk_bf16_f32 v43, v51, v209
	v_cvt_pk_bf16_f32 v44, v52, v210
	v_cvt_pk_bf16_f32 v45, v53, v45
	global_store_dwordx4 v197, v[42:45], s[18:19]
	s_nop 1
	s_waitcnt vmcnt(11)
	v_lshlrev_b32_e32 v42, 16, v212
	v_and_b32_e32 v43, 0xffff0000, v212
	v_lshlrev_b32_e32 v44, 16, v213
	v_and_b32_e32 v45, 0xffff0000, v213
	v_lshlrev_b32_e32 v212, 16, v214
	v_and_b32_e32 v213, 0xffff0000, v214
	v_lshlrev_b32_e32 v214, 16, v215
	v_and_b32_e32 v215, 0xffff0000, v215
	v_mul_f32_e32 v33, v33, v215
	v_mul_f32_e32 v38, v38, v42
	v_mul_f32_e32 v39, v39, v43
	v_mul_f32_e32 v40, v40, v44
	v_mul_f32_e32 v41, v41, v45
	v_mul_f32_e32 v42, v30, v212
	v_mul_f32_e32 v43, v31, v213
	v_mul_f32_e32 v44, v32, v214
	v_cvt_pk_bf16_f32 v30, v38, v39
	v_cvt_pk_bf16_f32 v31, v40, v41
	v_cvt_pk_bf16_f32 v32, v42, v43
	v_cvt_pk_bf16_f32 v33, v44, v33
	global_store_dwordx4 v197, v[30:33], s[18:19] offset:256
	s_nop 1
	s_waitcnt vmcnt(10)
	v_lshlrev_b32_e32 v38, 16, v216
	v_and_b32_e32 v216, 0xffff0000, v216
	v_lshlrev_b32_e32 v39, 16, v217
	v_and_b32_e32 v217, 0xffff0000, v217
	v_lshlrev_b32_e32 v40, 16, v218
	v_and_b32_e32 v218, 0xffff0000, v218
	v_lshlrev_b32_e32 v41, 16, v219
	v_and_b32_e32 v219, 0xffff0000, v219
	v_mul_f32_e32 v216, v35, v216
	v_mul_f32_e32 v217, v37, v217
	v_mul_f32_e32 v218, v27, v218
	v_mul_f32_e32 v29, v29, v219
	v_mul_f32_e32 v34, v34, v38
	v_mul_f32_e32 v35, v36, v39
	v_mul_f32_e32 v36, v26, v40
	v_mul_f32_e32 v37, v28, v41
	v_cvt_pk_bf16_f32 v26, v34, v216
	v_cvt_pk_bf16_f32 v27, v35, v217
	v_cvt_pk_bf16_f32 v28, v36, v218
	v_cvt_pk_bf16_f32 v29, v37, v29
	global_store_dwordx4 v198, v[26:29], s[18:19]
	s_nop 1
	s_waitcnt vmcnt(9)
	v_lshlrev_b32_e32 v26, 16, v220
	v_and_b32_e32 v27, 0xffff0000, v220
	v_lshlrev_b32_e32 v28, 16, v221
	v_and_b32_e32 v29, 0xffff0000, v221
	v_lshlrev_b32_e32 v220, 16, v222
	v_and_b32_e32 v221, 0xffff0000, v222
	v_lshlrev_b32_e32 v222, 16, v223
	v_and_b32_e32 v223, 0xffff0000, v223
	v_mul_f32_e32 v17, v17, v223
	v_mul_f32_e32 v22, v22, v26
	v_mul_f32_e32 v23, v23, v27
	v_mul_f32_e32 v24, v24, v28
	v_mul_f32_e32 v25, v25, v29
	v_mul_f32_e32 v26, v14, v220
	v_mul_f32_e32 v27, v15, v221
	v_mul_f32_e32 v28, v16, v222
	v_cvt_pk_bf16_f32 v14, v22, v23
	v_cvt_pk_bf16_f32 v15, v24, v25
	v_cvt_pk_bf16_f32 v16, v26, v27
	v_cvt_pk_bf16_f32 v17, v28, v17
	global_store_dwordx4 v198, v[14:17], s[18:19] offset:256
	s_nop 1
	s_waitcnt vmcnt(8)
	v_lshlrev_b32_e32 v22, 16, v224
	v_and_b32_e32 v224, 0xffff0000, v224
	v_lshlrev_b32_e32 v23, 16, v225
	v_and_b32_e32 v225, 0xffff0000, v225
	v_lshlrev_b32_e32 v24, 16, v226
	v_and_b32_e32 v226, 0xffff0000, v226
	v_lshlrev_b32_e32 v25, 16, v227
	v_and_b32_e32 v227, 0xffff0000, v227
	v_mul_f32_e32 v224, v19, v224
	v_mul_f32_e32 v225, v21, v225
	v_mul_f32_e32 v226, v11, v226
	v_mul_f32_e32 v13, v13, v227
	v_mul_f32_e32 v18, v18, v22
	v_mul_f32_e32 v19, v20, v23
	v_mul_f32_e32 v20, v10, v24
	v_mul_f32_e32 v21, v12, v25
	v_cvt_pk_bf16_f32 v10, v18, v224
	v_cvt_pk_bf16_f32 v11, v19, v225
	v_cvt_pk_bf16_f32 v12, v20, v226
	v_cvt_pk_bf16_f32 v13, v21, v13
	global_store_dwordx4 v199, v[10:13], s[18:19]
	s_nop 1
	s_waitcnt vmcnt(7)
	v_lshlrev_b32_e32 v10, 16, v228
	v_and_b32_e32 v11, 0xffff0000, v228
	v_lshlrev_b32_e32 v12, 16, v229
	v_and_b32_e32 v13, 0xffff0000, v229
	v_lshlrev_b32_e32 v228, 16, v230
	v_and_b32_e32 v229, 0xffff0000, v230
	v_lshlrev_b32_e32 v230, 16, v231
	v_and_b32_e32 v231, 0xffff0000, v231
	v_mul_f32_e32 v5, v5, v231
	v_mul_f32_e32 v6, v6, v10
	v_mul_f32_e32 v7, v7, v11
	v_mul_f32_e32 v8, v8, v12
	v_mul_f32_e32 v9, v9, v13
	v_mul_f32_e32 v10, v2, v228
	v_mul_f32_e32 v11, v3, v229
	v_mul_f32_e32 v12, v4, v230
	v_cvt_pk_bf16_f32 v2, v6, v7
	v_cvt_pk_bf16_f32 v3, v8, v9
	v_cvt_pk_bf16_f32 v4, v10, v11
	v_cvt_pk_bf16_f32 v5, v12, v5
	global_store_dwordx4 v199, v[2:5], s[18:19] offset:256
	s_nop 1
	s_cbranch_vccz .LBB0_651
	s_waitcnt vmcnt(0)
	s_cmpk_gt_u32 s25, 0xff
	s_cbranch_scc1 .LBB0_662
	s_barrier

.LBB0_690:
	ds_read_b128 v[138:141], v147
	ds_read_b128 v[186:189], v147 offset:1024
	ds_read_b128 v[190:193], v147 offset:2048
	ds_read_b128 v[194:197], v147 offset:3072
	s_add_u32 s48, s44, 0xfffc0080
	s_addc_u32 s49, s45, -1
	s_cmp_eq_u32 s47, 12
	s_cselect_b32 s51, s21, s49
	s_cselect_b32 s50, s22, s48
	s_cselect_b32 s49, s23, s46
	s_cselect_b32 s48, s35, s37
	v_lshl_add_u64 v[142:143], s[44:45], 0, v[130:131]
	s_add_i32 m0, s43, 0xc000
	ds_read_b128 v[198:201], v158
	ds_read_b128 v[202:205], v158 offset:1024
	ds_read_b128 v[206:209], v158 offset:2048
	ds_read_b128 v[210:213], v158 offset:3072
	ds_read_b128 v[214:217], v158 offset:4096
	ds_read_b128 v[218:221], v158 offset:5120
	ds_read_b128 v[222:225], v158 offset:6144
	ds_read_b128 v[226:229], v158 offset:7168
	global_load_lds_dwordx4 v[142:143], off
	v_lshl_add_u64 v[142:143], s[44:45], 0, v[132:133]
	s_add_i32 m0, s43, 0xe000
	s_nop 0
	global_load_lds_dwordx4 v[142:143], off
	s_waitcnt lgkmcnt(8)
	s_barrier
	s_waitcnt lgkmcnt(0)
	s_setprio 1
	s_waitcnt lgkmcnt(0)
	v_mfma_f32_16x16x32_bf16 v[126:129], v[138:141], v[198:201], v[126:129]
	v_mfma_f32_16x16x32_bf16 v[122:125], v[190:193], v[198:201], v[122:125]
	v_mfma_f32_16x16x32_bf16 v[110:113], v[138:141], v[206:209], v[110:113]
	v_mfma_f32_16x16x32_bf16 v[106:109], v[190:193], v[206:209], v[106:109]
	v_mfma_f32_16x16x32_bf16 v[94:97], v[138:141], v[214:217], v[94:97]
	v_mfma_f32_16x16x32_bf16 v[90:93], v[190:193], v[214:217], v[90:93]
	v_mfma_f32_16x16x32_bf16 v[78:81], v[138:141], v[222:225], v[78:81]
	v_mfma_f32_16x16x32_bf16 v[74:77], v[190:193], v[222:225], v[74:77]
	v_mfma_f32_16x16x32_bf16 v[126:129], v[186:189], v[202:205], v[126:129]
	v_mfma_f32_16x16x32_bf16 v[122:125], v[194:197], v[202:205], v[122:125]
	v_mfma_f32_16x16x32_bf16 v[110:113], v[186:189], v[210:213], v[110:113]
	v_mfma_f32_16x16x32_bf16 v[106:109], v[194:197], v[210:213], v[106:109]
	v_mfma_f32_16x16x32_bf16 v[94:97], v[186:189], v[218:221], v[94:97]
	v_mfma_f32_16x16x32_bf16 v[90:93], v[194:197], v[218:221], v[90:93]
	v_mfma_f32_16x16x32_bf16 v[78:81], v[186:189], v[226:229], v[78:81]
	v_mfma_f32_16x16x32_bf16 v[74:77], v[194:197], v[226:229], v[74:77]
	s_setprio 0
	s_barrier
	s_add_i32 s67, s65, s57
	v_lshl_add_u64 v[142:143], s[48:49], 0, v[152:153]
	s_mov_b32 m0, s67
	ds_read_b128 v[230:233], v159
	ds_read_b128 v[234:237], v159 offset:1024
	ds_read_b128 v[238:241], v159 offset:2048
	ds_read_b128 v[242:245], v159 offset:3072
	global_load_lds_dwordx4 v[142:143], off
	v_lshl_add_u64 v[168:169], s[48:49], 0, v[156:157]
	s_add_i32 m0, s67, 0x2000
	s_nop 0
	global_load_lds_dwordx4 v[168:169], off
	s_barrier
	s_waitcnt lgkmcnt(0)
	s_setprio 1
	s_waitcnt lgkmcnt(0)
	v_mfma_f32_16x16x32_bf16 v[118:121], v[230:233], v[198:201], v[118:121]
	v_mfma_f32_16x16x32_bf16 v[114:117], v[238:241], v[198:201], v[114:117]
	v_mfma_f32_16x16x32_bf16 v[102:105], v[230:233], v[206:209], v[102:105]
	v_mfma_f32_16x16x32_bf16 v[98:101], v[238:241], v[206:209], v[98:101]
	v_mfma_f32_16x16x32_bf16 v[86:89], v[230:233], v[214:217], v[86:89]
	v_mfma_f32_16x16x32_bf16 v[82:85], v[238:241], v[214:217], v[82:85]
	v_mfma_f32_16x16x32_bf16 v[70:73], v[230:233], v[222:225], v[70:73]
	v_mfma_f32_16x16x32_bf16 v[66:69], v[238:241], v[222:225], v[66:69]
	v_mfma_f32_16x16x32_bf16 v[118:121], v[234:237], v[202:205], v[118:121]
	v_mfma_f32_16x16x32_bf16 v[114:117], v[242:245], v[202:205], v[114:117]
	v_mfma_f32_16x16x32_bf16 v[102:105], v[234:237], v[210:213], v[102:105]
	v_mfma_f32_16x16x32_bf16 v[98:101], v[242:245], v[210:213], v[98:101]
	v_mfma_f32_16x16x32_bf16 v[86:89], v[234:237], v[218:221], v[86:89]
	v_mfma_f32_16x16x32_bf16 v[82:85], v[242:245], v[218:221], v[82:85]
	v_mfma_f32_16x16x32_bf16 v[70:73], v[234:237], v[226:229], v[70:73]
	v_mfma_f32_16x16x32_bf16 v[66:69], v[242:245], v[226:229], v[66:69]
	s_setprio 0
	s_mov_b32 m0, s43
	v_lshl_add_u64 v[246:247], s[50:51], 0, v[150:151]
	s_barrier
	ds_read_b128 v[198:201], v158 offset:16384
	ds_read_b128 v[202:205], v158 offset:17408
	ds_read_b128 v[206:209], v158 offset:18432
	ds_read_b128 v[210:213], v158 offset:19456
	ds_read_b128 v[214:217], v158 offset:20480
	ds_read_b128 v[218:221], v158 offset:21504
	ds_read_b128 v[222:225], v158 offset:22528
	ds_read_b128 v[226:229], v158 offset:23552
	global_load_lds_dwordx4 v[246:247], off
	v_lshl_add_u64 v[248:249], s[50:51], 0, v[154:155]
	s_mov_b32 m0, s58
	s_nop 0
	global_load_lds_dwordx4 v[248:249], off
	s_barrier
	s_waitcnt lgkmcnt(0)
	s_setprio 1
	s_waitcnt lgkmcnt(0)
	v_mfma_f32_16x16x32_bf16 v[62:65], v[138:141], v[198:201], v[62:65]
	v_mfma_f32_16x16x32_bf16 v[58:61], v[190:193], v[198:201], v[58:61]
	v_mfma_f32_16x16x32_bf16 v[50:53], v[138:141], v[206:209], v[50:53]
	v_mfma_f32_16x16x32_bf16 v[42:45], v[190:193], v[206:209], v[42:45]
	v_mfma_f32_16x16x32_bf16 v[34:37], v[138:141], v[214:217], v[34:37]
	v_mfma_f32_16x16x32_bf16 v[26:29], v[190:193], v[214:217], v[26:29]
	v_mfma_f32_16x16x32_bf16 v[18:21], v[138:141], v[222:225], v[18:21]
	v_mfma_f32_16x16x32_bf16 v[10:13], v[190:193], v[222:225], v[10:13]
	v_mfma_f32_16x16x32_bf16 v[62:65], v[186:189], v[202:205], v[62:65]
	v_mfma_f32_16x16x32_bf16 v[58:61], v[194:197], v[202:205], v[58:61]
	v_mfma_f32_16x16x32_bf16 v[50:53], v[186:189], v[210:213], v[50:53]
	v_mfma_f32_16x16x32_bf16 v[42:45], v[194:197], v[210:213], v[42:45]
	v_mfma_f32_16x16x32_bf16 v[34:37], v[186:189], v[218:221], v[34:37]
	v_mfma_f32_16x16x32_bf16 v[26:29], v[194:197], v[218:221], v[26:29]
	v_mfma_f32_16x16x32_bf16 v[18:21], v[186:189], v[226:229], v[18:21]
	v_mfma_f32_16x16x32_bf16 v[10:13], v[194:197], v[226:229], v[10:13]
	s_setprio 0
	s_barrier
	s_add_u32 s68, s48, 0x40000
	s_addc_u32 s69, s49, 0
	s_add_i32 s67, s66, s57
	v_lshl_add_u64 v[138:139], s[68:69], 0, v[152:153]
	s_mov_b32 m0, s67
	s_nop 0
	global_load_lds_dwordx4 v[138:139], off
	v_lshl_add_u64 v[138:139], s[68:69], 0, v[156:157]
	s_add_i32 m0, s67, 0x2000
	s_nop 0
	global_load_lds_dwordx4 v[138:139], off
	s_waitcnt vmcnt(6)
	s_barrier
	s_setprio 1
	v_mfma_f32_16x16x32_bf16 v[54:57], v[230:233], v[198:201], v[54:57]
	v_mfma_f32_16x16x32_bf16 v[46:49], v[238:241], v[198:201], v[46:49]
	v_mfma_f32_16x16x32_bf16 v[38:41], v[230:233], v[206:209], v[38:41]
	v_mfma_f32_16x16x32_bf16 v[30:33], v[238:241], v[206:209], v[30:33]
	v_mfma_f32_16x16x32_bf16 v[22:25], v[230:233], v[214:217], v[22:25]
	v_mfma_f32_16x16x32_bf16 v[14:17], v[238:241], v[214:217], v[14:17]
	v_mfma_f32_16x16x32_bf16 v[6:9], v[230:233], v[222:225], v[6:9]
	v_mfma_f32_16x16x32_bf16 v[2:5], v[238:241], v[222:225], v[2:5]
	v_mfma_f32_16x16x32_bf16 v[54:57], v[234:237], v[202:205], v[54:57]
	v_mfma_f32_16x16x32_bf16 v[46:49], v[242:245], v[202:205], v[46:49]
	v_mfma_f32_16x16x32_bf16 v[38:41], v[234:237], v[210:213], v[38:41]
	v_mfma_f32_16x16x32_bf16 v[30:33], v[242:245], v[210:213], v[30:33]
	v_mfma_f32_16x16x32_bf16 v[22:25], v[234:237], v[218:221], v[22:25]
	v_mfma_f32_16x16x32_bf16 v[14:17], v[242:245], v[218:221], v[14:17]
	v_mfma_f32_16x16x32_bf16 v[6:9], v[234:237], v[226:229], v[6:9]
	v_mfma_f32_16x16x32_bf16 v[2:5], v[242:245], v[226:229], v[2:5]
	s_setprio 0
	s_add_i32 s67, 0, 0x18000
	v_add_u32_e32 v185, s67, v145
	s_barrier
	ds_read_b128 v[138:141], v185
	ds_read_b128 v[186:189], v185 offset:1024
	ds_read_b128 v[190:193], v185 offset:2048
	ds_read_b128 v[194:197], v185 offset:3072
	s_add_u32 s50, s50, 0x40000
	s_addc_u32 s51, s51, 0
	s_mov_b32 m0, s59
	v_lshl_add_u64 v[230:231], s[50:51], 0, v[150:151]
	ds_read_b128 v[198:201], v158 offset:32768
	ds_read_b128 v[202:205], v158 offset:33792
	ds_read_b128 v[206:209], v158 offset:34816
	ds_read_b128 v[210:213], v158 offset:35840
	ds_read_b128 v[214:217], v158 offset:36864
	ds_read_b128 v[218:221], v158 offset:37888
	ds_read_b128 v[222:225], v158 offset:38912
	ds_read_b128 v[226:229], v158 offset:39936
	global_load_lds_dwordx4 v[230:231], off
	v_lshl_add_u64 v[230:231], s[50:51], 0, v[154:155]
	s_mov_b32 m0, s60
	s_nop 0
	global_load_lds_dwordx4 v[230:231], off
	s_waitcnt lgkmcnt(8)
	s_barrier
	s_waitcnt lgkmcnt(0)
	s_setprio 1
	s_waitcnt lgkmcnt(0)
	v_mfma_f32_16x16x32_bf16 v[126:129], v[138:141], v[198:201], v[126:129]
	v_mfma_f32_16x16x32_bf16 v[122:125], v[190:193], v[198:201], v[122:125]
	v_mfma_f32_16x16x32_bf16 v[110:113], v[138:141], v[206:209], v[110:113]
	v_mfma_f32_16x16x32_bf16 v[106:109], v[190:193], v[206:209], v[106:109]
	v_mfma_f32_16x16x32_bf16 v[94:97], v[138:141], v[214:217], v[94:97]
	v_mfma_f32_16x16x32_bf16 v[90:93], v[190:193], v[214:217], v[90:93]
	v_mfma_f32_16x16x32_bf16 v[78:81], v[138:141], v[222:225], v[78:81]
	v_mfma_f32_16x16x32_bf16 v[74:77], v[190:193], v[222:225], v[74:77]
	v_mfma_f32_16x16x32_bf16 v[126:129], v[186:189], v[202:205], v[126:129]
	v_mfma_f32_16x16x32_bf16 v[122:125], v[194:197], v[202:205], v[122:125]
	v_mfma_f32_16x16x32_bf16 v[110:113], v[186:189], v[210:213], v[110:113]
	v_mfma_f32_16x16x32_bf16 v[106:109], v[194:197], v[210:213], v[106:109]
	v_mfma_f32_16x16x32_bf16 v[94:97], v[186:189], v[218:221], v[94:97]
	v_mfma_f32_16x16x32_bf16 v[90:93], v[194:197], v[218:221], v[90:93]
	v_mfma_f32_16x16x32_bf16 v[78:81], v[186:189], v[226:229], v[78:81]
	v_mfma_f32_16x16x32_bf16 v[74:77], v[194:197], v[226:229], v[74:77]
	s_setprio 0
	s_barrier
	s_add_i32 s50, 0, 0x1c000
	s_add_i32 s51, s67, s57
	v_add_u32_e32 v185, s50, v145
	v_lshl_add_u64 v[142:143], v[142:143], 0, s[6:7]
	s_mov_b32 m0, s51
	ds_read_b128 v[230:233], v185
	ds_read_b128 v[234:237], v185 offset:1024
	ds_read_b128 v[238:241], v185 offset:2048
	ds_read_b128 v[242:245], v185 offset:3072
	global_load_lds_dwordx4 v[142:143], off
	v_lshl_add_u64 v[142:143], v[168:169], 0, s[6:7]
	s_add_i32 m0, s51, 0x2000
	s_nop 0
	global_load_lds_dwordx4 v[142:143], off
	s_barrier
	s_waitcnt lgkmcnt(0)
	s_setprio 1
	s_waitcnt lgkmcnt(0)
	v_mfma_f32_16x16x32_bf16 v[118:121], v[230:233], v[198:201], v[118:121]
	v_mfma_f32_16x16x32_bf16 v[114:117], v[238:241], v[198:201], v[114:117]
	v_mfma_f32_16x16x32_bf16 v[102:105], v[230:233], v[206:209], v[102:105]
	v_mfma_f32_16x16x32_bf16 v[98:101], v[238:241], v[206:209], v[98:101]
	v_mfma_f32_16x16x32_bf16 v[86:89], v[230:233], v[214:217], v[86:89]
	v_mfma_f32_16x16x32_bf16 v[82:85], v[238:241], v[214:217], v[82:85]
	v_mfma_f32_16x16x32_bf16 v[70:73], v[230:233], v[222:225], v[70:73]
	v_mfma_f32_16x16x32_bf16 v[66:69], v[238:241], v[222:225], v[66:69]
	v_mfma_f32_16x16x32_bf16 v[118:121], v[234:237], v[202:205], v[118:121]
	v_mfma_f32_16x16x32_bf16 v[114:117], v[242:245], v[202:205], v[114:117]
	v_mfma_f32_16x16x32_bf16 v[102:105], v[234:237], v[210:213], v[102:105]
	v_mfma_f32_16x16x32_bf16 v[98:101], v[242:245], v[210:213], v[98:101]
	v_mfma_f32_16x16x32_bf16 v[86:89], v[234:237], v[218:221], v[86:89]
	v_mfma_f32_16x16x32_bf16 v[82:85], v[242:245], v[218:221], v[82:85]
	v_mfma_f32_16x16x32_bf16 v[70:73], v[234:237], v[226:229], v[70:73]
	v_mfma_f32_16x16x32_bf16 v[66:69], v[242:245], v[226:229], v[66:69]
	s_setprio 0
	s_mov_b32 m0, s62
	v_lshl_add_u64 v[142:143], v[246:247], 0, s[6:7]
	s_barrier
	ds_read_b128 v[198:201], v158 offset:49152
	ds_read_b128 v[202:205], v158 offset:50176
	ds_read_b128 v[206:209], v158 offset:51200
	ds_read_b128 v[210:213], v158 offset:52224
	ds_read_b128 v[214:217], v158 offset:53248
	ds_read_b128 v[218:221], v158 offset:54272
	ds_read_b128 v[222:225], v158 offset:55296
	ds_read_b128 v[226:229], v158 offset:56320
	global_load_lds_dwordx4 v[142:143], off
	v_lshl_add_u64 v[142:143], v[248:249], 0, s[6:7]
	s_mov_b32 m0, s63
	s_nop 0
	global_load_lds_dwordx4 v[142:143], off
	s_barrier
	s_waitcnt lgkmcnt(0)
	s_setprio 1
	s_waitcnt lgkmcnt(0)
	v_mfma_f32_16x16x32_bf16 v[62:65], v[138:141], v[198:201], v[62:65]
	v_mfma_f32_16x16x32_bf16 v[58:61], v[190:193], v[198:201], v[58:61]
	v_mfma_f32_16x16x32_bf16 v[50:53], v[138:141], v[206:209], v[50:53]
	v_mfma_f32_16x16x32_bf16 v[42:45], v[190:193], v[206:209], v[42:45]
	v_mfma_f32_16x16x32_bf16 v[34:37], v[138:141], v[214:217], v[34:37]
	v_mfma_f32_16x16x32_bf16 v[26:29], v[190:193], v[214:217], v[26:29]
	v_mfma_f32_16x16x32_bf16 v[18:21], v[138:141], v[222:225], v[18:21]
	v_mfma_f32_16x16x32_bf16 v[10:13], v[190:193], v[222:225], v[10:13]
	v_mfma_f32_16x16x32_bf16 v[62:65], v[186:189], v[202:205], v[62:65]
	v_mfma_f32_16x16x32_bf16 v[58:61], v[194:197], v[202:205], v[58:61]
	v_mfma_f32_16x16x32_bf16 v[50:53], v[186:189], v[210:213], v[50:53]
	v_mfma_f32_16x16x32_bf16 v[42:45], v[194:197], v[210:213], v[42:45]
	v_mfma_f32_16x16x32_bf16 v[34:37], v[186:189], v[218:221], v[34:37]
	v_mfma_f32_16x16x32_bf16 v[26:29], v[194:197], v[218:221], v[26:29]
	v_mfma_f32_16x16x32_bf16 v[18:21], v[186:189], v[226:229], v[18:21]
	v_mfma_f32_16x16x32_bf16 v[10:13], v[194:197], v[226:229], v[10:13]
	s_setprio 0
	s_barrier
	s_add_u32 s48, s48, 0x40080
	s_addc_u32 s49, s49, 0
	s_add_i32 s50, s50, s57
	v_lshl_add_u64 v[138:139], s[48:49], 0, v[152:153]
	s_mov_b32 m0, s50
	s_nop 0
	global_load_lds_dwordx4 v[138:139], off
	v_lshl_add_u64 v[138:139], s[48:49], 0, v[156:157]
	s_add_i32 m0, s50, 0x2000
	s_nop 0
	global_load_lds_dwordx4 v[138:139], off
	s_waitcnt vmcnt(6)
	s_barrier
	s_setprio 1
	v_mfma_f32_16x16x32_bf16 v[54:57], v[230:233], v[198:201], v[54:57]
	v_mfma_f32_16x16x32_bf16 v[46:49], v[238:241], v[198:201], v[46:49]
	v_mfma_f32_16x16x32_bf16 v[38:41], v[230:233], v[206:209], v[38:41]
	v_mfma_f32_16x16x32_bf16 v[30:33], v[238:241], v[206:209], v[30:33]
	v_mfma_f32_16x16x32_bf16 v[22:25], v[230:233], v[214:217], v[22:25]
	v_mfma_f32_16x16x32_bf16 v[14:17], v[238:241], v[214:217], v[14:17]
	v_mfma_f32_16x16x32_bf16 v[6:9], v[230:233], v[222:225], v[6:9]
	v_mfma_f32_16x16x32_bf16 v[2:5], v[238:241], v[222:225], v[2:5]
	v_mfma_f32_16x16x32_bf16 v[54:57], v[234:237], v[202:205], v[54:57]
	v_mfma_f32_16x16x32_bf16 v[46:49], v[242:245], v[202:205], v[46:49]
	v_mfma_f32_16x16x32_bf16 v[38:41], v[234:237], v[210:213], v[38:41]
	v_mfma_f32_16x16x32_bf16 v[30:33], v[242:245], v[210:213], v[30:33]
	v_mfma_f32_16x16x32_bf16 v[22:25], v[234:237], v[218:221], v[22:25]
	v_mfma_f32_16x16x32_bf16 v[14:17], v[242:245], v[218:221], v[14:17]
	v_mfma_f32_16x16x32_bf16 v[6:9], v[234:237], v[226:229], v[6:9]
	v_mfma_f32_16x16x32_bf16 v[2:5], v[242:245], v[226:229], v[2:5]
	s_setprio 0
	s_add_i32 s47, s47, 2
	s_add_u32 s44, s44, 0x100
	s_addc_u32 s45, s45, 0
	s_add_u32 s37, s37, 0x100
	s_addc_u32 s46, s46, 0
	s_cmp_gt_u32 s47, 13
	s_barrier
	s_cbranch_scc0 .LBB0_690
	v_lshl_add_u32 v142, s42, 8, v144
	v_lshl_or_b32 v140, s20, 8, v146
	v_ashrrev_i32_e32 v143, 31, v142
	v_ashrrev_i32_e32 v141, 31, v140
	v_lshlrev_b64 v[138:139], 10, v[142:143]
	v_lshl_add_u64 v[138:139], v[138:139], 0, v[140:141]
	v_lshlrev_b64 v[138:139], 1, v[138:139]
	s_and_b64 vcc, exec, s[2:3]
	s_mov_b32 s20, s34
	s_mov_b32 s42, s36
	s_mov_b64 s[48:49], s[40:41]
	s_mov_b64 s[44:45], s[38:39]
	v_mov_b32_e32 v192, v138
	v_add_u32_e32 v193, 0x8000, v138
	v_add_u32_e32 v194, 0x10000, v138
	v_add_u32_e32 v195, 0x18000, v138
	v_add_u32_e32 v196, 0x40000, v138
	v_add_u32_e32 v197, 0x48000, v138
	v_add_u32_e32 v198, 0x50000, v138
	v_add_u32_e32 v199, 0x58000, v138
	global_load_dwordx4 v[200:203], v192, s[4:5]
	global_load_dwordx4 v[204:207], v192, s[4:5] offset:256
	global_load_dwordx4 v[208:211], v193, s[4:5]
	global_load_dwordx4 v[212:215], v193, s[4:5] offset:256
	global_load_dwordx4 v[216:219], v194, s[4:5]
	global_load_dwordx4 v[220:223], v194, s[4:5] offset:256
	global_load_dwordx4 v[224:227], v195, s[4:5]
	global_load_dwordx4 v[228:231], v195, s[4:5] offset:256
	s_waitcnt vmcnt(7)
	v_lshlrev_b32_e32 v143, 16, v200
	v_and_b32_e32 v185, 0xffff0000, v200
	v_lshlrev_b32_e32 v200, 16, v201
	v_and_b32_e32 v201, 0xffff0000, v201
	v_lshlrev_b32_e32 v191, 16, v203
	v_and_b32_e32 v203, 0xffff0000, v203
	v_lshlrev_b32_e32 v190, 16, v202
	v_and_b32_e32 v202, 0xffff0000, v202
	v_mul_f32_e32 v126, v126, v143
	v_mul_f32_e32 v127, v127, v185
	v_mul_f32_e32 v128, v128, v200
	v_mul_f32_e32 v129, v129, v201
	v_mul_f32_e32 v125, v125, v203
	v_mul_f32_e32 v143, v122, v190
	v_mul_f32_e32 v185, v123, v202
	v_mul_f32_e32 v200, v124, v191
	v_cvt_pk_bf16_f32 v122, v126, v127
	v_cvt_pk_bf16_f32 v123, v128, v129
	v_cvt_pk_bf16_f32 v124, v143, v185
	v_cvt_pk_bf16_f32 v125, v200, v125
	global_store_dwordx4 v192, v[122:125], s[18:19]
	s_nop 1
	global_load_dwordx4 v[200:203], v196, s[4:5]
	s_waitcnt vmcnt(8)
	v_lshlrev_b32_e32 v122, 16, v204
	v_and_b32_e32 v123, 0xffff0000, v204
	v_lshlrev_b32_e32 v124, 16, v205
	v_and_b32_e32 v125, 0xffff0000, v205
	v_lshlrev_b32_e32 v204, 16, v206
	v_and_b32_e32 v205, 0xffff0000, v206
	v_lshlrev_b32_e32 v206, 16, v207
	v_and_b32_e32 v207, 0xffff0000, v207
	v_mul_f32_e32 v117, v117, v207
	v_mul_f32_e32 v118, v118, v122
	v_mul_f32_e32 v119, v119, v123
	v_mul_f32_e32 v120, v120, v124
	v_mul_f32_e32 v121, v121, v125
	v_mul_f32_e32 v122, v114, v204
	v_mul_f32_e32 v123, v115, v205
	v_mul_f32_e32 v124, v116, v206
	v_cvt_pk_bf16_f32 v114, v118, v119
	v_cvt_pk_bf16_f32 v115, v120, v121
	v_cvt_pk_bf16_f32 v116, v122, v123
	v_cvt_pk_bf16_f32 v117, v124, v117
	global_store_dwordx4 v192, v[114:117], s[18:19] offset:256
	s_nop 1
	global_load_dwordx4 v[204:207], v196, s[4:5] offset:256
	s_waitcnt vmcnt(9)
	v_lshlrev_b32_e32 v118, 16, v208
	v_and_b32_e32 v208, 0xffff0000, v208
	v_lshlrev_b32_e32 v119, 16, v209
	v_and_b32_e32 v209, 0xffff0000, v209
	v_lshlrev_b32_e32 v121, 16, v211
	v_and_b32_e32 v211, 0xffff0000, v211
	v_lshlrev_b32_e32 v120, 16, v210
	v_and_b32_e32 v210, 0xffff0000, v210
	v_mul_f32_e32 v110, v110, v118
	v_mul_f32_e32 v111, v111, v208
	v_mul_f32_e32 v112, v112, v119
	v_mul_f32_e32 v113, v113, v209
	v_mul_f32_e32 v109, v109, v211
	v_mul_f32_e32 v208, v106, v120
	v_mul_f32_e32 v209, v107, v210
	v_mul_f32_e32 v210, v108, v121
	v_cvt_pk_bf16_f32 v106, v110, v111
	v_cvt_pk_bf16_f32 v107, v112, v113
	v_cvt_pk_bf16_f32 v108, v208, v209
	v_cvt_pk_bf16_f32 v109, v210, v109
	global_store_dwordx4 v193, v[106:109], s[18:19]
	s_nop 1
	global_load_dwordx4 v[208:211], v197, s[4:5]
	s_waitcnt vmcnt(10)
	v_lshlrev_b32_e32 v106, 16, v212
	v_and_b32_e32 v107, 0xffff0000, v212
	v_lshlrev_b32_e32 v108, 16, v213
	v_and_b32_e32 v109, 0xffff0000, v213
	v_lshlrev_b32_e32 v212, 16, v214
	v_and_b32_e32 v213, 0xffff0000, v214
	v_lshlrev_b32_e32 v214, 16, v215
	v_and_b32_e32 v215, 0xffff0000, v215
	v_mul_f32_e32 v101, v101, v215
	v_mul_f32_e32 v102, v102, v106
	v_mul_f32_e32 v103, v103, v107
	v_mul_f32_e32 v104, v104, v108
	v_mul_f32_e32 v105, v105, v109
	v_mul_f32_e32 v106, v98, v212
	v_mul_f32_e32 v107, v99, v213
	v_mul_f32_e32 v108, v100, v214
	v_cvt_pk_bf16_f32 v98, v102, v103
	v_cvt_pk_bf16_f32 v99, v104, v105
	v_cvt_pk_bf16_f32 v100, v106, v107
	v_cvt_pk_bf16_f32 v101, v108, v101
	global_store_dwordx4 v193, v[98:101], s[18:19] offset:256
	s_nop 1
	global_load_dwordx4 v[212:215], v197, s[4:5] offset:256
	s_waitcnt vmcnt(11)
	v_lshlrev_b32_e32 v102, 16, v216
	v_and_b32_e32 v216, 0xffff0000, v216
	v_lshlrev_b32_e32 v103, 16, v217
	v_and_b32_e32 v217, 0xffff0000, v217
	v_lshlrev_b32_e32 v105, 16, v219
	v_and_b32_e32 v219, 0xffff0000, v219
	v_lshlrev_b32_e32 v104, 16, v218
	v_and_b32_e32 v218, 0xffff0000, v218
	v_mul_f32_e32 v94, v94, v102
	v_mul_f32_e32 v95, v95, v216
	v_mul_f32_e32 v96, v96, v103
	v_mul_f32_e32 v97, v97, v217
	v_mul_f32_e32 v93, v93, v219
	v_mul_f32_e32 v216, v90, v104
	v_mul_f32_e32 v217, v91, v218
	v_mul_f32_e32 v218, v92, v105
	v_cvt_pk_bf16_f32 v90, v94, v95
	v_cvt_pk_bf16_f32 v91, v96, v97
	v_cvt_pk_bf16_f32 v92, v216, v217
	v_cvt_pk_bf16_f32 v93, v218, v93
	global_store_dwordx4 v194, v[90:93], s[18:19]
	s_nop 1
	global_load_dwordx4 v[216:219], v198, s[4:5]
	s_waitcnt vmcnt(12)
	v_lshlrev_b32_e32 v90, 16, v220
	v_and_b32_e32 v91, 0xffff0000, v220
	v_lshlrev_b32_e32 v92, 16, v221
	v_and_b32_e32 v93, 0xffff0000, v221
	v_lshlrev_b32_e32 v220, 16, v222
	v_and_b32_e32 v221, 0xffff0000, v222
	v_lshlrev_b32_e32 v222, 16, v223
	v_and_b32_e32 v223, 0xffff0000, v223
	v_mul_f32_e32 v85, v85, v223
	v_mul_f32_e32 v86, v86, v90
	v_mul_f32_e32 v87, v87, v91
	v_mul_f32_e32 v88, v88, v92
	v_mul_f32_e32 v89, v89, v93
	v_mul_f32_e32 v90, v82, v220
	v_mul_f32_e32 v91, v83, v221
	v_mul_f32_e32 v92, v84, v222
	v_cvt_pk_bf16_f32 v82, v86, v87
	v_cvt_pk_bf16_f32 v83, v88, v89
	v_cvt_pk_bf16_f32 v84, v90, v91
	v_cvt_pk_bf16_f32 v85, v92, v85
	global_store_dwordx4 v194, v[82:85], s[18:19] offset:256
	s_nop 1
	global_load_dwordx4 v[220:223], v198, s[4:5] offset:256
	s_waitcnt vmcnt(13)
	v_lshlrev_b32_e32 v86, 16, v224
	v_and_b32_e32 v224, 0xffff0000, v224
	v_lshlrev_b32_e32 v87, 16, v225
	v_and_b32_e32 v225, 0xffff0000, v225
	v_lshlrev_b32_e32 v89, 16, v227
	v_and_b32_e32 v227, 0xffff0000, v227
	v_lshlrev_b32_e32 v88, 16, v226
	v_and_b32_e32 v226, 0xffff0000, v226
	v_mul_f32_e32 v78, v78, v86
	v_mul_f32_e32 v79, v79, v224
	v_mul_f32_e32 v80, v80, v87
	v_mul_f32_e32 v81, v81, v225
	v_mul_f32_e32 v77, v77, v227
	v_mul_f32_e32 v224, v74, v88
	v_mul_f32_e32 v225, v75, v226
	v_mul_f32_e32 v226, v76, v89
	v_cvt_pk_bf16_f32 v74, v78, v79
	v_cvt_pk_bf16_f32 v75, v80, v81
	v_cvt_pk_bf16_f32 v76, v224, v225
	v_cvt_pk_bf16_f32 v77, v226, v77
	global_store_dwordx4 v195, v[74:77], s[18:19]
	s_nop 1
	global_load_dwordx4 v[224:227], v199, s[4:5]
	s_waitcnt vmcnt(14)
	v_lshlrev_b32_e32 v74, 16, v228
	v_and_b32_e32 v75, 0xffff0000, v228
	v_lshlrev_b32_e32 v76, 16, v229
	v_and_b32_e32 v77, 0xffff0000, v229
	v_lshlrev_b32_e32 v228, 16, v230
	v_and_b32_e32 v229, 0xffff0000, v230
	v_lshlrev_b32_e32 v230, 16, v231
	v_and_b32_e32 v231, 0xffff0000, v231
	v_mul_f32_e32 v69, v69, v231
	v_mul_f32_e32 v70, v70, v74
	v_mul_f32_e32 v71, v71, v75
	v_mul_f32_e32 v72, v72, v76
	v_mul_f32_e32 v73, v73, v77
	v_mul_f32_e32 v74, v66, v228
	v_mul_f32_e32 v75, v67, v229
	v_mul_f32_e32 v76, v68, v230
	v_cvt_pk_bf16_f32 v66, v70, v71
	v_cvt_pk_bf16_f32 v67, v72, v73
	v_cvt_pk_bf16_f32 v68, v74, v75
	v_cvt_pk_bf16_f32 v69, v76, v69
	global_store_dwordx4 v195, v[66:69], s[18:19] offset:256
	s_nop 1
	global_load_dwordx4 v[228:231], v199, s[4:5] offset:256
	s_waitcnt vmcnt(14)
	v_lshlrev_b32_e32 v70, 16, v200
	v_and_b32_e32 v200, 0xffff0000, v200
	v_lshlrev_b32_e32 v71, 16, v201
	v_and_b32_e32 v201, 0xffff0000, v201
	v_lshlrev_b32_e32 v73, 16, v203
	v_and_b32_e32 v203, 0xffff0000, v203
	v_lshlrev_b32_e32 v72, 16, v202
	v_and_b32_e32 v202, 0xffff0000, v202
	v_mul_f32_e32 v62, v62, v70
	v_mul_f32_e32 v63, v63, v200
	v_mul_f32_e32 v64, v64, v71
	v_mul_f32_e32 v65, v65, v201
	v_mul_f32_e32 v61, v61, v203
	v_mul_f32_e32 v200, v58, v72
	v_mul_f32_e32 v201, v59, v202
	v_mul_f32_e32 v202, v60, v73
	v_cvt_pk_bf16_f32 v58, v62, v63
	v_cvt_pk_bf16_f32 v59, v64, v65
	v_cvt_pk_bf16_f32 v60, v200, v201
	v_cvt_pk_bf16_f32 v61, v202, v61
	global_store_dwordx4 v196, v[58:61], s[18:19]
	s_nop 1
	s_waitcnt vmcnt(13)
	v_lshlrev_b32_e32 v58, 16, v204
	v_and_b32_e32 v59, 0xffff0000, v204
	v_lshlrev_b32_e32 v60, 16, v205
	v_and_b32_e32 v61, 0xffff0000, v205
	v_lshlrev_b32_e32 v204, 16, v206
	v_and_b32_e32 v205, 0xffff0000, v206
	v_lshlrev_b32_e32 v206, 16, v207
	v_and_b32_e32 v207, 0xffff0000, v207
	v_mul_f32_e32 v49, v49, v207
	v_mul_f32_e32 v54, v54, v58
	v_mul_f32_e32 v55, v55, v59
	v_mul_f32_e32 v56, v56, v60
	v_mul_f32_e32 v57, v57, v61
	v_mul_f32_e32 v58, v46, v204
	v_mul_f32_e32 v59, v47, v205
	v_mul_f32_e32 v60, v48, v206
	v_cvt_pk_bf16_f32 v46, v54, v55
	v_cvt_pk_bf16_f32 v47, v56, v57
	v_cvt_pk_bf16_f32 v48, v58, v59
	v_cvt_pk_bf16_f32 v49, v60, v49
	global_store_dwordx4 v196, v[46:49], s[18:19] offset:256
	s_nop 1
	s_waitcnt vmcnt(12)
	v_lshlrev_b32_e32 v54, 16, v208
	v_and_b32_e32 v208, 0xffff0000, v208
	v_lshlrev_b32_e32 v55, 16, v209
	v_and_b32_e32 v209, 0xffff0000, v209
	v_lshlrev_b32_e32 v56, 16, v210
	v_and_b32_e32 v210, 0xffff0000, v210
	v_lshlrev_b32_e32 v57, 16, v211
	v_and_b32_e32 v211, 0xffff0000, v211
	v_mul_f32_e32 v208, v51, v208
	v_mul_f32_e32 v209, v53, v209
	v_mul_f32_e32 v210, v43, v210
	v_mul_f32_e32 v45, v45, v211
	v_mul_f32_e32 v50, v50, v54
	v_mul_f32_e32 v51, v52, v55
	v_mul_f32_e32 v52, v42, v56
	v_mul_f32_e32 v53, v44, v57
	v_cvt_pk_bf16_f32 v42, v50, v208
	v_cvt_pk_bf16_f32 v43, v51, v209
	v_cvt_pk_bf16_f32 v44, v52, v210
	v_cvt_pk_bf16_f32 v45, v53, v45
	global_store_dwordx4 v197, v[42:45], s[18:19]
	s_nop 1
	s_waitcnt vmcnt(11)
	v_lshlrev_b32_e32 v42, 16, v212
	v_and_b32_e32 v43, 0xffff0000, v212
	v_lshlrev_b32_e32 v44, 16, v213
	v_and_b32_e32 v45, 0xffff0000, v213
	v_lshlrev_b32_e32 v212, 16, v214
	v_and_b32_e32 v213, 0xffff0000, v214
	v_lshlrev_b32_e32 v214, 16, v215
	v_and_b32_e32 v215, 0xffff0000, v215
	v_mul_f32_e32 v33, v33, v215
	v_mul_f32_e32 v38, v38, v42
	v_mul_f32_e32 v39, v39, v43
	v_mul_f32_e32 v40, v40, v44
	v_mul_f32_e32 v41, v41, v45
	v_mul_f32_e32 v42, v30, v212
	v_mul_f32_e32 v43, v31, v213
	v_mul_f32_e32 v44, v32, v214
	v_cvt_pk_bf16_f32 v30, v38, v39
	v_cvt_pk_bf16_f32 v31, v40, v41
	v_cvt_pk_bf16_f32 v32, v42, v43
	v_cvt_pk_bf16_f32 v33, v44, v33
	global_store_dwordx4 v197, v[30:33], s[18:19] offset:256
	s_nop 1
	s_waitcnt vmcnt(10)
	v_lshlrev_b32_e32 v38, 16, v216
	v_and_b32_e32 v216, 0xffff0000, v216
	v_lshlrev_b32_e32 v39, 16, v217
	v_and_b32_e32 v217, 0xffff0000, v217
	v_lshlrev_b32_e32 v40, 16, v218
	v_and_b32_e32 v218, 0xffff0000, v218
	v_lshlrev_b32_e32 v41, 16, v219
	v_and_b32_e32 v219, 0xffff0000, v219
	v_mul_f32_e32 v216, v35, v216
	v_mul_f32_e32 v217, v37, v217
	v_mul_f32_e32 v218, v27, v218
	v_mul_f32_e32 v29, v29, v219
	v_mul_f32_e32 v34, v34, v38
	v_mul_f32_e32 v35, v36, v39
	v_mul_f32_e32 v36, v26, v40
	v_mul_f32_e32 v37, v28, v41
	v_cvt_pk_bf16_f32 v26, v34, v216
	v_cvt_pk_bf16_f32 v27, v35, v217
	v_cvt_pk_bf16_f32 v28, v36, v218
	v_cvt_pk_bf16_f32 v29, v37, v29
	global_store_dwordx4 v198, v[26:29], s[18:19]
	s_nop 1
	s_waitcnt vmcnt(9)
	v_lshlrev_b32_e32 v26, 16, v220
	v_and_b32_e32 v27, 0xffff0000, v220
	v_lshlrev_b32_e32 v28, 16, v221
	v_and_b32_e32 v29, 0xffff0000, v221
	v_lshlrev_b32_e32 v220, 16, v222
	v_and_b32_e32 v221, 0xffff0000, v222
	v_lshlrev_b32_e32 v222, 16, v223
	v_and_b32_e32 v223, 0xffff0000, v223
	v_mul_f32_e32 v17, v17, v223
	v_mul_f32_e32 v22, v22, v26
	v_mul_f32_e32 v23, v23, v27
	v_mul_f32_e32 v24, v24, v28
	v_mul_f32_e32 v25, v25, v29
	v_mul_f32_e32 v26, v14, v220
	v_mul_f32_e32 v27, v15, v221
	v_mul_f32_e32 v28, v16, v222
	v_cvt_pk_bf16_f32 v14, v22, v23
	v_cvt_pk_bf16_f32 v15, v24, v25
	v_cvt_pk_bf16_f32 v16, v26, v27
	v_cvt_pk_bf16_f32 v17, v28, v17
	global_store_dwordx4 v198, v[14:17], s[18:19] offset:256
	s_nop 1
	s_waitcnt vmcnt(8)
	v_lshlrev_b32_e32 v22, 16, v224
	v_and_b32_e32 v224, 0xffff0000, v224
	v_lshlrev_b32_e32 v23, 16, v225
	v_and_b32_e32 v225, 0xffff0000, v225
	v_lshlrev_b32_e32 v24, 16, v226
	v_and_b32_e32 v226, 0xffff0000, v226
	v_lshlrev_b32_e32 v25, 16, v227
	v_and_b32_e32 v227, 0xffff0000, v227
	v_mul_f32_e32 v224, v19, v224
	v_mul_f32_e32 v225, v21, v225
	v_mul_f32_e32 v226, v11, v226
	v_mul_f32_e32 v13, v13, v227
	v_mul_f32_e32 v18, v18, v22
	v_mul_f32_e32 v19, v20, v23
	v_mul_f32_e32 v20, v10, v24
	v_mul_f32_e32 v21, v12, v25
	v_cvt_pk_bf16_f32 v10, v18, v224
	v_cvt_pk_bf16_f32 v11, v19, v225
	v_cvt_pk_bf16_f32 v12, v20, v226
	v_cvt_pk_bf16_f32 v13, v21, v13
	global_store_dwordx4 v199, v[10:13], s[18:19]
	s_nop 1
	s_waitcnt vmcnt(7)
	v_lshlrev_b32_e32 v10, 16, v228
	v_and_b32_e32 v11, 0xffff0000, v228
	v_lshlrev_b32_e32 v12, 16, v229
	v_and_b32_e32 v13, 0xffff0000, v229
	v_lshlrev_b32_e32 v228, 16, v230
	v_and_b32_e32 v229, 0xffff0000, v230
	v_lshlrev_b32_e32 v230, 16, v231
	v_and_b32_e32 v231, 0xffff0000, v231
	v_mul_f32_e32 v5, v5, v231
	v_mul_f32_e32 v6, v6, v10
	v_mul_f32_e32 v7, v7, v11
	v_mul_f32_e32 v8, v8, v12
	v_mul_f32_e32 v9, v9, v13
	v_mul_f32_e32 v10, v2, v228
	v_mul_f32_e32 v11, v3, v229
	v_mul_f32_e32 v12, v4, v230
	v_cvt_pk_bf16_f32 v2, v6, v7
	v_cvt_pk_bf16_f32 v3, v8, v9
	v_cvt_pk_bf16_f32 v4, v10, v11
	v_cvt_pk_bf16_f32 v5, v12, v5
	global_store_dwordx4 v199, v[2:5], s[18:19] offset:256
	s_nop 1
	s_cbranch_vccz .LBB0_683
	s_waitcnt vmcnt(0)
	s_cmpk_gt_u32 s25, 0xff
	s_cbranch_scc1 .LBB0_694
	s_barrier

.LBB0_762:
	ds_read_b128 v[138:141], v147
	ds_read_b128 v[186:189], v147 offset:1024
	ds_read_b128 v[190:193], v147 offset:2048
	ds_read_b128 v[194:197], v147 offset:3072
	s_add_u32 s58, s56, 0xfffc0080
	s_addc_u32 s59, s57, -1
	s_cmp_eq_u32 s47, 12
	s_cselect_b32 s61, s21, s59
	s_cselect_b32 s60, s22, s58
	s_cselect_b32 s59, s23, s46
	s_cselect_b32 s58, s41, s43
	v_lshl_add_u64 v[142:143], s[56:57], 0, v[130:131]
	s_add_i32 m0, s51, 0xc000
	ds_read_b128 v[198:201], v158
	ds_read_b128 v[202:205], v158 offset:1024
	ds_read_b128 v[206:209], v158 offset:2048
	ds_read_b128 v[210:213], v158 offset:3072
	ds_read_b128 v[214:217], v158 offset:4096
	ds_read_b128 v[218:221], v158 offset:5120
	ds_read_b128 v[222:225], v158 offset:6144
	ds_read_b128 v[226:229], v158 offset:7168
	global_load_lds_dwordx4 v[142:143], off
	v_lshl_add_u64 v[142:143], s[56:57], 0, v[132:133]
	s_add_i32 m0, s51, 0xe000
	s_nop 0
	global_load_lds_dwordx4 v[142:143], off
	s_waitcnt lgkmcnt(8)
	s_barrier
	s_waitcnt lgkmcnt(0)
	s_setprio 1
	s_waitcnt lgkmcnt(0)
	v_mfma_f32_16x16x32_bf16 v[126:129], v[138:141], v[198:201], v[126:129]
	v_mfma_f32_16x16x32_bf16 v[122:125], v[190:193], v[198:201], v[122:125]
	v_mfma_f32_16x16x32_bf16 v[110:113], v[138:141], v[206:209], v[110:113]
	v_mfma_f32_16x16x32_bf16 v[106:109], v[190:193], v[206:209], v[106:109]
	v_mfma_f32_16x16x32_bf16 v[94:97], v[138:141], v[214:217], v[94:97]
	v_mfma_f32_16x16x32_bf16 v[90:93], v[190:193], v[214:217], v[90:93]
	v_mfma_f32_16x16x32_bf16 v[78:81], v[138:141], v[222:225], v[78:81]
	v_mfma_f32_16x16x32_bf16 v[74:77], v[190:193], v[222:225], v[74:77]
	v_mfma_f32_16x16x32_bf16 v[126:129], v[186:189], v[202:205], v[126:129]
	v_mfma_f32_16x16x32_bf16 v[122:125], v[194:197], v[202:205], v[122:125]
	v_mfma_f32_16x16x32_bf16 v[110:113], v[186:189], v[210:213], v[110:113]
	v_mfma_f32_16x16x32_bf16 v[106:109], v[194:197], v[210:213], v[106:109]
	v_mfma_f32_16x16x32_bf16 v[94:97], v[186:189], v[218:221], v[94:97]
	v_mfma_f32_16x16x32_bf16 v[90:93], v[194:197], v[218:221], v[90:93]
	v_mfma_f32_16x16x32_bf16 v[78:81], v[186:189], v[226:229], v[78:81]
	v_mfma_f32_16x16x32_bf16 v[74:77], v[194:197], v[226:229], v[74:77]
	s_setprio 0
	s_barrier
	s_add_i32 s74, s72, s64
	v_lshl_add_u64 v[142:143], s[58:59], 0, v[152:153]
	s_mov_b32 m0, s74
	ds_read_b128 v[230:233], v159
	ds_read_b128 v[234:237], v159 offset:1024
	ds_read_b128 v[238:241], v159 offset:2048
	ds_read_b128 v[242:245], v159 offset:3072
	global_load_lds_dwordx4 v[142:143], off
	v_lshl_add_u64 v[246:247], s[58:59], 0, v[156:157]
	s_add_i32 m0, s74, 0x2000
	s_nop 0
	global_load_lds_dwordx4 v[246:247], off
	s_barrier
	s_waitcnt lgkmcnt(0)
	s_setprio 1
	s_waitcnt lgkmcnt(0)
	v_mfma_f32_16x16x32_bf16 v[118:121], v[230:233], v[198:201], v[118:121]
	v_mfma_f32_16x16x32_bf16 v[114:117], v[238:241], v[198:201], v[114:117]
	v_mfma_f32_16x16x32_bf16 v[102:105], v[230:233], v[206:209], v[102:105]
	v_mfma_f32_16x16x32_bf16 v[98:101], v[238:241], v[206:209], v[98:101]
	v_mfma_f32_16x16x32_bf16 v[86:89], v[230:233], v[214:217], v[86:89]
	v_mfma_f32_16x16x32_bf16 v[82:85], v[238:241], v[214:217], v[82:85]
	v_mfma_f32_16x16x32_bf16 v[70:73], v[230:233], v[222:225], v[70:73]
	v_mfma_f32_16x16x32_bf16 v[66:69], v[238:241], v[222:225], v[66:69]
	v_mfma_f32_16x16x32_bf16 v[118:121], v[234:237], v[202:205], v[118:121]
	v_mfma_f32_16x16x32_bf16 v[114:117], v[242:245], v[202:205], v[114:117]
	v_mfma_f32_16x16x32_bf16 v[102:105], v[234:237], v[210:213], v[102:105]
	v_mfma_f32_16x16x32_bf16 v[98:101], v[242:245], v[210:213], v[98:101]
	v_mfma_f32_16x16x32_bf16 v[86:89], v[234:237], v[218:221], v[86:89]
	v_mfma_f32_16x16x32_bf16 v[82:85], v[242:245], v[218:221], v[82:85]
	v_mfma_f32_16x16x32_bf16 v[70:73], v[234:237], v[226:229], v[70:73]
	v_mfma_f32_16x16x32_bf16 v[66:69], v[242:245], v[226:229], v[66:69]
	s_setprio 0
	s_mov_b32 m0, s51
	v_lshl_add_u64 v[248:249], s[60:61], 0, v[150:151]
	s_barrier
	ds_read_b128 v[198:201], v158 offset:16384
	ds_read_b128 v[202:205], v158 offset:17408
	ds_read_b128 v[206:209], v158 offset:18432
	ds_read_b128 v[210:213], v158 offset:19456
	ds_read_b128 v[214:217], v158 offset:20480
	ds_read_b128 v[218:221], v158 offset:21504
	ds_read_b128 v[222:225], v158 offset:22528
	ds_read_b128 v[226:229], v158 offset:23552
	global_load_lds_dwordx4 v[248:249], off
	v_lshl_add_u64 v[250:251], s[60:61], 0, v[154:155]
	s_mov_b32 m0, s65
	s_nop 0
	global_load_lds_dwordx4 v[250:251], off
	s_barrier
	s_waitcnt lgkmcnt(0)
	s_setprio 1
	s_waitcnt lgkmcnt(0)
	v_mfma_f32_16x16x32_bf16 v[62:65], v[138:141], v[198:201], v[62:65]
	v_mfma_f32_16x16x32_bf16 v[58:61], v[190:193], v[198:201], v[58:61]
	v_mfma_f32_16x16x32_bf16 v[46:49], v[138:141], v[206:209], v[46:49]
	v_mfma_f32_16x16x32_bf16 v[42:45], v[190:193], v[206:209], v[42:45]
	v_mfma_f32_16x16x32_bf16 v[30:33], v[138:141], v[214:217], v[30:33]
	v_mfma_f32_16x16x32_bf16 v[26:29], v[190:193], v[214:217], v[26:29]
	v_mfma_f32_16x16x32_bf16 v[14:17], v[138:141], v[222:225], v[14:17]
	v_mfma_f32_16x16x32_bf16 v[10:13], v[190:193], v[222:225], v[10:13]
	v_mfma_f32_16x16x32_bf16 v[62:65], v[186:189], v[202:205], v[62:65]
	v_mfma_f32_16x16x32_bf16 v[58:61], v[194:197], v[202:205], v[58:61]
	v_mfma_f32_16x16x32_bf16 v[46:49], v[186:189], v[210:213], v[46:49]
	v_mfma_f32_16x16x32_bf16 v[42:45], v[194:197], v[210:213], v[42:45]
	v_mfma_f32_16x16x32_bf16 v[30:33], v[186:189], v[218:221], v[30:33]
	v_mfma_f32_16x16x32_bf16 v[26:29], v[194:197], v[218:221], v[26:29]
	v_mfma_f32_16x16x32_bf16 v[14:17], v[186:189], v[226:229], v[14:17]
	v_mfma_f32_16x16x32_bf16 v[10:13], v[194:197], v[226:229], v[10:13]
	s_setprio 0
	s_barrier
	s_add_u32 s74, s58, 0x40000
	s_addc_u32 s75, s59, 0
	s_add_i32 s76, s73, s64
	v_lshl_add_u64 v[138:139], s[74:75], 0, v[152:153]
	s_mov_b32 m0, s76
	s_nop 0
	global_load_lds_dwordx4 v[138:139], off
	v_lshl_add_u64 v[138:139], s[74:75], 0, v[156:157]
	s_add_i32 m0, s76, 0x2000
	s_nop 0
	global_load_lds_dwordx4 v[138:139], off
	s_waitcnt vmcnt(6)
	s_barrier
	s_setprio 1
	v_mfma_f32_16x16x32_bf16 v[54:57], v[230:233], v[198:201], v[54:57]
	v_mfma_f32_16x16x32_bf16 v[50:53], v[238:241], v[198:201], v[50:53]
	v_mfma_f32_16x16x32_bf16 v[38:41], v[230:233], v[206:209], v[38:41]
	v_mfma_f32_16x16x32_bf16 v[34:37], v[238:241], v[206:209], v[34:37]
	v_mfma_f32_16x16x32_bf16 v[22:25], v[230:233], v[214:217], v[22:25]
	v_mfma_f32_16x16x32_bf16 v[18:21], v[238:241], v[214:217], v[18:21]
	v_mfma_f32_16x16x32_bf16 v[6:9], v[230:233], v[222:225], v[6:9]
	v_mfma_f32_16x16x32_bf16 v[2:5], v[238:241], v[222:225], v[2:5]
	v_mfma_f32_16x16x32_bf16 v[54:57], v[234:237], v[202:205], v[54:57]
	v_mfma_f32_16x16x32_bf16 v[50:53], v[242:245], v[202:205], v[50:53]
	v_mfma_f32_16x16x32_bf16 v[38:41], v[234:237], v[210:213], v[38:41]
	v_mfma_f32_16x16x32_bf16 v[34:37], v[242:245], v[210:213], v[34:37]
	v_mfma_f32_16x16x32_bf16 v[22:25], v[234:237], v[218:221], v[22:25]
	v_mfma_f32_16x16x32_bf16 v[18:21], v[242:245], v[218:221], v[18:21]
	v_mfma_f32_16x16x32_bf16 v[6:9], v[234:237], v[226:229], v[6:9]
	v_mfma_f32_16x16x32_bf16 v[2:5], v[242:245], v[226:229], v[2:5]
	s_setprio 0
	s_add_i32 s74, 0, 0x18000
	v_add_u32_e32 v169, s74, v145
	s_barrier
	ds_read_b128 v[138:141], v169
	ds_read_b128 v[186:189], v169 offset:1024
	ds_read_b128 v[190:193], v169 offset:2048
	ds_read_b128 v[194:197], v169 offset:3072
	s_add_u32 s60, s60, 0x40000
	s_addc_u32 s61, s61, 0
	s_mov_b32 m0, s66
	v_lshl_add_u64 v[230:231], s[60:61], 0, v[150:151]
	ds_read_b128 v[198:201], v158 offset:32768
	ds_read_b128 v[202:205], v158 offset:33792
	ds_read_b128 v[206:209], v158 offset:34816
	ds_read_b128 v[210:213], v158 offset:35840
	ds_read_b128 v[214:217], v158 offset:36864
	ds_read_b128 v[218:221], v158 offset:37888
	ds_read_b128 v[222:225], v158 offset:38912
	ds_read_b128 v[226:229], v158 offset:39936
	global_load_lds_dwordx4 v[230:231], off
	v_lshl_add_u64 v[230:231], s[60:61], 0, v[154:155]
	s_mov_b32 m0, s67
	s_nop 0
	global_load_lds_dwordx4 v[230:231], off
	s_waitcnt lgkmcnt(8)
	s_barrier
	s_waitcnt lgkmcnt(0)
	s_setprio 1
	s_waitcnt lgkmcnt(0)
	v_mfma_f32_16x16x32_bf16 v[126:129], v[138:141], v[198:201], v[126:129]
	v_mfma_f32_16x16x32_bf16 v[122:125], v[190:193], v[198:201], v[122:125]
	v_mfma_f32_16x16x32_bf16 v[110:113], v[138:141], v[206:209], v[110:113]
	v_mfma_f32_16x16x32_bf16 v[106:109], v[190:193], v[206:209], v[106:109]
	v_mfma_f32_16x16x32_bf16 v[94:97], v[138:141], v[214:217], v[94:97]
	v_mfma_f32_16x16x32_bf16 v[90:93], v[190:193], v[214:217], v[90:93]
	v_mfma_f32_16x16x32_bf16 v[78:81], v[138:141], v[222:225], v[78:81]
	v_mfma_f32_16x16x32_bf16 v[74:77], v[190:193], v[222:225], v[74:77]
	v_mfma_f32_16x16x32_bf16 v[126:129], v[186:189], v[202:205], v[126:129]
	v_mfma_f32_16x16x32_bf16 v[122:125], v[194:197], v[202:205], v[122:125]
	v_mfma_f32_16x16x32_bf16 v[110:113], v[186:189], v[210:213], v[110:113]
	v_mfma_f32_16x16x32_bf16 v[106:109], v[194:197], v[210:213], v[106:109]
	v_mfma_f32_16x16x32_bf16 v[94:97], v[186:189], v[218:221], v[94:97]
	v_mfma_f32_16x16x32_bf16 v[90:93], v[194:197], v[218:221], v[90:93]
	v_mfma_f32_16x16x32_bf16 v[78:81], v[186:189], v[226:229], v[78:81]
	v_mfma_f32_16x16x32_bf16 v[74:77], v[194:197], v[226:229], v[74:77]
	s_setprio 0
	s_barrier
	s_add_i32 s60, 0, 0x1c000
	s_add_i32 s61, s74, s64
	v_add_u32_e32 v169, s60, v145
	v_lshl_add_u64 v[142:143], v[142:143], 0, s[12:13]
	s_mov_b32 m0, s61
	ds_read_b128 v[230:233], v169
	ds_read_b128 v[234:237], v169 offset:1024
	ds_read_b128 v[238:241], v169 offset:2048
	ds_read_b128 v[242:245], v169 offset:3072
	global_load_lds_dwordx4 v[142:143], off
	v_lshl_add_u64 v[142:143], v[246:247], 0, s[12:13]
	s_add_i32 m0, s61, 0x2000
	s_nop 0
	global_load_lds_dwordx4 v[142:143], off
	s_barrier
	s_waitcnt lgkmcnt(0)
	s_setprio 1
	s_waitcnt lgkmcnt(0)
	v_mfma_f32_16x16x32_bf16 v[118:121], v[230:233], v[198:201], v[118:121]
	v_mfma_f32_16x16x32_bf16 v[114:117], v[238:241], v[198:201], v[114:117]
	v_mfma_f32_16x16x32_bf16 v[102:105], v[230:233], v[206:209], v[102:105]
	v_mfma_f32_16x16x32_bf16 v[98:101], v[238:241], v[206:209], v[98:101]
	v_mfma_f32_16x16x32_bf16 v[86:89], v[230:233], v[214:217], v[86:89]
	v_mfma_f32_16x16x32_bf16 v[82:85], v[238:241], v[214:217], v[82:85]
	v_mfma_f32_16x16x32_bf16 v[70:73], v[230:233], v[222:225], v[70:73]
	v_mfma_f32_16x16x32_bf16 v[66:69], v[238:241], v[222:225], v[66:69]
	v_mfma_f32_16x16x32_bf16 v[118:121], v[234:237], v[202:205], v[118:121]
	v_mfma_f32_16x16x32_bf16 v[114:117], v[242:245], v[202:205], v[114:117]
	v_mfma_f32_16x16x32_bf16 v[102:105], v[234:237], v[210:213], v[102:105]
	v_mfma_f32_16x16x32_bf16 v[98:101], v[242:245], v[210:213], v[98:101]
	v_mfma_f32_16x16x32_bf16 v[86:89], v[234:237], v[218:221], v[86:89]
	v_mfma_f32_16x16x32_bf16 v[82:85], v[242:245], v[218:221], v[82:85]
	v_mfma_f32_16x16x32_bf16 v[70:73], v[234:237], v[226:229], v[70:73]
	v_mfma_f32_16x16x32_bf16 v[66:69], v[242:245], v[226:229], v[66:69]
	s_setprio 0
	s_mov_b32 m0, s69
	v_lshl_add_u64 v[142:143], v[248:249], 0, s[12:13]
	s_barrier
	ds_read_b128 v[198:201], v158 offset:49152
	ds_read_b128 v[202:205], v158 offset:50176
	ds_read_b128 v[206:209], v158 offset:51200
	ds_read_b128 v[210:213], v158 offset:52224
	ds_read_b128 v[214:217], v158 offset:53248
	ds_read_b128 v[218:221], v158 offset:54272
	ds_read_b128 v[222:225], v158 offset:55296
	ds_read_b128 v[226:229], v158 offset:56320
	global_load_lds_dwordx4 v[142:143], off
	v_lshl_add_u64 v[142:143], v[250:251], 0, s[12:13]
	s_mov_b32 m0, s70
	s_nop 0
	global_load_lds_dwordx4 v[142:143], off
	s_barrier
	s_waitcnt lgkmcnt(0)
	s_setprio 1
	s_waitcnt lgkmcnt(0)
	v_mfma_f32_16x16x32_bf16 v[62:65], v[138:141], v[198:201], v[62:65]
	v_mfma_f32_16x16x32_bf16 v[58:61], v[190:193], v[198:201], v[58:61]
	v_mfma_f32_16x16x32_bf16 v[46:49], v[138:141], v[206:209], v[46:49]
	v_mfma_f32_16x16x32_bf16 v[42:45], v[190:193], v[206:209], v[42:45]
	v_mfma_f32_16x16x32_bf16 v[30:33], v[138:141], v[214:217], v[30:33]
	v_mfma_f32_16x16x32_bf16 v[26:29], v[190:193], v[214:217], v[26:29]
	v_mfma_f32_16x16x32_bf16 v[14:17], v[138:141], v[222:225], v[14:17]
	v_mfma_f32_16x16x32_bf16 v[10:13], v[190:193], v[222:225], v[10:13]
	v_mfma_f32_16x16x32_bf16 v[62:65], v[186:189], v[202:205], v[62:65]
	v_mfma_f32_16x16x32_bf16 v[58:61], v[194:197], v[202:205], v[58:61]
	v_mfma_f32_16x16x32_bf16 v[46:49], v[186:189], v[210:213], v[46:49]
	v_mfma_f32_16x16x32_bf16 v[42:45], v[194:197], v[210:213], v[42:45]
	v_mfma_f32_16x16x32_bf16 v[30:33], v[186:189], v[218:221], v[30:33]
	v_mfma_f32_16x16x32_bf16 v[26:29], v[194:197], v[218:221], v[26:29]
	v_mfma_f32_16x16x32_bf16 v[14:17], v[186:189], v[226:229], v[14:17]
	v_mfma_f32_16x16x32_bf16 v[10:13], v[194:197], v[226:229], v[10:13]
	s_setprio 0
	s_barrier
	s_add_u32 s58, s58, 0x40080
	s_addc_u32 s59, s59, 0
	s_add_i32 s60, s60, s64
	v_lshl_add_u64 v[138:139], s[58:59], 0, v[152:153]
	s_mov_b32 m0, s60
	s_nop 0
	global_load_lds_dwordx4 v[138:139], off
	v_lshl_add_u64 v[138:139], s[58:59], 0, v[156:157]
	s_add_i32 m0, s60, 0x2000
	s_nop 0
	global_load_lds_dwordx4 v[138:139], off
	s_waitcnt vmcnt(6)
	s_barrier
	s_setprio 1
	v_mfma_f32_16x16x32_bf16 v[54:57], v[230:233], v[198:201], v[54:57]
	v_mfma_f32_16x16x32_bf16 v[50:53], v[238:241], v[198:201], v[50:53]
	v_mfma_f32_16x16x32_bf16 v[38:41], v[230:233], v[206:209], v[38:41]
	v_mfma_f32_16x16x32_bf16 v[34:37], v[238:241], v[206:209], v[34:37]
	v_mfma_f32_16x16x32_bf16 v[22:25], v[230:233], v[214:217], v[22:25]
	v_mfma_f32_16x16x32_bf16 v[18:21], v[238:241], v[214:217], v[18:21]
	v_mfma_f32_16x16x32_bf16 v[6:9], v[230:233], v[222:225], v[6:9]
	v_mfma_f32_16x16x32_bf16 v[2:5], v[238:241], v[222:225], v[2:5]
	v_mfma_f32_16x16x32_bf16 v[54:57], v[234:237], v[202:205], v[54:57]
	v_mfma_f32_16x16x32_bf16 v[50:53], v[242:245], v[202:205], v[50:53]
	v_mfma_f32_16x16x32_bf16 v[38:41], v[234:237], v[210:213], v[38:41]
	v_mfma_f32_16x16x32_bf16 v[34:37], v[242:245], v[210:213], v[34:37]
	v_mfma_f32_16x16x32_bf16 v[22:25], v[234:237], v[218:221], v[22:25]
	v_mfma_f32_16x16x32_bf16 v[18:21], v[242:245], v[218:221], v[18:21]
	v_mfma_f32_16x16x32_bf16 v[6:9], v[234:237], v[226:229], v[6:9]
	v_mfma_f32_16x16x32_bf16 v[2:5], v[242:245], v[226:229], v[2:5]
	s_setprio 0
	s_add_i32 s47, s47, 2
	s_add_u32 s56, s56, 0x100
	s_addc_u32 s57, s57, 0
	s_add_u32 s43, s43, 0x100
	s_addc_u32 s46, s46, 0
	s_cmp_gt_u32 s47, 13
	s_barrier
	s_cbranch_scc0 .LBB0_762
	v_lshl_add_u32 v142, s50, 8, v144
	v_lshl_or_b32 v140, s20, 8, v146
	v_ashrrev_i32_e32 v143, 31, v142
	v_ashrrev_i32_e32 v141, 31, v140
	v_lshlrev_b64 v[138:139], 10, v[142:143]
	v_lshl_add_u64 v[138:139], v[138:139], 0, v[140:141]
	v_lshlrev_b64 v[138:139], 1, v[138:139]
	v_readlane_b32 s74, v254, 46
	s_and_b64 vcc, exec, s[2:3]
	s_mov_b32 s20, s40
	s_mov_b32 s50, s42
	s_mov_b64 s[58:59], s[48:49]
	s_mov_b64 s[56:57], s[44:45]
	v_readlane_b32 s75, v254, 47
	v_mov_b32_e32 v203, v138
	v_add_u32_e32 v204, 0x8000, v138
	v_add_u32_e32 v205, 0x10000, v138
	v_add_u32_e32 v206, 0x18000, v138
	v_add_u32_e32 v207, 0x40000, v138
	v_add_u32_e32 v208, 0x48000, v138
	v_add_u32_e32 v209, 0x50000, v138
	v_add_u32_e32 v210, 0x58000, v138
	global_load_dwordx4 v[212:215], v203, s[18:19]
	global_load_dwordx4 v[216:219], v203, s[0:1]
	global_load_dwordx4 v[220:223], v203, s[18:19] offset:256
	global_load_dwordx4 v[224:227], v203, s[0:1] offset:256
	global_load_dwordx4 v[228:231], v204, s[18:19]
	global_load_dwordx4 v[232:235], v204, s[0:1]
	global_load_dwordx4 v[236:239], v204, s[18:19] offset:256
	global_load_dwordx4 v[240:243], v204, s[0:1] offset:256
	global_load_dwordx4 v[244:247], v205, s[18:19]
	global_load_dwordx4 v[248:251], v205, s[0:1]
	s_waitcnt vmcnt(8)
	v_lshlrev_b32_e32 v143, 16, v212
	v_lshlrev_b32_e32 v169, 16, v216
	v_and_b32_e32 v185, 0xffff0000, v212
	v_and_b32_e32 v212, 0xffff0000, v216
	v_lshlrev_b32_e32 v216, 16, v213
	v_lshlrev_b32_e32 v198, 16, v217
	v_and_b32_e32 v213, 0xffff0000, v213
	v_and_b32_e32 v217, 0xffff0000, v217
	v_lshlrev_b32_e32 v199, 16, v214
	v_lshlrev_b32_e32 v200, 16, v218
	v_and_b32_e32 v214, 0xffff0000, v214
	v_and_b32_e32 v218, 0xffff0000, v218
	v_lshlrev_b32_e32 v201, 16, v215
	v_lshlrev_b32_e32 v202, 16, v219
	v_and_b32_e32 v215, 0xffff0000, v215
	v_and_b32_e32 v219, 0xffff0000, v219
	v_fmac_f32_e32 v213, v129, v217
	v_fmac_f32_e32 v214, v123, v218
	v_fmac_f32_e32 v215, v125, v219
	v_fmac_f32_e32 v143, v126, v169
	v_fmac_f32_e32 v185, v127, v212
	v_fmac_f32_e32 v216, v128, v198
	v_fmac_f32_e32 v199, v122, v200
	v_fmac_f32_e32 v201, v124, v202
	v_cvt_pk_bf16_f32 v122, v143, v185
	v_cvt_pk_bf16_f32 v123, v216, v213
	v_cvt_pk_bf16_f32 v124, v199, v214
	v_cvt_pk_bf16_f32 v125, v201, v215
	global_store_dwordx4 v203, v[122:125], s[26:27]
	s_nop 1
	global_load_dwordx4 v[212:215], v205, s[18:19] offset:256
	global_load_dwordx4 v[216:219], v205, s[0:1] offset:256
	s_waitcnt vmcnt(9)
	v_lshlrev_b32_e32 v122, 16, v220
	v_lshlrev_b32_e32 v123, 16, v224
	v_and_b32_e32 v124, 0xffff0000, v220
	v_and_b32_e32 v125, 0xffff0000, v224
	v_lshlrev_b32_e32 v220, 16, v221
	v_lshlrev_b32_e32 v143, 16, v225
	v_and_b32_e32 v221, 0xffff0000, v221
	v_and_b32_e32 v169, 0xffff0000, v225
	v_lshlrev_b32_e32 v185, 16, v222
	v_lshlrev_b32_e32 v224, 16, v226
	v_and_b32_e32 v222, 0xffff0000, v222
	v_and_b32_e32 v225, 0xffff0000, v226
	v_lshlrev_b32_e32 v226, 16, v223
	v_lshlrev_b32_e32 v198, 16, v227
	v_and_b32_e32 v223, 0xffff0000, v223
	v_and_b32_e32 v227, 0xffff0000, v227
	v_fmac_f32_e32 v122, v118, v123
	v_fmac_f32_e32 v124, v119, v125
	v_fmac_f32_e32 v220, v120, v143
	v_fmac_f32_e32 v221, v121, v169
	v_fmac_f32_e32 v185, v114, v224
	v_fmac_f32_e32 v222, v115, v225
	v_fmac_f32_e32 v226, v116, v198
	v_fmac_f32_e32 v223, v117, v227
	v_cvt_pk_bf16_f32 v114, v122, v124
	v_cvt_pk_bf16_f32 v115, v220, v221
	v_cvt_pk_bf16_f32 v116, v185, v222
	v_cvt_pk_bf16_f32 v117, v226, v223
	global_store_dwordx4 v203, v[114:117], s[26:27] offset:256
	s_nop 1
	global_load_dwordx4 v[220:223], v206, s[18:19]
	global_load_dwordx4 v[224:227], v206, s[0:1]
	s_waitcnt vmcnt(10)
	v_lshlrev_b32_e32 v122, 16, v228
	v_lshlrev_b32_e32 v123, 16, v232
	v_and_b32_e32 v228, 0xffff0000, v228
	v_and_b32_e32 v232, 0xffff0000, v232
	v_lshlrev_b32_e32 v124, 16, v229
	v_lshlrev_b32_e32 v125, 16, v233
	v_and_b32_e32 v229, 0xffff0000, v229
	v_and_b32_e32 v233, 0xffff0000, v233
	v_lshlrev_b32_e32 v126, 16, v230
	v_lshlrev_b32_e32 v127, 16, v234
	v_and_b32_e32 v230, 0xffff0000, v230
	v_and_b32_e32 v234, 0xffff0000, v234
	v_lshlrev_b32_e32 v128, 16, v231
	v_lshlrev_b32_e32 v129, 16, v235
	v_and_b32_e32 v231, 0xffff0000, v231
	v_and_b32_e32 v235, 0xffff0000, v235
	v_fmac_f32_e32 v228, v111, v232
	v_fmac_f32_e32 v229, v113, v233
	v_fmac_f32_e32 v230, v107, v234
	v_fmac_f32_e32 v231, v109, v235
	v_fmac_f32_e32 v122, v110, v123
	v_fmac_f32_e32 v124, v112, v125
	v_fmac_f32_e32 v126, v106, v127
	v_fmac_f32_e32 v128, v108, v129
	v_cvt_pk_bf16_f32 v106, v122, v228
	v_cvt_pk_bf16_f32 v107, v124, v229
	v_cvt_pk_bf16_f32 v108, v126, v230
	v_cvt_pk_bf16_f32 v109, v128, v231
	global_store_dwordx4 v204, v[106:109], s[26:27]
	s_nop 1
	global_load_dwordx4 v[228:231], v206, s[18:19] offset:256
	global_load_dwordx4 v[232:235], v206, s[0:1] offset:256
	s_waitcnt vmcnt(11)
	v_lshlrev_b32_e32 v106, 16, v236
	v_lshlrev_b32_e32 v107, 16, v240
	v_and_b32_e32 v108, 0xffff0000, v236
	v_and_b32_e32 v109, 0xffff0000, v240
	v_lshlrev_b32_e32 v236, 16, v237
	v_lshlrev_b32_e32 v240, 16, v241
	v_and_b32_e32 v237, 0xffff0000, v237
	v_and_b32_e32 v241, 0xffff0000, v241
	v_lshlrev_b32_e32 v126, 16, v238
	v_lshlrev_b32_e32 v127, 16, v242
	v_and_b32_e32 v238, 0xffff0000, v238
	v_and_b32_e32 v242, 0xffff0000, v242
	v_lshlrev_b32_e32 v128, 16, v239
	v_lshlrev_b32_e32 v129, 16, v243
	v_and_b32_e32 v239, 0xffff0000, v239
	v_and_b32_e32 v243, 0xffff0000, v243
	v_fmac_f32_e32 v106, v102, v107
	v_fmac_f32_e32 v108, v103, v109
	v_fmac_f32_e32 v236, v104, v240
	v_fmac_f32_e32 v237, v105, v241
	v_fmac_f32_e32 v126, v98, v127
	v_fmac_f32_e32 v238, v99, v242
	v_fmac_f32_e32 v128, v100, v129
	v_fmac_f32_e32 v239, v101, v243
	v_cvt_pk_bf16_f32 v98, v106, v108
	v_cvt_pk_bf16_f32 v99, v236, v237
	v_cvt_pk_bf16_f32 v100, v126, v238
	v_cvt_pk_bf16_f32 v101, v128, v239
	global_store_dwordx4 v204, v[98:101], s[26:27] offset:256
	s_nop 1
	global_load_dwordx4 v[236:239], v207, s[18:19]
	global_load_dwordx4 v[240:243], v207, s[0:1]
	s_waitcnt vmcnt(12)
	v_lshlrev_b32_e32 v106, 16, v244
	v_lshlrev_b32_e32 v107, 16, v248
	v_and_b32_e32 v244, 0xffff0000, v244
	v_and_b32_e32 v248, 0xffff0000, v248
	v_lshlrev_b32_e32 v108, 16, v245
	v_lshlrev_b32_e32 v109, 16, v249
	v_and_b32_e32 v245, 0xffff0000, v245
	v_and_b32_e32 v249, 0xffff0000, v249
	v_lshlrev_b32_e32 v110, 16, v246
	v_lshlrev_b32_e32 v111, 16, v250
	v_and_b32_e32 v246, 0xffff0000, v246
	v_and_b32_e32 v250, 0xffff0000, v250
	v_lshlrev_b32_e32 v112, 16, v247
	v_lshlrev_b32_e32 v113, 16, v251
	v_and_b32_e32 v247, 0xffff0000, v247
	v_and_b32_e32 v251, 0xffff0000, v251
	v_fmac_f32_e32 v244, v95, v248
	v_fmac_f32_e32 v245, v97, v249
	v_fmac_f32_e32 v246, v91, v250
	v_fmac_f32_e32 v247, v93, v251
	v_fmac_f32_e32 v106, v94, v107
	v_fmac_f32_e32 v108, v96, v109
	v_fmac_f32_e32 v110, v90, v111
	v_fmac_f32_e32 v112, v92, v113
	v_cvt_pk_bf16_f32 v90, v106, v244
	v_cvt_pk_bf16_f32 v91, v108, v245
	v_cvt_pk_bf16_f32 v92, v110, v246
	v_cvt_pk_bf16_f32 v93, v112, v247
	global_store_dwordx4 v205, v[90:93], s[26:27]
	s_nop 1
	global_load_dwordx4 v[244:247], v207, s[18:19] offset:256
	global_load_dwordx4 v[248:251], v207, s[0:1] offset:256
	s_waitcnt vmcnt(12)
	v_lshlrev_b32_e32 v90, 16, v212
	v_lshlrev_b32_e32 v91, 16, v216
	v_and_b32_e32 v92, 0xffff0000, v212
	v_and_b32_e32 v93, 0xffff0000, v216
	v_lshlrev_b32_e32 v212, 16, v213
	v_lshlrev_b32_e32 v216, 16, v217
	v_and_b32_e32 v213, 0xffff0000, v213
	v_and_b32_e32 v217, 0xffff0000, v217
	v_lshlrev_b32_e32 v110, 16, v214
	v_lshlrev_b32_e32 v111, 16, v218
	v_and_b32_e32 v214, 0xffff0000, v214
	v_and_b32_e32 v218, 0xffff0000, v218
	v_lshlrev_b32_e32 v112, 16, v215
	v_lshlrev_b32_e32 v113, 16, v219
	v_and_b32_e32 v215, 0xffff0000, v215
	v_and_b32_e32 v219, 0xffff0000, v219
	v_fmac_f32_e32 v90, v86, v91
	v_fmac_f32_e32 v92, v87, v93
	v_fmac_f32_e32 v212, v88, v216
	v_fmac_f32_e32 v213, v89, v217
	v_fmac_f32_e32 v110, v82, v111
	v_fmac_f32_e32 v214, v83, v218
	v_fmac_f32_e32 v112, v84, v113
	v_fmac_f32_e32 v215, v85, v219
	v_cvt_pk_bf16_f32 v82, v90, v92
	v_cvt_pk_bf16_f32 v83, v212, v213
	v_cvt_pk_bf16_f32 v84, v110, v214
	v_cvt_pk_bf16_f32 v85, v112, v215
	global_store_dwordx4 v205, v[82:85], s[26:27] offset:256
	s_nop 1
	global_load_dwordx4 v[212:215], v208, s[18:19]
	global_load_dwordx4 v[216:219], v208, s[0:1]
	s_waitcnt vmcnt(12)
	v_lshlrev_b32_e32 v90, 16, v220
	v_lshlrev_b32_e32 v91, 16, v224
	v_and_b32_e32 v220, 0xffff0000, v220
	v_and_b32_e32 v224, 0xffff0000, v224
	v_lshlrev_b32_e32 v92, 16, v221
	v_lshlrev_b32_e32 v93, 16, v225
	v_and_b32_e32 v221, 0xffff0000, v221
	v_and_b32_e32 v225, 0xffff0000, v225
	v_lshlrev_b32_e32 v94, 16, v222
	v_lshlrev_b32_e32 v95, 16, v226
	v_and_b32_e32 v222, 0xffff0000, v222
	v_and_b32_e32 v226, 0xffff0000, v226
	v_lshlrev_b32_e32 v96, 16, v223
	v_lshlrev_b32_e32 v97, 16, v227
	v_and_b32_e32 v223, 0xffff0000, v223
	v_and_b32_e32 v227, 0xffff0000, v227
	v_fmac_f32_e32 v220, v79, v224
	v_fmac_f32_e32 v221, v81, v225
	v_fmac_f32_e32 v222, v75, v226
	v_fmac_f32_e32 v223, v77, v227
	v_fmac_f32_e32 v90, v78, v91
	v_fmac_f32_e32 v92, v80, v93
	v_fmac_f32_e32 v94, v74, v95
	v_fmac_f32_e32 v96, v76, v97
	v_cvt_pk_bf16_f32 v74, v90, v220
	v_cvt_pk_bf16_f32 v75, v92, v221
	v_cvt_pk_bf16_f32 v76, v94, v222
	v_cvt_pk_bf16_f32 v77, v96, v223
	global_store_dwordx4 v206, v[74:77], s[26:27]
	s_nop 1
	global_load_dwordx4 v[220:223], v208, s[18:19] offset:256
	global_load_dwordx4 v[224:227], v208, s[0:1] offset:256
	s_waitcnt vmcnt(12)
	v_lshlrev_b32_e32 v74, 16, v228
	v_lshlrev_b32_e32 v75, 16, v232
	v_and_b32_e32 v76, 0xffff0000, v228
	v_and_b32_e32 v77, 0xffff0000, v232
	v_lshlrev_b32_e32 v228, 16, v229
	v_lshlrev_b32_e32 v232, 16, v233
	v_and_b32_e32 v229, 0xffff0000, v229
	v_and_b32_e32 v233, 0xffff0000, v233
	v_lshlrev_b32_e32 v94, 16, v230
	v_lshlrev_b32_e32 v95, 16, v234
	v_and_b32_e32 v230, 0xffff0000, v230
	v_and_b32_e32 v234, 0xffff0000, v234
	v_lshlrev_b32_e32 v96, 16, v231
	v_lshlrev_b32_e32 v97, 16, v235
	v_and_b32_e32 v231, 0xffff0000, v231
	v_and_b32_e32 v235, 0xffff0000, v235
	v_fmac_f32_e32 v74, v70, v75
	v_fmac_f32_e32 v76, v71, v77
	v_fmac_f32_e32 v228, v72, v232
	v_fmac_f32_e32 v229, v73, v233
	v_fmac_f32_e32 v94, v66, v95
	v_fmac_f32_e32 v230, v67, v234
	v_fmac_f32_e32 v96, v68, v97
	v_fmac_f32_e32 v231, v69, v235
	v_cvt_pk_bf16_f32 v66, v74, v76
	v_cvt_pk_bf16_f32 v67, v228, v229
	v_cvt_pk_bf16_f32 v68, v94, v230
	v_cvt_pk_bf16_f32 v69, v96, v231
	global_store_dwordx4 v206, v[66:69], s[26:27] offset:256
	s_nop 1
	global_load_dwordx4 v[228:231], v209, s[18:19]
	global_load_dwordx4 v[232:235], v209, s[0:1]
	s_waitcnt vmcnt(12)
	v_lshlrev_b32_e32 v74, 16, v236
	v_lshlrev_b32_e32 v75, 16, v240
	v_and_b32_e32 v236, 0xffff0000, v236
	v_and_b32_e32 v240, 0xffff0000, v240
	v_lshlrev_b32_e32 v76, 16, v237
	v_lshlrev_b32_e32 v77, 16, v241
	v_and_b32_e32 v237, 0xffff0000, v237
	v_and_b32_e32 v241, 0xffff0000, v241
	v_lshlrev_b32_e32 v78, 16, v238
	v_lshlrev_b32_e32 v79, 16, v242
	v_and_b32_e32 v238, 0xffff0000, v238
	v_and_b32_e32 v242, 0xffff0000, v242
	v_lshlrev_b32_e32 v80, 16, v239
	v_lshlrev_b32_e32 v81, 16, v243
	v_and_b32_e32 v239, 0xffff0000, v239
	v_and_b32_e32 v243, 0xffff0000, v243
	v_fmac_f32_e32 v236, v63, v240
	v_fmac_f32_e32 v237, v65, v241
	v_fmac_f32_e32 v238, v59, v242
	v_fmac_f32_e32 v239, v61, v243
	v_fmac_f32_e32 v74, v62, v75
	v_fmac_f32_e32 v76, v64, v77
	v_fmac_f32_e32 v78, v58, v79
	v_fmac_f32_e32 v80, v60, v81
	v_cvt_pk_bf16_f32 v58, v74, v236
	v_cvt_pk_bf16_f32 v59, v76, v237
	v_cvt_pk_bf16_f32 v60, v78, v238
	v_cvt_pk_bf16_f32 v61, v80, v239
	global_store_dwordx4 v207, v[58:61], s[26:27]
	s_nop 1
	global_load_dwordx4 v[236:239], v209, s[18:19] offset:256
	global_load_dwordx4 v[240:243], v209, s[0:1] offset:256
	s_waitcnt vmcnt(12)
	v_lshlrev_b32_e32 v58, 16, v244
	v_lshlrev_b32_e32 v59, 16, v248
	v_and_b32_e32 v60, 0xffff0000, v244
	v_and_b32_e32 v61, 0xffff0000, v248
	v_lshlrev_b32_e32 v244, 16, v245
	v_lshlrev_b32_e32 v248, 16, v249
	v_and_b32_e32 v245, 0xffff0000, v245
	v_and_b32_e32 v249, 0xffff0000, v249
	v_lshlrev_b32_e32 v78, 16, v246
	v_lshlrev_b32_e32 v79, 16, v250
	v_and_b32_e32 v246, 0xffff0000, v246
	v_and_b32_e32 v250, 0xffff0000, v250
	v_lshlrev_b32_e32 v80, 16, v247
	v_lshlrev_b32_e32 v81, 16, v251
	v_and_b32_e32 v247, 0xffff0000, v247
	v_and_b32_e32 v251, 0xffff0000, v251
	v_fmac_f32_e32 v58, v54, v59
	v_fmac_f32_e32 v60, v55, v61
	v_fmac_f32_e32 v244, v56, v248
	v_fmac_f32_e32 v245, v57, v249
	v_fmac_f32_e32 v78, v50, v79
	v_fmac_f32_e32 v246, v51, v250
	v_fmac_f32_e32 v80, v52, v81
	v_fmac_f32_e32 v247, v53, v251
	v_cvt_pk_bf16_f32 v50, v58, v60
	v_cvt_pk_bf16_f32 v51, v244, v245
	v_cvt_pk_bf16_f32 v52, v78, v246
	v_cvt_pk_bf16_f32 v53, v80, v247
	global_store_dwordx4 v207, v[50:53], s[26:27] offset:256
	s_nop 1
	global_load_dwordx4 v[244:247], v210, s[18:19]
	global_load_dwordx4 v[248:251], v210, s[0:1]
	s_waitcnt vmcnt(12)
	v_lshlrev_b32_e32 v58, 16, v212
	v_lshlrev_b32_e32 v59, 16, v216
	v_and_b32_e32 v212, 0xffff0000, v212
	v_and_b32_e32 v216, 0xffff0000, v216
	v_lshlrev_b32_e32 v60, 16, v213
	v_lshlrev_b32_e32 v61, 16, v217
	v_and_b32_e32 v213, 0xffff0000, v213
	v_and_b32_e32 v217, 0xffff0000, v217
	v_lshlrev_b32_e32 v62, 16, v214
	v_lshlrev_b32_e32 v63, 16, v218
	v_and_b32_e32 v214, 0xffff0000, v214
	v_and_b32_e32 v218, 0xffff0000, v218
	v_lshlrev_b32_e32 v64, 16, v215
	v_lshlrev_b32_e32 v65, 16, v219
	v_and_b32_e32 v215, 0xffff0000, v215
	v_and_b32_e32 v219, 0xffff0000, v219
	v_fmac_f32_e32 v212, v47, v216
	v_fmac_f32_e32 v213, v49, v217
	v_fmac_f32_e32 v214, v43, v218
	v_fmac_f32_e32 v215, v45, v219
	v_fmac_f32_e32 v58, v46, v59
	v_fmac_f32_e32 v60, v48, v61
	v_fmac_f32_e32 v62, v42, v63
	v_fmac_f32_e32 v64, v44, v65
	v_cvt_pk_bf16_f32 v42, v58, v212
	v_cvt_pk_bf16_f32 v43, v60, v213
	v_cvt_pk_bf16_f32 v44, v62, v214
	v_cvt_pk_bf16_f32 v45, v64, v215
	global_store_dwordx4 v208, v[42:45], s[26:27]
	s_nop 1
	global_load_dwordx4 v[212:215], v210, s[18:19] offset:256
	global_load_dwordx4 v[216:219], v210, s[0:1] offset:256
	s_waitcnt vmcnt(12)
	v_lshlrev_b32_e32 v42, 16, v220
	v_lshlrev_b32_e32 v43, 16, v224
	v_and_b32_e32 v44, 0xffff0000, v220
	v_and_b32_e32 v45, 0xffff0000, v224
	v_lshlrev_b32_e32 v220, 16, v221
	v_lshlrev_b32_e32 v224, 16, v225
	v_and_b32_e32 v221, 0xffff0000, v221
	v_and_b32_e32 v225, 0xffff0000, v225
	v_lshlrev_b32_e32 v62, 16, v222
	v_lshlrev_b32_e32 v63, 16, v226
	v_and_b32_e32 v222, 0xffff0000, v222
	v_and_b32_e32 v226, 0xffff0000, v226
	v_lshlrev_b32_e32 v64, 16, v223
	v_lshlrev_b32_e32 v65, 16, v227
	v_and_b32_e32 v223, 0xffff0000, v223
	v_and_b32_e32 v227, 0xffff0000, v227
	v_fmac_f32_e32 v42, v38, v43
	v_fmac_f32_e32 v44, v39, v45
	v_fmac_f32_e32 v220, v40, v224
	v_fmac_f32_e32 v221, v41, v225
	v_fmac_f32_e32 v62, v34, v63
	v_fmac_f32_e32 v222, v35, v226
	v_fmac_f32_e32 v64, v36, v65
	v_fmac_f32_e32 v223, v37, v227
	v_cvt_pk_bf16_f32 v34, v42, v44
	v_cvt_pk_bf16_f32 v35, v220, v221
	v_cvt_pk_bf16_f32 v36, v62, v222
	v_cvt_pk_bf16_f32 v37, v64, v223
	global_store_dwordx4 v208, v[34:37], s[26:27] offset:256
	s_nop 1
	s_waitcnt vmcnt(10)
	v_lshlrev_b32_e32 v42, 16, v228
	v_lshlrev_b32_e32 v43, 16, v232
	v_and_b32_e32 v228, 0xffff0000, v228
	v_and_b32_e32 v232, 0xffff0000, v232
	v_lshlrev_b32_e32 v44, 16, v229
	v_lshlrev_b32_e32 v45, 16, v233
	v_and_b32_e32 v229, 0xffff0000, v229
	v_and_b32_e32 v233, 0xffff0000, v233
	v_lshlrev_b32_e32 v46, 16, v230
	v_lshlrev_b32_e32 v47, 16, v234
	v_and_b32_e32 v230, 0xffff0000, v230
	v_and_b32_e32 v234, 0xffff0000, v234
	v_lshlrev_b32_e32 v48, 16, v231
	v_lshlrev_b32_e32 v49, 16, v235
	v_and_b32_e32 v231, 0xffff0000, v231
	v_and_b32_e32 v235, 0xffff0000, v235
	v_fmac_f32_e32 v228, v31, v232
	v_fmac_f32_e32 v229, v33, v233
	v_fmac_f32_e32 v230, v27, v234
	v_fmac_f32_e32 v231, v29, v235
	v_fmac_f32_e32 v42, v30, v43
	v_fmac_f32_e32 v44, v32, v45
	v_fmac_f32_e32 v46, v26, v47
	v_fmac_f32_e32 v48, v28, v49
	v_cvt_pk_bf16_f32 v26, v42, v228
	v_cvt_pk_bf16_f32 v27, v44, v229
	v_cvt_pk_bf16_f32 v28, v46, v230
	v_cvt_pk_bf16_f32 v29, v48, v231
	global_store_dwordx4 v209, v[26:29], s[26:27]
	s_nop 1
	s_waitcnt vmcnt(8)
	v_lshlrev_b32_e32 v26, 16, v236
	v_lshlrev_b32_e32 v27, 16, v240
	v_and_b32_e32 v28, 0xffff0000, v236
	v_and_b32_e32 v29, 0xffff0000, v240
	v_lshlrev_b32_e32 v236, 16, v237
	v_lshlrev_b32_e32 v240, 16, v241
	v_and_b32_e32 v237, 0xffff0000, v237
	v_and_b32_e32 v241, 0xffff0000, v241
	v_lshlrev_b32_e32 v46, 16, v238
	v_lshlrev_b32_e32 v47, 16, v242
	v_and_b32_e32 v238, 0xffff0000, v238
	v_and_b32_e32 v242, 0xffff0000, v242
	v_lshlrev_b32_e32 v48, 16, v239
	v_lshlrev_b32_e32 v49, 16, v243
	v_and_b32_e32 v239, 0xffff0000, v239
	v_and_b32_e32 v243, 0xffff0000, v243
	v_fmac_f32_e32 v26, v22, v27
	v_fmac_f32_e32 v28, v23, v29
	v_fmac_f32_e32 v236, v24, v240
	v_fmac_f32_e32 v237, v25, v241
	v_fmac_f32_e32 v46, v18, v47
	v_fmac_f32_e32 v238, v19, v242
	v_fmac_f32_e32 v48, v20, v49
	v_fmac_f32_e32 v239, v21, v243
	v_cvt_pk_bf16_f32 v18, v26, v28
	v_cvt_pk_bf16_f32 v19, v236, v237
	v_cvt_pk_bf16_f32 v20, v46, v238
	v_cvt_pk_bf16_f32 v21, v48, v239
	global_store_dwordx4 v209, v[18:21], s[26:27] offset:256
	s_nop 1
	s_waitcnt vmcnt(6)
	v_lshlrev_b32_e32 v26, 16, v244
	v_lshlrev_b32_e32 v27, 16, v248
	v_and_b32_e32 v244, 0xffff0000, v244
	v_and_b32_e32 v248, 0xffff0000, v248
	v_lshlrev_b32_e32 v28, 16, v245
	v_lshlrev_b32_e32 v29, 16, v249
	v_and_b32_e32 v245, 0xffff0000, v245
	v_and_b32_e32 v249, 0xffff0000, v249
	v_lshlrev_b32_e32 v30, 16, v246
	v_lshlrev_b32_e32 v31, 16, v250
	v_and_b32_e32 v246, 0xffff0000, v246
	v_and_b32_e32 v250, 0xffff0000, v250
	v_lshlrev_b32_e32 v32, 16, v247
	v_lshlrev_b32_e32 v33, 16, v251
	v_and_b32_e32 v247, 0xffff0000, v247
	v_and_b32_e32 v251, 0xffff0000, v251
	v_fmac_f32_e32 v244, v15, v248
	v_fmac_f32_e32 v245, v17, v249
	v_fmac_f32_e32 v246, v11, v250
	v_fmac_f32_e32 v247, v13, v251
	v_fmac_f32_e32 v26, v14, v27
	v_fmac_f32_e32 v28, v16, v29
	v_fmac_f32_e32 v30, v10, v31
	v_fmac_f32_e32 v32, v12, v33
	v_cvt_pk_bf16_f32 v10, v26, v244
	v_cvt_pk_bf16_f32 v11, v28, v245
	v_cvt_pk_bf16_f32 v12, v30, v246
	v_cvt_pk_bf16_f32 v13, v32, v247
	global_store_dwordx4 v210, v[10:13], s[26:27]
	s_nop 1
	s_waitcnt vmcnt(4)
	v_lshlrev_b32_e32 v24, 16, v214
	v_lshlrev_b32_e32 v10, 16, v212
	v_lshlrev_b32_e32 v11, 16, v216
	v_and_b32_e32 v12, 0xffff0000, v212
	v_and_b32_e32 v13, 0xffff0000, v216
	v_lshlrev_b32_e32 v212, 16, v213
	v_lshlrev_b32_e32 v216, 16, v217
	v_and_b32_e32 v213, 0xffff0000, v213
	v_and_b32_e32 v217, 0xffff0000, v217
	v_lshlrev_b32_e32 v25, 16, v218
	v_and_b32_e32 v214, 0xffff0000, v214
	v_and_b32_e32 v218, 0xffff0000, v218
	v_lshlrev_b32_e32 v26, 16, v215
	v_lshlrev_b32_e32 v27, 16, v219
	v_and_b32_e32 v215, 0xffff0000, v215
	v_and_b32_e32 v219, 0xffff0000, v219
	v_fmac_f32_e32 v10, v6, v11
	v_fmac_f32_e32 v12, v7, v13
	v_fmac_f32_e32 v212, v8, v216
	v_fmac_f32_e32 v213, v9, v217
	v_fmac_f32_e32 v24, v2, v25
	v_fmac_f32_e32 v214, v3, v218
	v_fmac_f32_e32 v26, v4, v27
	v_fmac_f32_e32 v215, v5, v219
	v_cvt_pk_bf16_f32 v2, v10, v12
	v_cvt_pk_bf16_f32 v3, v212, v213
	v_cvt_pk_bf16_f32 v4, v24, v214
	v_cvt_pk_bf16_f32 v5, v26, v215
	global_store_dwordx4 v210, v[2:5], s[26:27] offset:256
	s_nop 1
	s_cbranch_vccz .LBB0_755
	s_waitcnt vmcnt(0)
	s_cmpk_gt_u32 s24, 0xff
	s_cbranch_scc1 .LBB0_766
	s_barrier
